# all six GEMM K-loops: first iteration peeled with C=0 first MFMAs, per-unit accumulator zeroing deleted
# baseline (speedup 1.0000x reference)
.LBB0_71:
	s_ashr_i32 s39, s38, 31
	s_lshl_b64 s[44:45], s[38:39], 19
	s_add_u32 s48, s16, s44
	s_addc_u32 s49, s17, s45
	s_and_b64 s[44:45], s[42:43], exec
	s_cselect_b32 s39, s49, s13
	s_cselect_b32 s54, s48, s12
	s_ashr_i32 s29, s28, 31
	s_lshl_b64 s[44:45], s[28:29], 19
	s_add_u32 s50, s18, s44
	s_addc_u32 s51, s19, s45
	s_and_b64 s[44:45], s[42:43], exec
	s_cselect_b32 s29, s51, s15
	s_cselect_b32 s55, s50, s14
	s_add_u32 s60, s14, 0x100
	s_addc_u32 s61, s15, 0
	s_add_u32 s12, s12, 0x40080
	s_addc_u32 s13, s13, 0
	s_mov_b32 s96, -2
	s_waitcnt lgkmcnt(0)
	s_add_u32 s14, s12, 0xfffc0080
	s_addc_u32 s15, s13, -1
	s_add_i32 s24, 0, 0x10000
	s_cmp_eq_u32 s96, 12
	s_cselect_b32 s45, s39, s15
	s_cselect_b32 s44, s54, s14
	v_add_u32_e32 v2, s24, v185
	s_cselect_b32 s15, s29, s61
	s_cselect_b32 s14, s55, s60
	s_add_i32 s25, 0, 0x14000
	ds_read_b128 v[142:145], v2
	ds_read_b128 v[146:149], v2 offset:1024
	ds_read_b128 v[150:153], v2 offset:2048
	ds_read_b128 v[172:175], v2 offset:3072
	v_add_u32_e32 v2, s25, v185
	ds_read_b128 v[176:179], v2
	ds_read_b128 v[180:183], v2 offset:1024
	ds_read_b128 v[188:191], v2 offset:2048
	ds_read_b128 v[200:203], v2 offset:3072
	v_lshl_add_u64 v[154:155], s[12:13], 0, v[140:141]
	s_add_i32 m0, s21, 0xc000
	ds_read_b128 v[204:207], v187
	ds_read_b128 v[208:211], v187 offset:1024
	ds_read_b128 v[212:215], v187 offset:2048
	ds_read_b128 v[216:219], v187 offset:3072
	ds_read_b128 v[220:223], v187 offset:4096
	ds_read_b128 v[224:227], v187 offset:5120
	ds_read_b128 v[228:231], v187 offset:6144
	ds_read_b128 v[232:235], v187 offset:7168
	global_load_lds_dwordx4 v[154:155], off
	v_lshl_add_u64 v[154:155], s[12:13], 0, v[138:139]
	s_add_i32 m0, s21, 0xe000
	s_nop 0
	global_load_lds_dwordx4 v[154:155], off
	s_waitcnt vmcnt(8)
	s_waitcnt lgkmcnt(0)
	s_barrier
	s_setprio 1
	s_waitcnt lgkmcnt(0)
	v_mfma_f32_16x16x32_bf16 v[128:131], v[142:145], v[204:207], 0
	v_mfma_f32_16x16x32_bf16 v[124:127], v[150:153], v[204:207], 0
	v_mfma_f32_16x16x32_bf16 v[112:115], v[142:145], v[212:215], 0
	v_mfma_f32_16x16x32_bf16 v[108:111], v[150:153], v[212:215], 0
	v_mfma_f32_16x16x32_bf16 v[96:99], v[142:145], v[220:223], 0
	v_mfma_f32_16x16x32_bf16 v[92:95], v[150:153], v[220:223], 0
	v_mfma_f32_16x16x32_bf16 v[80:83], v[142:145], v[228:231], 0
	v_mfma_f32_16x16x32_bf16 v[76:79], v[150:153], v[228:231], 0
	v_mfma_f32_16x16x32_bf16 v[128:131], v[146:149], v[208:211], v[128:131]
	v_mfma_f32_16x16x32_bf16 v[124:127], v[172:175], v[208:211], v[124:127]
	v_mfma_f32_16x16x32_bf16 v[112:115], v[146:149], v[216:219], v[112:115]
	v_mfma_f32_16x16x32_bf16 v[108:111], v[172:175], v[216:219], v[108:111]
	v_mfma_f32_16x16x32_bf16 v[96:99], v[146:149], v[224:227], v[96:99]
	v_mfma_f32_16x16x32_bf16 v[92:95], v[172:175], v[224:227], v[92:95]
	v_mfma_f32_16x16x32_bf16 v[80:83], v[146:149], v[232:235], v[80:83]
	v_mfma_f32_16x16x32_bf16 v[76:79], v[172:175], v[232:235], v[76:79]
	s_setprio 0
	s_setprio 1
	v_mfma_f32_16x16x32_bf16 v[120:123], v[176:179], v[204:207], 0
	v_mfma_f32_16x16x32_bf16 v[116:119], v[188:191], v[204:207], 0
	v_mfma_f32_16x16x32_bf16 v[104:107], v[176:179], v[212:215], 0
	v_mfma_f32_16x16x32_bf16 v[100:103], v[188:191], v[212:215], 0
	v_mfma_f32_16x16x32_bf16 v[88:91], v[176:179], v[220:223], 0
	v_mfma_f32_16x16x32_bf16 v[84:87], v[188:191], v[220:223], 0
	v_mfma_f32_16x16x32_bf16 v[72:75], v[176:179], v[228:231], 0
	v_mfma_f32_16x16x32_bf16 v[68:71], v[188:191], v[228:231], 0
	v_mfma_f32_16x16x32_bf16 v[120:123], v[180:183], v[208:211], v[120:123]
	v_mfma_f32_16x16x32_bf16 v[116:119], v[200:203], v[208:211], v[116:119]
	v_mfma_f32_16x16x32_bf16 v[104:107], v[180:183], v[216:219], v[104:107]
	v_mfma_f32_16x16x32_bf16 v[100:103], v[200:203], v[216:219], v[100:103]
	v_mfma_f32_16x16x32_bf16 v[88:91], v[180:183], v[224:227], v[88:91]
	v_mfma_f32_16x16x32_bf16 v[84:87], v[200:203], v[224:227], v[84:87]
	v_mfma_f32_16x16x32_bf16 v[72:75], v[180:183], v[232:235], v[72:75]
	v_mfma_f32_16x16x32_bf16 v[68:71], v[200:203], v[232:235], v[68:71]
	s_setprio 0
	s_barrier
	s_add_i32 s24, s24, s20
	v_lshl_add_u64 v[154:155], s[14:15], 0, v[134:135]
	s_mov_b32 m0, s24
	ds_read_b128 v[204:207], v187 offset:16384
	ds_read_b128 v[208:211], v187 offset:17408
	ds_read_b128 v[212:215], v187 offset:18432
	ds_read_b128 v[216:219], v187 offset:19456
	ds_read_b128 v[220:223], v187 offset:20480
	ds_read_b128 v[224:227], v187 offset:21504
	ds_read_b128 v[228:231], v187 offset:22528
	ds_read_b128 v[232:235], v187 offset:23552
	global_load_lds_dwordx4 v[154:155], off
	s_add_i32 m0, s24, 0x2000
	s_add_u32 vcc_lo, s14, 0x40000
	v_lshl_add_u64 v[192:193], s[14:15], 0, v[0:1]
	s_addc_u32 vcc_hi, s15, 0
	s_add_i32 s24, s25, s20
	global_load_lds_dwordx4 v[192:193], off
	v_lshl_add_u64 v[236:237], vcc, 0, v[134:135]
	s_mov_b32 m0, s24
	v_lshl_add_u64 v[238:239], s[44:45], 0, v[132:133]
	global_load_lds_dwordx4 v[236:237], off
	v_lshl_add_u64 v[236:237], vcc, 0, v[0:1]
	s_add_i32 m0, s24, 0x2000
	s_nop 0
	global_load_lds_dwordx4 v[236:237], off
	v_lshl_add_u64 v[236:237], s[44:45], 0, v[136:137]
	s_mov_b32 m0, s21
	s_nop 0
	global_load_lds_dwordx4 v[236:237], off
	s_mov_b32 m0, s22
	s_nop 0
	global_load_lds_dwordx4 v[238:239], off
	s_waitcnt vmcnt(8)
	s_waitcnt lgkmcnt(0)
	s_barrier
	s_setprio 1
	s_waitcnt lgkmcnt(0)
	v_mfma_f32_16x16x32_bf16 v[64:67], v[142:145], v[204:207], 0
	v_mfma_f32_16x16x32_bf16 v[60:63], v[150:153], v[204:207], 0
	v_mfma_f32_16x16x32_bf16 v[48:51], v[142:145], v[212:215], 0
	v_mfma_f32_16x16x32_bf16 v[44:47], v[150:153], v[212:215], 0
	v_mfma_f32_16x16x32_bf16 v[32:35], v[142:145], v[220:223], 0
	v_mfma_f32_16x16x32_bf16 v[28:31], v[150:153], v[220:223], 0
	v_mfma_f32_16x16x32_bf16 v[16:19], v[142:145], v[228:231], 0
	v_mfma_f32_16x16x32_bf16 v[12:15], v[150:153], v[228:231], 0
	v_mfma_f32_16x16x32_bf16 v[64:67], v[146:149], v[208:211], v[64:67]
	v_mfma_f32_16x16x32_bf16 v[60:63], v[172:175], v[208:211], v[60:63]
	v_mfma_f32_16x16x32_bf16 v[48:51], v[146:149], v[216:219], v[48:51]
	v_mfma_f32_16x16x32_bf16 v[44:47], v[172:175], v[216:219], v[44:47]
	v_mfma_f32_16x16x32_bf16 v[32:35], v[146:149], v[224:227], v[32:35]
	v_mfma_f32_16x16x32_bf16 v[28:31], v[172:175], v[224:227], v[28:31]
	v_mfma_f32_16x16x32_bf16 v[16:19], v[146:149], v[232:235], v[16:19]
	v_mfma_f32_16x16x32_bf16 v[12:15], v[172:175], v[232:235], v[12:15]
	s_setprio 0
	s_setprio 1
	v_mfma_f32_16x16x32_bf16 v[56:59], v[176:179], v[204:207], 0
	v_mfma_f32_16x16x32_bf16 v[52:55], v[188:191], v[204:207], 0
	v_mfma_f32_16x16x32_bf16 v[40:43], v[176:179], v[212:215], 0
	v_mfma_f32_16x16x32_bf16 v[36:39], v[188:191], v[212:215], 0
	v_mfma_f32_16x16x32_bf16 v[24:27], v[176:179], v[220:223], 0
	v_mfma_f32_16x16x32_bf16 v[20:23], v[188:191], v[220:223], 0
	v_mfma_f32_16x16x32_bf16 v[8:11], v[176:179], v[228:231], 0
	v_mfma_f32_16x16x32_bf16 v[4:7], v[188:191], v[228:231], 0
	v_mfma_f32_16x16x32_bf16 v[56:59], v[180:183], v[208:211], v[56:59]
	v_mfma_f32_16x16x32_bf16 v[52:55], v[200:203], v[208:211], v[52:55]
	v_mfma_f32_16x16x32_bf16 v[40:43], v[180:183], v[216:219], v[40:43]
	v_mfma_f32_16x16x32_bf16 v[36:39], v[200:203], v[216:219], v[36:39]
	v_mfma_f32_16x16x32_bf16 v[24:27], v[180:183], v[224:227], v[24:27]
	v_mfma_f32_16x16x32_bf16 v[20:23], v[200:203], v[224:227], v[20:23]
	v_mfma_f32_16x16x32_bf16 v[8:11], v[180:183], v[232:235], v[8:11]
	v_mfma_f32_16x16x32_bf16 v[4:7], v[200:203], v[232:235], v[4:7]
	s_setprio 0
	s_barrier
	s_add_i32 s24, 0, 0x18000
	v_add_u32_e32 v2, s24, v185
	s_add_i32 s25, 0, 0x1c000
	ds_read_b128 v[142:145], v2
	ds_read_b128 v[146:149], v2 offset:1024
	ds_read_b128 v[150:153], v2 offset:2048
	ds_read_b128 v[172:175], v2 offset:3072
	v_add_u32_e32 v2, s25, v185
	ds_read_b128 v[176:179], v2
	ds_read_b128 v[180:183], v2 offset:1024
	ds_read_b128 v[188:191], v2 offset:2048
	ds_read_b128 v[200:203], v2 offset:3072
	s_add_u32 s44, s44, 0x40000
	s_addc_u32 s45, s45, 0
	s_mov_b32 m0, s23
	v_lshl_add_u64 v[240:241], s[44:45], 0, v[136:137]
	ds_read_b128 v[204:207], v187 offset:32768
	ds_read_b128 v[208:211], v187 offset:33792
	ds_read_b128 v[212:215], v187 offset:34816
	ds_read_b128 v[216:219], v187 offset:35840
	ds_read_b128 v[220:223], v187 offset:36864
	ds_read_b128 v[224:227], v187 offset:37888
	ds_read_b128 v[228:231], v187 offset:38912
	ds_read_b128 v[232:235], v187 offset:39936
	global_load_lds_dwordx4 v[240:241], off
	v_lshl_add_u64 v[240:241], s[44:45], 0, v[132:133]
	s_mov_b32 m0, s36
	s_nop 0
	global_load_lds_dwordx4 v[240:241], off
	s_waitcnt vmcnt(8)
	s_waitcnt lgkmcnt(0)
	s_barrier
	s_setprio 1
	s_waitcnt lgkmcnt(0)
	v_mfma_f32_16x16x32_bf16 v[128:131], v[142:145], v[204:207], v[128:131]
	v_mfma_f32_16x16x32_bf16 v[124:127], v[150:153], v[204:207], v[124:127]
	v_mfma_f32_16x16x32_bf16 v[112:115], v[142:145], v[212:215], v[112:115]
	v_mfma_f32_16x16x32_bf16 v[108:111], v[150:153], v[212:215], v[108:111]
	v_mfma_f32_16x16x32_bf16 v[96:99], v[142:145], v[220:223], v[96:99]
	v_mfma_f32_16x16x32_bf16 v[92:95], v[150:153], v[220:223], v[92:95]
	v_mfma_f32_16x16x32_bf16 v[80:83], v[142:145], v[228:231], v[80:83]
	v_mfma_f32_16x16x32_bf16 v[76:79], v[150:153], v[228:231], v[76:79]
	v_mfma_f32_16x16x32_bf16 v[128:131], v[146:149], v[208:211], v[128:131]
	v_mfma_f32_16x16x32_bf16 v[124:127], v[172:175], v[208:211], v[124:127]
	v_mfma_f32_16x16x32_bf16 v[112:115], v[146:149], v[216:219], v[112:115]
	v_mfma_f32_16x16x32_bf16 v[108:111], v[172:175], v[216:219], v[108:111]
	v_mfma_f32_16x16x32_bf16 v[96:99], v[146:149], v[224:227], v[96:99]
	v_mfma_f32_16x16x32_bf16 v[92:95], v[172:175], v[224:227], v[92:95]
	v_mfma_f32_16x16x32_bf16 v[80:83], v[146:149], v[232:235], v[80:83]
	v_mfma_f32_16x16x32_bf16 v[76:79], v[172:175], v[232:235], v[76:79]
	s_setprio 0
	s_setprio 1
	v_mfma_f32_16x16x32_bf16 v[120:123], v[176:179], v[204:207], v[120:123]
	v_mfma_f32_16x16x32_bf16 v[116:119], v[188:191], v[204:207], v[116:119]
	v_mfma_f32_16x16x32_bf16 v[104:107], v[176:179], v[212:215], v[104:107]
	v_mfma_f32_16x16x32_bf16 v[100:103], v[188:191], v[212:215], v[100:103]
	v_mfma_f32_16x16x32_bf16 v[88:91], v[176:179], v[220:223], v[88:91]
	v_mfma_f32_16x16x32_bf16 v[84:87], v[188:191], v[220:223], v[84:87]
	v_mfma_f32_16x16x32_bf16 v[72:75], v[176:179], v[228:231], v[72:75]
	v_mfma_f32_16x16x32_bf16 v[68:71], v[188:191], v[228:231], v[68:71]
	v_mfma_f32_16x16x32_bf16 v[120:123], v[180:183], v[208:211], v[120:123]
	v_mfma_f32_16x16x32_bf16 v[116:119], v[200:203], v[208:211], v[116:119]
	v_mfma_f32_16x16x32_bf16 v[104:107], v[180:183], v[216:219], v[104:107]
	v_mfma_f32_16x16x32_bf16 v[100:103], v[200:203], v[216:219], v[100:103]
	v_mfma_f32_16x16x32_bf16 v[88:91], v[180:183], v[224:227], v[88:91]
	v_mfma_f32_16x16x32_bf16 v[84:87], v[200:203], v[224:227], v[84:87]
	v_mfma_f32_16x16x32_bf16 v[72:75], v[180:183], v[232:235], v[72:75]
	v_mfma_f32_16x16x32_bf16 v[68:71], v[200:203], v[232:235], v[68:71]
	s_setprio 0
	s_barrier
	s_add_i32 s24, s24, s20
	v_lshl_add_u64 v[154:155], v[154:155], 0, s[26:27]
	s_mov_b32 m0, s24
	ds_read_b128 v[204:207], v187 offset:49152
	ds_read_b128 v[208:211], v187 offset:50176
	ds_read_b128 v[212:215], v187 offset:51200
	ds_read_b128 v[216:219], v187 offset:52224
	ds_read_b128 v[220:223], v187 offset:53248
	ds_read_b128 v[224:227], v187 offset:54272
	ds_read_b128 v[228:231], v187 offset:55296
	ds_read_b128 v[232:235], v187 offset:56320
	global_load_lds_dwordx4 v[154:155], off
	s_add_i32 m0, s24, 0x2000
	s_add_u32 s14, s14, 0x40080
	v_lshl_add_u64 v[154:155], v[192:193], 0, s[26:27]
	s_addc_u32 s15, s15, 0
	s_add_i32 s24, s25, s20
	global_load_lds_dwordx4 v[154:155], off
	v_lshl_add_u64 v[154:155], s[14:15], 0, v[134:135]
	s_mov_b32 m0, s24
	s_nop 0
	global_load_lds_dwordx4 v[154:155], off
	v_lshl_add_u64 v[154:155], s[14:15], 0, v[0:1]
	s_add_i32 m0, s24, 0x2000
	s_nop 0
	global_load_lds_dwordx4 v[154:155], off
	v_lshl_add_u64 v[154:155], v[236:237], 0, s[26:27]
	s_mov_b32 m0, s77
	s_nop 0
	global_load_lds_dwordx4 v[154:155], off
	v_lshl_add_u64 v[154:155], v[238:239], 0, s[26:27]
	s_mov_b32 m0, s87
	s_nop 0
	global_load_lds_dwordx4 v[154:155], off
	s_waitcnt vmcnt(8)
	s_waitcnt lgkmcnt(0)
	s_barrier
	s_setprio 1
	s_waitcnt lgkmcnt(0)
	v_mfma_f32_16x16x32_bf16 v[64:67], v[142:145], v[204:207], v[64:67]
	v_mfma_f32_16x16x32_bf16 v[60:63], v[150:153], v[204:207], v[60:63]
	v_mfma_f32_16x16x32_bf16 v[48:51], v[142:145], v[212:215], v[48:51]
	v_mfma_f32_16x16x32_bf16 v[44:47], v[150:153], v[212:215], v[44:47]
	v_mfma_f32_16x16x32_bf16 v[32:35], v[142:145], v[220:223], v[32:35]
	v_mfma_f32_16x16x32_bf16 v[28:31], v[150:153], v[220:223], v[28:31]
	v_mfma_f32_16x16x32_bf16 v[16:19], v[142:145], v[228:231], v[16:19]
	v_mfma_f32_16x16x32_bf16 v[12:15], v[150:153], v[228:231], v[12:15]
	v_mfma_f32_16x16x32_bf16 v[64:67], v[146:149], v[208:211], v[64:67]
	v_mfma_f32_16x16x32_bf16 v[60:63], v[172:175], v[208:211], v[60:63]
	v_mfma_f32_16x16x32_bf16 v[48:51], v[146:149], v[216:219], v[48:51]
	v_mfma_f32_16x16x32_bf16 v[44:47], v[172:175], v[216:219], v[44:47]
	v_mfma_f32_16x16x32_bf16 v[32:35], v[146:149], v[224:227], v[32:35]
	v_mfma_f32_16x16x32_bf16 v[28:31], v[172:175], v[224:227], v[28:31]
	v_mfma_f32_16x16x32_bf16 v[16:19], v[146:149], v[232:235], v[16:19]
	v_mfma_f32_16x16x32_bf16 v[12:15], v[172:175], v[232:235], v[12:15]
	s_setprio 0
	s_setprio 1
	v_mfma_f32_16x16x32_bf16 v[56:59], v[176:179], v[204:207], v[56:59]
	v_mfma_f32_16x16x32_bf16 v[52:55], v[188:191], v[204:207], v[52:55]
	v_mfma_f32_16x16x32_bf16 v[40:43], v[176:179], v[212:215], v[40:43]
	v_mfma_f32_16x16x32_bf16 v[36:39], v[188:191], v[212:215], v[36:39]
	v_mfma_f32_16x16x32_bf16 v[24:27], v[176:179], v[220:223], v[24:27]
	v_mfma_f32_16x16x32_bf16 v[20:23], v[188:191], v[220:223], v[20:23]
	v_mfma_f32_16x16x32_bf16 v[8:11], v[176:179], v[228:231], v[8:11]
	v_mfma_f32_16x16x32_bf16 v[4:7], v[188:191], v[228:231], v[4:7]
	v_mfma_f32_16x16x32_bf16 v[56:59], v[180:183], v[208:211], v[56:59]
	v_mfma_f32_16x16x32_bf16 v[52:55], v[200:203], v[208:211], v[52:55]
	v_mfma_f32_16x16x32_bf16 v[40:43], v[180:183], v[216:219], v[40:43]
	v_mfma_f32_16x16x32_bf16 v[36:39], v[200:203], v[216:219], v[36:39]
	v_mfma_f32_16x16x32_bf16 v[24:27], v[180:183], v[224:227], v[24:27]
	v_mfma_f32_16x16x32_bf16 v[20:23], v[200:203], v[224:227], v[20:23]
	v_mfma_f32_16x16x32_bf16 v[8:11], v[180:183], v[232:235], v[8:11]
	v_mfma_f32_16x16x32_bf16 v[4:7], v[200:203], v[232:235], v[4:7]
	s_setprio 0
	s_barrier
	s_add_i32 s96, s96, 2
	s_add_u32 s60, s60, 0x100
	s_addc_u32 s61, s61, 0
	s_add_u32 s12, s12, 0x100
	s_addc_u32 s13, s13, 0
	s_cmp_gt_u32 s96, 13
	s_cbranch_scc0 .LBB0_72
	s_branch .Lpeel_exit_G1B
.LBB0_72:
	s_add_u32 s14, s12, 0xfffc0080
	s_addc_u32 s15, s13, -1
	s_add_i32 s24, 0, 0x10000
	s_cmp_eq_u32 s96, 12
	s_cselect_b32 s45, s39, s15
	s_cselect_b32 s44, s54, s14
	v_add_u32_e32 v2, s24, v185
	s_cselect_b32 s15, s29, s61
	s_cselect_b32 s14, s55, s60
	s_add_i32 s25, 0, 0x14000
	ds_read_b128 v[142:145], v2
	ds_read_b128 v[146:149], v2 offset:1024
	ds_read_b128 v[150:153], v2 offset:2048
	ds_read_b128 v[172:175], v2 offset:3072
	v_add_u32_e32 v2, s25, v185
	ds_read_b128 v[176:179], v2
	ds_read_b128 v[180:183], v2 offset:1024
	ds_read_b128 v[188:191], v2 offset:2048
	ds_read_b128 v[200:203], v2 offset:3072
	v_lshl_add_u64 v[154:155], s[12:13], 0, v[140:141]
	s_add_i32 m0, s21, 0xc000
	ds_read_b128 v[204:207], v187
	ds_read_b128 v[208:211], v187 offset:1024
	ds_read_b128 v[212:215], v187 offset:2048
	ds_read_b128 v[216:219], v187 offset:3072
	ds_read_b128 v[220:223], v187 offset:4096
	ds_read_b128 v[224:227], v187 offset:5120
	ds_read_b128 v[228:231], v187 offset:6144
	ds_read_b128 v[232:235], v187 offset:7168
	global_load_lds_dwordx4 v[154:155], off
	v_lshl_add_u64 v[154:155], s[12:13], 0, v[138:139]
	s_add_i32 m0, s21, 0xe000
	s_nop 0
	global_load_lds_dwordx4 v[154:155], off
	s_waitcnt vmcnt(8)
	s_waitcnt lgkmcnt(0)
	s_barrier
	s_setprio 1
	s_waitcnt lgkmcnt(0)
	v_mfma_f32_16x16x32_bf16 v[128:131], v[142:145], v[204:207], v[128:131]
	v_mfma_f32_16x16x32_bf16 v[124:127], v[150:153], v[204:207], v[124:127]
	v_mfma_f32_16x16x32_bf16 v[112:115], v[142:145], v[212:215], v[112:115]
	v_mfma_f32_16x16x32_bf16 v[108:111], v[150:153], v[212:215], v[108:111]
	v_mfma_f32_16x16x32_bf16 v[96:99], v[142:145], v[220:223], v[96:99]
	v_mfma_f32_16x16x32_bf16 v[92:95], v[150:153], v[220:223], v[92:95]
	v_mfma_f32_16x16x32_bf16 v[80:83], v[142:145], v[228:231], v[80:83]
	v_mfma_f32_16x16x32_bf16 v[76:79], v[150:153], v[228:231], v[76:79]
	v_mfma_f32_16x16x32_bf16 v[128:131], v[146:149], v[208:211], v[128:131]
	v_mfma_f32_16x16x32_bf16 v[124:127], v[172:175], v[208:211], v[124:127]
	v_mfma_f32_16x16x32_bf16 v[112:115], v[146:149], v[216:219], v[112:115]
	v_mfma_f32_16x16x32_bf16 v[108:111], v[172:175], v[216:219], v[108:111]
	v_mfma_f32_16x16x32_bf16 v[96:99], v[146:149], v[224:227], v[96:99]
	v_mfma_f32_16x16x32_bf16 v[92:95], v[172:175], v[224:227], v[92:95]
	v_mfma_f32_16x16x32_bf16 v[80:83], v[146:149], v[232:235], v[80:83]
	v_mfma_f32_16x16x32_bf16 v[76:79], v[172:175], v[232:235], v[76:79]
	s_setprio 0
	s_setprio 1
	v_mfma_f32_16x16x32_bf16 v[120:123], v[176:179], v[204:207], v[120:123]
	v_mfma_f32_16x16x32_bf16 v[116:119], v[188:191], v[204:207], v[116:119]
	v_mfma_f32_16x16x32_bf16 v[104:107], v[176:179], v[212:215], v[104:107]
	v_mfma_f32_16x16x32_bf16 v[100:103], v[188:191], v[212:215], v[100:103]
	v_mfma_f32_16x16x32_bf16 v[88:91], v[176:179], v[220:223], v[88:91]
	v_mfma_f32_16x16x32_bf16 v[84:87], v[188:191], v[220:223], v[84:87]
	v_mfma_f32_16x16x32_bf16 v[72:75], v[176:179], v[228:231], v[72:75]
	v_mfma_f32_16x16x32_bf16 v[68:71], v[188:191], v[228:231], v[68:71]
	v_mfma_f32_16x16x32_bf16 v[120:123], v[180:183], v[208:211], v[120:123]
	v_mfma_f32_16x16x32_bf16 v[116:119], v[200:203], v[208:211], v[116:119]
	v_mfma_f32_16x16x32_bf16 v[104:107], v[180:183], v[216:219], v[104:107]
	v_mfma_f32_16x16x32_bf16 v[100:103], v[200:203], v[216:219], v[100:103]
	v_mfma_f32_16x16x32_bf16 v[88:91], v[180:183], v[224:227], v[88:91]
	v_mfma_f32_16x16x32_bf16 v[84:87], v[200:203], v[224:227], v[84:87]
	v_mfma_f32_16x16x32_bf16 v[72:75], v[180:183], v[232:235], v[72:75]
	v_mfma_f32_16x16x32_bf16 v[68:71], v[200:203], v[232:235], v[68:71]
	s_setprio 0
	s_barrier
	s_add_i32 s24, s24, s20
	v_lshl_add_u64 v[154:155], s[14:15], 0, v[134:135]
	s_mov_b32 m0, s24
	ds_read_b128 v[204:207], v187 offset:16384
	ds_read_b128 v[208:211], v187 offset:17408
	ds_read_b128 v[212:215], v187 offset:18432
	ds_read_b128 v[216:219], v187 offset:19456
	ds_read_b128 v[220:223], v187 offset:20480
	ds_read_b128 v[224:227], v187 offset:21504
	ds_read_b128 v[228:231], v187 offset:22528
	ds_read_b128 v[232:235], v187 offset:23552
	global_load_lds_dwordx4 v[154:155], off
	s_add_i32 m0, s24, 0x2000
	s_add_u32 vcc_lo, s14, 0x40000
	v_lshl_add_u64 v[192:193], s[14:15], 0, v[0:1]
	s_addc_u32 vcc_hi, s15, 0
	s_add_i32 s24, s25, s20
	global_load_lds_dwordx4 v[192:193], off
	v_lshl_add_u64 v[236:237], vcc, 0, v[134:135]
	s_mov_b32 m0, s24
	v_lshl_add_u64 v[238:239], s[44:45], 0, v[132:133]
	global_load_lds_dwordx4 v[236:237], off
	v_lshl_add_u64 v[236:237], vcc, 0, v[0:1]
	s_add_i32 m0, s24, 0x2000
	s_nop 0
	global_load_lds_dwordx4 v[236:237], off
	v_lshl_add_u64 v[236:237], s[44:45], 0, v[136:137]
	s_mov_b32 m0, s21
	s_nop 0
	global_load_lds_dwordx4 v[236:237], off
	s_mov_b32 m0, s22
	s_nop 0
	global_load_lds_dwordx4 v[238:239], off
	s_waitcnt vmcnt(8)
	s_waitcnt lgkmcnt(0)
	s_barrier
	s_setprio 1
	s_waitcnt lgkmcnt(0)
	v_mfma_f32_16x16x32_bf16 v[64:67], v[142:145], v[204:207], v[64:67]
	v_mfma_f32_16x16x32_bf16 v[60:63], v[150:153], v[204:207], v[60:63]
	v_mfma_f32_16x16x32_bf16 v[48:51], v[142:145], v[212:215], v[48:51]
	v_mfma_f32_16x16x32_bf16 v[44:47], v[150:153], v[212:215], v[44:47]
	v_mfma_f32_16x16x32_bf16 v[32:35], v[142:145], v[220:223], v[32:35]
	v_mfma_f32_16x16x32_bf16 v[28:31], v[150:153], v[220:223], v[28:31]
	v_mfma_f32_16x16x32_bf16 v[16:19], v[142:145], v[228:231], v[16:19]
	v_mfma_f32_16x16x32_bf16 v[12:15], v[150:153], v[228:231], v[12:15]
	v_mfma_f32_16x16x32_bf16 v[64:67], v[146:149], v[208:211], v[64:67]
	v_mfma_f32_16x16x32_bf16 v[60:63], v[172:175], v[208:211], v[60:63]
	v_mfma_f32_16x16x32_bf16 v[48:51], v[146:149], v[216:219], v[48:51]
	v_mfma_f32_16x16x32_bf16 v[44:47], v[172:175], v[216:219], v[44:47]
	v_mfma_f32_16x16x32_bf16 v[32:35], v[146:149], v[224:227], v[32:35]
	v_mfma_f32_16x16x32_bf16 v[28:31], v[172:175], v[224:227], v[28:31]
	v_mfma_f32_16x16x32_bf16 v[16:19], v[146:149], v[232:235], v[16:19]
	v_mfma_f32_16x16x32_bf16 v[12:15], v[172:175], v[232:235], v[12:15]
	s_setprio 0
	s_setprio 1
	v_mfma_f32_16x16x32_bf16 v[56:59], v[176:179], v[204:207], v[56:59]
	v_mfma_f32_16x16x32_bf16 v[52:55], v[188:191], v[204:207], v[52:55]
	v_mfma_f32_16x16x32_bf16 v[40:43], v[176:179], v[212:215], v[40:43]
	v_mfma_f32_16x16x32_bf16 v[36:39], v[188:191], v[212:215], v[36:39]
	v_mfma_f32_16x16x32_bf16 v[24:27], v[176:179], v[220:223], v[24:27]
	v_mfma_f32_16x16x32_bf16 v[20:23], v[188:191], v[220:223], v[20:23]
	v_mfma_f32_16x16x32_bf16 v[8:11], v[176:179], v[228:231], v[8:11]
	v_mfma_f32_16x16x32_bf16 v[4:7], v[188:191], v[228:231], v[4:7]
	v_mfma_f32_16x16x32_bf16 v[56:59], v[180:183], v[208:211], v[56:59]
	v_mfma_f32_16x16x32_bf16 v[52:55], v[200:203], v[208:211], v[52:55]
	v_mfma_f32_16x16x32_bf16 v[40:43], v[180:183], v[216:219], v[40:43]
	v_mfma_f32_16x16x32_bf16 v[36:39], v[200:203], v[216:219], v[36:39]
	v_mfma_f32_16x16x32_bf16 v[24:27], v[180:183], v[224:227], v[24:27]
	v_mfma_f32_16x16x32_bf16 v[20:23], v[200:203], v[224:227], v[20:23]
	v_mfma_f32_16x16x32_bf16 v[8:11], v[180:183], v[232:235], v[8:11]
	v_mfma_f32_16x16x32_bf16 v[4:7], v[200:203], v[232:235], v[4:7]
	s_setprio 0
	s_barrier
	s_add_i32 s24, 0, 0x18000
	v_add_u32_e32 v2, s24, v185
	s_add_i32 s25, 0, 0x1c000
	ds_read_b128 v[142:145], v2
	ds_read_b128 v[146:149], v2 offset:1024
	ds_read_b128 v[150:153], v2 offset:2048
	ds_read_b128 v[172:175], v2 offset:3072
	v_add_u32_e32 v2, s25, v185
	ds_read_b128 v[176:179], v2
	ds_read_b128 v[180:183], v2 offset:1024
	ds_read_b128 v[188:191], v2 offset:2048
	ds_read_b128 v[200:203], v2 offset:3072
	s_add_u32 s44, s44, 0x40000
	s_addc_u32 s45, s45, 0
	s_mov_b32 m0, s23
	v_lshl_add_u64 v[240:241], s[44:45], 0, v[136:137]
	ds_read_b128 v[204:207], v187 offset:32768
	ds_read_b128 v[208:211], v187 offset:33792
	ds_read_b128 v[212:215], v187 offset:34816
	ds_read_b128 v[216:219], v187 offset:35840
	ds_read_b128 v[220:223], v187 offset:36864
	ds_read_b128 v[224:227], v187 offset:37888
	ds_read_b128 v[228:231], v187 offset:38912
	ds_read_b128 v[232:235], v187 offset:39936
	global_load_lds_dwordx4 v[240:241], off
	v_lshl_add_u64 v[240:241], s[44:45], 0, v[132:133]
	s_mov_b32 m0, s36
	s_nop 0
	global_load_lds_dwordx4 v[240:241], off
	s_waitcnt vmcnt(8)
	s_waitcnt lgkmcnt(0)
	s_barrier
	s_setprio 1
	s_waitcnt lgkmcnt(0)
	v_mfma_f32_16x16x32_bf16 v[128:131], v[142:145], v[204:207], v[128:131]
	v_mfma_f32_16x16x32_bf16 v[124:127], v[150:153], v[204:207], v[124:127]
	v_mfma_f32_16x16x32_bf16 v[112:115], v[142:145], v[212:215], v[112:115]
	v_mfma_f32_16x16x32_bf16 v[108:111], v[150:153], v[212:215], v[108:111]
	v_mfma_f32_16x16x32_bf16 v[96:99], v[142:145], v[220:223], v[96:99]
	v_mfma_f32_16x16x32_bf16 v[92:95], v[150:153], v[220:223], v[92:95]
	v_mfma_f32_16x16x32_bf16 v[80:83], v[142:145], v[228:231], v[80:83]
	v_mfma_f32_16x16x32_bf16 v[76:79], v[150:153], v[228:231], v[76:79]
	v_mfma_f32_16x16x32_bf16 v[128:131], v[146:149], v[208:211], v[128:131]
	v_mfma_f32_16x16x32_bf16 v[124:127], v[172:175], v[208:211], v[124:127]
	v_mfma_f32_16x16x32_bf16 v[112:115], v[146:149], v[216:219], v[112:115]
	v_mfma_f32_16x16x32_bf16 v[108:111], v[172:175], v[216:219], v[108:111]
	v_mfma_f32_16x16x32_bf16 v[96:99], v[146:149], v[224:227], v[96:99]
	v_mfma_f32_16x16x32_bf16 v[92:95], v[172:175], v[224:227], v[92:95]
	v_mfma_f32_16x16x32_bf16 v[80:83], v[146:149], v[232:235], v[80:83]
	v_mfma_f32_16x16x32_bf16 v[76:79], v[172:175], v[232:235], v[76:79]
	s_setprio 0
	s_setprio 1
	v_mfma_f32_16x16x32_bf16 v[120:123], v[176:179], v[204:207], v[120:123]
	v_mfma_f32_16x16x32_bf16 v[116:119], v[188:191], v[204:207], v[116:119]
	v_mfma_f32_16x16x32_bf16 v[104:107], v[176:179], v[212:215], v[104:107]
	v_mfma_f32_16x16x32_bf16 v[100:103], v[188:191], v[212:215], v[100:103]
	v_mfma_f32_16x16x32_bf16 v[88:91], v[176:179], v[220:223], v[88:91]
	v_mfma_f32_16x16x32_bf16 v[84:87], v[188:191], v[220:223], v[84:87]
	v_mfma_f32_16x16x32_bf16 v[72:75], v[176:179], v[228:231], v[72:75]
	v_mfma_f32_16x16x32_bf16 v[68:71], v[188:191], v[228:231], v[68:71]
	v_mfma_f32_16x16x32_bf16 v[120:123], v[180:183], v[208:211], v[120:123]
	v_mfma_f32_16x16x32_bf16 v[116:119], v[200:203], v[208:211], v[116:119]
	v_mfma_f32_16x16x32_bf16 v[104:107], v[180:183], v[216:219], v[104:107]
	v_mfma_f32_16x16x32_bf16 v[100:103], v[200:203], v[216:219], v[100:103]
	v_mfma_f32_16x16x32_bf16 v[88:91], v[180:183], v[224:227], v[88:91]
	v_mfma_f32_16x16x32_bf16 v[84:87], v[200:203], v[224:227], v[84:87]
	v_mfma_f32_16x16x32_bf16 v[72:75], v[180:183], v[232:235], v[72:75]
	v_mfma_f32_16x16x32_bf16 v[68:71], v[200:203], v[232:235], v[68:71]
	s_setprio 0
	s_barrier
	s_add_i32 s24, s24, s20
	v_lshl_add_u64 v[154:155], v[154:155], 0, s[26:27]
	s_mov_b32 m0, s24
	ds_read_b128 v[204:207], v187 offset:49152
	ds_read_b128 v[208:211], v187 offset:50176
	ds_read_b128 v[212:215], v187 offset:51200
	ds_read_b128 v[216:219], v187 offset:52224
	ds_read_b128 v[220:223], v187 offset:53248
	ds_read_b128 v[224:227], v187 offset:54272
	ds_read_b128 v[228:231], v187 offset:55296
	ds_read_b128 v[232:235], v187 offset:56320
	global_load_lds_dwordx4 v[154:155], off
	s_add_i32 m0, s24, 0x2000
	s_add_u32 s14, s14, 0x40080
	v_lshl_add_u64 v[154:155], v[192:193], 0, s[26:27]
	s_addc_u32 s15, s15, 0
	s_add_i32 s24, s25, s20
	global_load_lds_dwordx4 v[154:155], off
	v_lshl_add_u64 v[154:155], s[14:15], 0, v[134:135]
	s_mov_b32 m0, s24
	s_nop 0
	global_load_lds_dwordx4 v[154:155], off
	v_lshl_add_u64 v[154:155], s[14:15], 0, v[0:1]
	s_add_i32 m0, s24, 0x2000
	s_nop 0
	global_load_lds_dwordx4 v[154:155], off
	v_lshl_add_u64 v[154:155], v[236:237], 0, s[26:27]
	s_mov_b32 m0, s77
	s_nop 0
	global_load_lds_dwordx4 v[154:155], off
	v_lshl_add_u64 v[154:155], v[238:239], 0, s[26:27]
	s_mov_b32 m0, s87
	s_nop 0
	global_load_lds_dwordx4 v[154:155], off
	s_waitcnt vmcnt(8)
	s_waitcnt lgkmcnt(0)
	s_barrier
	s_setprio 1
	s_waitcnt lgkmcnt(0)
	v_mfma_f32_16x16x32_bf16 v[64:67], v[142:145], v[204:207], v[64:67]
	v_mfma_f32_16x16x32_bf16 v[60:63], v[150:153], v[204:207], v[60:63]
	v_mfma_f32_16x16x32_bf16 v[48:51], v[142:145], v[212:215], v[48:51]
	v_mfma_f32_16x16x32_bf16 v[44:47], v[150:153], v[212:215], v[44:47]
	v_mfma_f32_16x16x32_bf16 v[32:35], v[142:145], v[220:223], v[32:35]
	v_mfma_f32_16x16x32_bf16 v[28:31], v[150:153], v[220:223], v[28:31]
	v_mfma_f32_16x16x32_bf16 v[16:19], v[142:145], v[228:231], v[16:19]
	v_mfma_f32_16x16x32_bf16 v[12:15], v[150:153], v[228:231], v[12:15]
	v_mfma_f32_16x16x32_bf16 v[64:67], v[146:149], v[208:211], v[64:67]
	v_mfma_f32_16x16x32_bf16 v[60:63], v[172:175], v[208:211], v[60:63]
	v_mfma_f32_16x16x32_bf16 v[48:51], v[146:149], v[216:219], v[48:51]
	v_mfma_f32_16x16x32_bf16 v[44:47], v[172:175], v[216:219], v[44:47]
	v_mfma_f32_16x16x32_bf16 v[32:35], v[146:149], v[224:227], v[32:35]
	v_mfma_f32_16x16x32_bf16 v[28:31], v[172:175], v[224:227], v[28:31]
	v_mfma_f32_16x16x32_bf16 v[16:19], v[146:149], v[232:235], v[16:19]
	v_mfma_f32_16x16x32_bf16 v[12:15], v[172:175], v[232:235], v[12:15]
	s_setprio 0
	s_setprio 1
	v_mfma_f32_16x16x32_bf16 v[56:59], v[176:179], v[204:207], v[56:59]
	v_mfma_f32_16x16x32_bf16 v[52:55], v[188:191], v[204:207], v[52:55]
	v_mfma_f32_16x16x32_bf16 v[40:43], v[176:179], v[212:215], v[40:43]
	v_mfma_f32_16x16x32_bf16 v[36:39], v[188:191], v[212:215], v[36:39]
	v_mfma_f32_16x16x32_bf16 v[24:27], v[176:179], v[220:223], v[24:27]
	v_mfma_f32_16x16x32_bf16 v[20:23], v[188:191], v[220:223], v[20:23]
	v_mfma_f32_16x16x32_bf16 v[8:11], v[176:179], v[228:231], v[8:11]
	v_mfma_f32_16x16x32_bf16 v[4:7], v[188:191], v[228:231], v[4:7]
	v_mfma_f32_16x16x32_bf16 v[56:59], v[180:183], v[208:211], v[56:59]
	v_mfma_f32_16x16x32_bf16 v[52:55], v[200:203], v[208:211], v[52:55]
	v_mfma_f32_16x16x32_bf16 v[40:43], v[180:183], v[216:219], v[40:43]
	v_mfma_f32_16x16x32_bf16 v[36:39], v[200:203], v[216:219], v[36:39]
	v_mfma_f32_16x16x32_bf16 v[24:27], v[180:183], v[224:227], v[24:27]
	v_mfma_f32_16x16x32_bf16 v[20:23], v[200:203], v[224:227], v[20:23]
	v_mfma_f32_16x16x32_bf16 v[8:11], v[180:183], v[232:235], v[8:11]
	v_mfma_f32_16x16x32_bf16 v[4:7], v[200:203], v[232:235], v[4:7]
	s_setprio 0
	s_barrier
	s_add_i32 s96, s96, 2
	s_add_u32 s60, s60, 0x100
	s_addc_u32 s61, s61, 0
	s_add_u32 s12, s12, 0x100
	s_addc_u32 s13, s13, 0
	s_cmp_gt_u32 s96, 13
	s_cbranch_scc0 .LBB0_72
.Lpeel_exit_G1B:
	s_and_b64 vcc, exec, s[10:11]
	s_cbranch_vccz .LBB0_75
	s_barrier
.LBB0_75:
	v_lshl_add_u32 v142, s47, 8, v184
	v_ashrrev_i32_e32 v143, 31, v142
	v_lshl_add_u64 v[144:145], v[142:143], 2, s[4:5]
	global_load_dword v208, v[144:145], off
	global_load_dword v209, v[144:145], off offset:64
	global_load_dword v210, v[144:145], off offset:128
	global_load_dword v211, v[144:145], off offset:192
	global_load_dword v212, v[144:145], off offset:512
	global_load_dword v213, v[144:145], off offset:576
	global_load_dword v214, v[144:145], off offset:640
	global_load_dword v215, v[144:145], off offset:704
	s_mul_hi_i32 s12, s46, 0x55555556
	s_lshr_b32 s13, s12, 31
	s_add_i32 s12, s12, s13
	s_mul_i32 s12, s12, 3
	s_sub_i32 s12, s46, s12
	v_lshl_or_b32 v2, s12, 8, v186
	s_add_i32 s12, s46, -6
	s_cmp_gt_u32 s12, 2
	s_cselect_b64 s[14:15], -1, 0
	s_add_i32 s12, s46, 2
	s_cmp_lt_u32 s12, 5
	s_cselect_b64 s[12:13], -1, 0
	s_and_b64 vcc, exec, s[14:15]
	s_mov_b32 s24, 0xbf3a00e3
	s_mov_b64 s[96:97], s[68:69]
	s_waitcnt vmcnt(0)
	v_fmamk_f32 v146, v208, 0x3a800000, v195
	v_rsq_f32_e32 v148, v146
	v_mad_i64_i32 v[146:147], s[44:45], v142, s95, 0
	s_mov_b64 s[44:45], -1
	v_pk_mul_f32 v[152:153], v[130:131], v[148:149] op_sel_hi:[1,0]
	v_pk_mul_f32 v[154:155], v[128:129], v[148:149] op_sel_hi:[1,0]
	v_pk_mul_f32 v[130:131], v[126:127], v[148:149] op_sel_hi:[1,0]
	v_pk_mul_f32 v[150:151], v[124:125], v[148:149] op_sel_hi:[1,0]
	v_ashrrev_i32_e32 v125, 31, v2
	s_cbranch_vccz .LBB0_77
	v_and_b32_e32 v127, 0x7fffffff, v155
	v_and_b32_e32 v126, 0x7fffffff, v154
	v_pk_fma_f32 v[126:127], v[126:127], s[52:53], 1.0 op_sel_hi:[1,0,0]
	v_mov_b64_e32 v[128:129], s[24:25]
	v_rcp_f32_e32 v126, v126
	v_rcp_f32_e32 v127, v127
	v_pk_mul_f32 v[174:175], v[154:155], v[154:155]
	v_and_b32_e32 v177, 0x7fffffff, v153
	v_and_b32_e32 v176, 0x7fffffff, v152
	v_pk_fma_f32 v[172:173], v[126:127], s[62:63], v[128:129] op_sel_hi:[1,0,0]
	v_pk_mul_f32 v[174:175], v[174:175], s[86:87] op_sel_hi:[1,0]
	v_pk_fma_f32 v[176:177], v[176:177], s[52:53], 1.0 op_sel_hi:[1,0,0]
	v_pk_fma_f32 v[172:173], v[126:127], v[172:173], s[30:31] op_sel_hi:[1,1,0]
	v_exp_f32_e32 v174, v174
	v_exp_f32_e32 v175, v175
	v_rcp_f32_e32 v176, v176
	v_rcp_f32_e32 v177, v177
	v_pk_fma_f32 v[172:173], v[126:127], v[172:173], s[94:95] op_sel_hi:[1,1,0]
	v_pk_mul_f32 v[182:183], v[150:151], v[150:151]
	v_pk_fma_f32 v[172:173], v[126:127], v[172:173], s[84:85] op_sel_hi:[1,1,0]
	v_pk_mul_f32 v[182:183], v[182:183], s[86:87] op_sel_hi:[1,0]
	v_pk_mul_f32 v[126:127], v[126:127], v[172:173]
	v_pk_mul_f32 v[172:173], v[152:153], v[152:153]
	v_pk_mul_f32 v[126:127], v[174:175], v[126:127]
	v_pk_fma_f32 v[174:175], v[176:177], s[62:63], v[128:129] op_sel_hi:[1,0,0]
	v_pk_mul_f32 v[172:173], v[172:173], s[86:87] op_sel_hi:[1,0]
	v_pk_fma_f32 v[174:175], v[176:177], v[174:175], s[30:31] op_sel_hi:[1,1,0]
	v_exp_f32_e32 v172, v172
	v_pk_fma_f32 v[174:175], v[176:177], v[174:175], s[94:95] op_sel_hi:[1,1,0]
	v_exp_f32_e32 v173, v173
	v_pk_fma_f32 v[174:175], v[176:177], v[174:175], s[84:85] op_sel_hi:[1,1,0]
	v_and_b32_e32 v189, 0x7fffffff, v131
	v_pk_mul_f32 v[174:175], v[176:177], v[174:175]
	v_and_b32_e32 v177, 0x7fffffff, v151
	v_and_b32_e32 v176, 0x7fffffff, v150
	v_pk_fma_f32 v[176:177], v[176:177], s[52:53], 1.0 op_sel_hi:[1,0,0]
	v_pk_mul_f32 v[172:173], v[172:173], v[174:175]
	v_rcp_f32_e32 v176, v176
	v_rcp_f32_e32 v177, v177
	v_and_b32_e32 v188, 0x7fffffff, v130
	v_exp_f32_e32 v182, v182
	v_exp_f32_e32 v183, v183
	v_pk_fma_f32 v[174:175], v[176:177], s[62:63], v[128:129] op_sel_hi:[1,0,0]
	v_pk_fma_f32 v[188:189], v[188:189], s[52:53], 1.0 op_sel_hi:[1,0,0]
	v_pk_fma_f32 v[174:175], v[176:177], v[174:175], s[30:31] op_sel_hi:[1,1,0]
	v_rcp_f32_e32 v188, v188
	v_pk_fma_f32 v[174:175], v[176:177], v[174:175], s[94:95] op_sel_hi:[1,1,0]
	v_rcp_f32_e32 v189, v189
	v_pk_fma_f32 v[174:175], v[176:177], v[174:175], s[84:85] op_sel_hi:[1,1,0]
	v_cmp_gt_f32_e32 vcc, 0, v150
	v_pk_mul_f32 v[174:175], v[176:177], v[174:175]
	v_pk_mul_f32 v[176:177], v[130:131], v[130:131]
	v_pk_mul_f32 v[174:175], v[182:183], v[174:175]
	v_pk_fma_f32 v[128:129], v[188:189], s[62:63], v[128:129] op_sel_hi:[1,0,0]
	v_pk_mul_f32 v[182:183], v[150:151], v[174:175]
	v_pk_fma_f32 v[190:191], v[150:151], v[174:175], v[150:151] neg_lo:[1,0,0] neg_hi:[1,0,0]
	v_pk_mul_f32 v[174:175], v[176:177], s[86:87] op_sel_hi:[1,0]
	v_pk_fma_f32 v[128:129], v[188:189], v[128:129], s[30:31] op_sel_hi:[1,1,0]
	v_exp_f32_e32 v174, v174
	v_exp_f32_e32 v175, v175
	v_pk_fma_f32 v[128:129], v[188:189], v[128:129], s[94:95] op_sel_hi:[1,1,0]
	v_pk_mul_f32 v[178:179], v[154:155], v[126:127]
	v_pk_fma_f32 v[126:127], v[154:155], v[126:127], v[154:155] neg_lo:[1,0,0] neg_hi:[1,0,0]
	v_pk_fma_f32 v[128:129], v[188:189], v[128:129], s[84:85] op_sel_hi:[1,1,0]
	v_cndmask_b32_e32 v193, v190, v182, vcc
	v_cmp_gt_f32_e32 vcc, 0, v154
	v_pk_mul_f32 v[128:129], v[188:189], v[128:129]
	v_pk_mul_f32 v[180:181], v[152:153], v[172:173]
	v_cndmask_b32_e32 v192, v126, v178, vcc
	v_cmp_gt_f32_e32 vcc, 0, v151
	v_pk_mul_f32 v[128:129], v[174:175], v[128:129]
	v_pk_fma_f32 v[172:173], v[152:153], v[172:173], v[152:153] neg_lo:[1,0,0] neg_hi:[1,0,0]
	v_cndmask_b32_e32 v177, v191, v183, vcc
	v_cmp_gt_f32_e32 vcc, 0, v155
	v_pk_mul_f32 v[188:189], v[130:131], v[128:129]
	v_pk_fma_f32 v[128:129], v[130:131], v[128:129], v[130:131] neg_lo:[1,0,0] neg_hi:[1,0,0]
	v_cndmask_b32_e32 v176, v127, v179, vcc
	v_cmp_gt_f32_e32 vcc, 0, v130
	v_pk_add_f32 v[126:127], v[192:193], v[176:177]
	s_and_b64 s[44:45], s[12:13], exec
	v_cndmask_b32_e32 v191, v128, v188, vcc
	v_cmp_gt_f32_e32 vcc, 0, v152
	s_cselect_b32 s45, s64, s76
	s_cselect_b32 s44, s63, s65
	v_cndmask_b32_e32 v190, v172, v180, vcc
	v_cmp_gt_f32_e32 vcc, 0, v131
	v_lshl_add_u64 v[174:175], s[44:45], 0, v[146:147]
	v_mov_b32_e32 v124, v2
	v_cndmask_b32_e32 v179, v129, v189, vcc
	v_cmp_gt_f32_e32 vcc, 0, v153
	v_lshl_add_u64 v[174:175], v[124:125], 1, v[174:175]
	s_mov_b64 s[44:45], 0
	v_cndmask_b32_e32 v178, v173, v181, vcc
	v_pk_add_f32 v[128:129], v[190:191], v[178:179]
	v_pk_mul_f32 v[172:173], v[178:179], v[178:179]
	v_pk_add_f32 v[128:129], v[126:127], v[128:129]
	v_pk_mul_f32 v[126:127], v[176:177], v[176:177]
	v_pk_fma_f32 v[172:173], v[190:191], v[190:191], v[172:173]
	v_pk_fma_f32 v[126:127], v[192:193], v[192:193], v[126:127]
	v_add_f32_e32 v128, v128, v129
	v_pk_add_f32 v[126:127], v[126:127], v[172:173]
	v_mov_b32_e32 v181, v178
	v_add_f32_e32 v126, v126, v127
	v_mov_b32_e32 v180, v190
	v_mov_b32_e32 v183, v176
	v_mov_b32_e32 v182, v192
	v_mov_b32_e32 v178, v191
	v_mov_b32_e32 v176, v193

.LBB0_197:
	s_ashr_i32 s7, s6, 31
	s_lshl_b64 s[8:9], s[6:7], 19
	s_add_u32 s8, s36, s8
	s_addc_u32 s9, s91, s9
	s_and_b64 s[10:11], s[40:41], exec
	s_cselect_b32 s7, s9, s1
	s_cselect_b32 s23, s8, s0
	s_ashr_i32 s5, s4, 31
	s_lshl_b64 s[10:11], s[4:5], 19
	s_add_u32 s10, s46, s10
	s_addc_u32 s11, s47, s11
	s_and_b64 s[14:15], s[40:41], exec
	s_cselect_b32 s5, s11, s13
	s_cselect_b32 s42, s10, s12
	s_add_u32 s43, s12, 0x100
	s_addc_u32 s44, s13, 0
	s_add_u32 s0, s0, 0x40080
	s_addc_u32 s1, s1, 0
	s_mov_b32 s45, -2
	s_add_u32 s12, s0, 0xfffc0080
	s_addc_u32 s13, s1, -1
	s_add_i32 vcc_lo, 0, 0x10000
	s_cmp_eq_u32 s45, 12
	s_cselect_b32 s15, s7, s13
	s_cselect_b32 s14, s23, s12
	v_add_u32_e32 v2, vcc_lo, v200
	s_cselect_b32 s13, s5, s44
	s_cselect_b32 s12, s42, s43
	s_add_i32 s24, 0, 0x14000
	ds_read_b128 v[20:23], v2
	ds_read_b128 v[24:27], v2 offset:1024
	ds_read_b128 v[36:39], v2 offset:2048
	ds_read_b128 v[40:43], v2 offset:3072
	v_add_u32_e32 v2, s24, v200
	ds_read_b128 v[148:151], v2
	ds_read_b128 v[152:155], v2 offset:1024
	ds_read_b128 v[182:185], v2 offset:2048
	ds_read_b128 v[186:189], v2 offset:3072
	v_lshl_add_u64 v[232:233], s[0:1], 0, v[180:181]
	s_add_i32 m0, s63, 0xc000
	ds_read_b128 v[190:193], v202
	ds_read_b128 v[204:207], v202 offset:1024
	ds_read_b128 v[208:211], v202 offset:2048
	ds_read_b128 v[212:215], v202 offset:3072
	ds_read_b128 v[216:219], v202 offset:4096
	ds_read_b128 v[220:223], v202 offset:5120
	ds_read_b128 v[224:227], v202 offset:6144
	ds_read_b128 v[228:231], v202 offset:7168
	global_load_lds_dwordx4 v[232:233], off
	v_lshl_add_u64 v[232:233], s[0:1], 0, v[178:179]
	s_add_i32 m0, s63, 0xe000
	s_nop 0
	global_load_lds_dwordx4 v[232:233], off
	s_waitcnt vmcnt(8)
	s_waitcnt lgkmcnt(0)
	s_barrier
	s_setprio 1
	s_waitcnt lgkmcnt(0)
	v_mfma_f32_16x16x32_bf16 v[144:147], v[20:23], v[190:193], 0
	v_mfma_f32_16x16x32_bf16 v[140:143], v[36:39], v[190:193], 0
	v_mfma_f32_16x16x32_bf16 v[128:131], v[20:23], v[208:211], 0
	v_mfma_f32_16x16x32_bf16 v[124:127], v[36:39], v[208:211], 0
	v_mfma_f32_16x16x32_bf16 v[112:115], v[20:23], v[216:219], 0
	v_mfma_f32_16x16x32_bf16 v[108:111], v[36:39], v[216:219], 0
	v_mfma_f32_16x16x32_bf16 v[96:99], v[20:23], v[224:227], 0
	v_mfma_f32_16x16x32_bf16 v[92:95], v[36:39], v[224:227], 0
	v_mfma_f32_16x16x32_bf16 v[144:147], v[24:27], v[204:207], v[144:147]
	v_mfma_f32_16x16x32_bf16 v[140:143], v[40:43], v[204:207], v[140:143]
	v_mfma_f32_16x16x32_bf16 v[128:131], v[24:27], v[212:215], v[128:131]
	v_mfma_f32_16x16x32_bf16 v[124:127], v[40:43], v[212:215], v[124:127]
	v_mfma_f32_16x16x32_bf16 v[112:115], v[24:27], v[220:223], v[112:115]
	v_mfma_f32_16x16x32_bf16 v[108:111], v[40:43], v[220:223], v[108:111]
	v_mfma_f32_16x16x32_bf16 v[96:99], v[24:27], v[228:231], v[96:99]
	v_mfma_f32_16x16x32_bf16 v[92:95], v[40:43], v[228:231], v[92:95]
	s_setprio 0
	s_setprio 1
	v_mfma_f32_16x16x32_bf16 v[136:139], v[148:151], v[190:193], 0
	v_mfma_f32_16x16x32_bf16 v[132:135], v[182:185], v[190:193], 0
	v_mfma_f32_16x16x32_bf16 v[120:123], v[148:151], v[208:211], 0
	v_mfma_f32_16x16x32_bf16 v[116:119], v[182:185], v[208:211], 0
	v_mfma_f32_16x16x32_bf16 v[104:107], v[148:151], v[216:219], 0
	v_mfma_f32_16x16x32_bf16 v[100:103], v[182:185], v[216:219], 0
	v_mfma_f32_16x16x32_bf16 v[88:91], v[148:151], v[224:227], 0
	v_mfma_f32_16x16x32_bf16 v[84:87], v[182:185], v[224:227], 0
	v_mfma_f32_16x16x32_bf16 v[136:139], v[152:155], v[204:207], v[136:139]
	v_mfma_f32_16x16x32_bf16 v[132:135], v[186:189], v[204:207], v[132:135]
	v_mfma_f32_16x16x32_bf16 v[120:123], v[152:155], v[212:215], v[120:123]
	v_mfma_f32_16x16x32_bf16 v[116:119], v[186:189], v[212:215], v[116:119]
	v_mfma_f32_16x16x32_bf16 v[104:107], v[152:155], v[220:223], v[104:107]
	v_mfma_f32_16x16x32_bf16 v[100:103], v[186:189], v[220:223], v[100:103]
	v_mfma_f32_16x16x32_bf16 v[88:91], v[152:155], v[228:231], v[88:91]
	v_mfma_f32_16x16x32_bf16 v[84:87], v[186:189], v[228:231], v[84:87]
	s_setprio 0
	s_barrier
	s_add_i32 s25, vcc_lo, s89
	v_lshl_add_u64 v[232:233], s[12:13], 0, v[174:175]
	s_mov_b32 m0, s25
	ds_read_b128 v[190:193], v202 offset:16384
	ds_read_b128 v[204:207], v202 offset:17408
	ds_read_b128 v[208:211], v202 offset:18432
	ds_read_b128 v[212:215], v202 offset:19456
	ds_read_b128 v[216:219], v202 offset:20480
	ds_read_b128 v[220:223], v202 offset:21504
	ds_read_b128 v[224:227], v202 offset:22528
	ds_read_b128 v[228:231], v202 offset:23552
	global_load_lds_dwordx4 v[232:233], off
	s_add_i32 m0, s25, 0x2000
	s_add_u32 vcc_lo, s12, 0x40000
	v_lshl_add_u64 v[234:235], s[12:13], 0, v[0:1]
	s_addc_u32 vcc_hi, s13, 0
	s_add_i32 s24, s24, s89
	global_load_lds_dwordx4 v[234:235], off
	v_lshl_add_u64 v[236:237], vcc, 0, v[174:175]
	s_mov_b32 m0, s24
	v_lshl_add_u64 v[238:239], s[14:15], 0, v[172:173]
	global_load_lds_dwordx4 v[236:237], off
	v_lshl_add_u64 v[236:237], vcc, 0, v[0:1]
	s_add_i32 m0, s24, 0x2000
	s_nop 0
	global_load_lds_dwordx4 v[236:237], off
	v_lshl_add_u64 v[236:237], s[14:15], 0, v[176:177]
	s_mov_b32 m0, s63
	s_nop 0
	global_load_lds_dwordx4 v[236:237], off
	s_mov_b32 m0, s87
	s_nop 0
	global_load_lds_dwordx4 v[238:239], off
	s_waitcnt vmcnt(8)
	s_waitcnt lgkmcnt(0)
	s_barrier
	s_setprio 1
	s_waitcnt lgkmcnt(0)
	v_mfma_f32_16x16x32_bf16 v[80:83], v[20:23], v[190:193], 0
	v_mfma_f32_16x16x32_bf16 v[76:79], v[36:39], v[190:193], 0
	v_mfma_f32_16x16x32_bf16 v[64:67], v[20:23], v[208:211], 0
	v_mfma_f32_16x16x32_bf16 v[60:63], v[36:39], v[208:211], 0
	v_mfma_f32_16x16x32_bf16 v[48:51], v[20:23], v[216:219], 0
	v_mfma_f32_16x16x32_bf16 v[44:47], v[36:39], v[216:219], 0
	v_mfma_f32_16x16x32_bf16 v[16:19], v[20:23], v[224:227], 0
	v_mfma_f32_16x16x32_bf16 v[12:15], v[36:39], v[224:227], 0
	v_mfma_f32_16x16x32_bf16 v[80:83], v[24:27], v[204:207], v[80:83]
	v_mfma_f32_16x16x32_bf16 v[76:79], v[40:43], v[204:207], v[76:79]
	v_mfma_f32_16x16x32_bf16 v[64:67], v[24:27], v[212:215], v[64:67]
	v_mfma_f32_16x16x32_bf16 v[60:63], v[40:43], v[212:215], v[60:63]
	v_mfma_f32_16x16x32_bf16 v[48:51], v[24:27], v[220:223], v[48:51]
	v_mfma_f32_16x16x32_bf16 v[44:47], v[40:43], v[220:223], v[44:47]
	v_mfma_f32_16x16x32_bf16 v[16:19], v[24:27], v[228:231], v[16:19]
	v_mfma_f32_16x16x32_bf16 v[12:15], v[40:43], v[228:231], v[12:15]
	s_setprio 0
	s_setprio 1
	v_mfma_f32_16x16x32_bf16 v[32:35], v[148:151], v[216:219], 0
	v_mfma_f32_16x16x32_bf16 v[28:31], v[182:185], v[216:219], 0
	v_mfma_f32_16x16x32_bf16 v[8:11], v[148:151], v[224:227], 0
	v_mfma_f32_16x16x32_bf16 v[4:7], v[182:185], v[224:227], 0
	v_mfma_f32_16x16x32_bf16 v[20:23], v[148:151], v[190:193], 0
	v_mfma_f32_16x16x32_bf16 v[24:27], v[182:185], v[190:193], 0
	v_mfma_f32_16x16x32_bf16 v[36:39], v[148:151], v[208:211], 0
	v_mfma_f32_16x16x32_bf16 v[40:43], v[182:185], v[208:211], 0
	v_mfma_f32_16x16x32_bf16 v[32:35], v[152:155], v[220:223], v[32:35]
	v_mfma_f32_16x16x32_bf16 v[28:31], v[186:189], v[220:223], v[28:31]
	v_mfma_f32_16x16x32_bf16 v[8:11], v[152:155], v[228:231], v[8:11]
	v_mfma_f32_16x16x32_bf16 v[4:7], v[186:189], v[228:231], v[4:7]
	v_mfma_f32_16x16x32_bf16 v[20:23], v[152:155], v[204:207], v[20:23]
	v_mfma_f32_16x16x32_bf16 v[24:27], v[186:189], v[204:207], v[24:27]
	v_mfma_f32_16x16x32_bf16 v[36:39], v[152:155], v[212:215], v[36:39]
	v_mfma_f32_16x16x32_bf16 v[40:43], v[186:189], v[212:215], v[40:43]
	s_setprio 0
	s_barrier
	s_add_i32 s24, 0, 0x18000
	v_add_u32_e32 v2, s24, v200
	s_add_i32 s25, 0, 0x1c000
	ds_read_b128 v[52:55], v2
	ds_read_b128 v[56:59], v2 offset:1024
	ds_read_b128 v[68:71], v2 offset:2048
	ds_read_b128 v[72:75], v2 offset:3072
	v_add_u32_e32 v2, s25, v200
	ds_read_b128 v[148:151], v2
	ds_read_b128 v[152:155], v2 offset:1024
	ds_read_b128 v[182:185], v2 offset:2048
	ds_read_b128 v[186:189], v2 offset:3072
	s_add_u32 s14, s14, 0x40000
	s_addc_u32 s15, s15, 0
	s_mov_b32 m0, s18
	v_lshl_add_u64 v[240:241], s[14:15], 0, v[176:177]
	ds_read_b128 v[190:193], v202 offset:32768
	ds_read_b128 v[204:207], v202 offset:33792
	ds_read_b128 v[208:211], v202 offset:34816
	ds_read_b128 v[212:215], v202 offset:35840
	ds_read_b128 v[216:219], v202 offset:36864
	ds_read_b128 v[220:223], v202 offset:37888
	ds_read_b128 v[224:227], v202 offset:38912
	ds_read_b128 v[228:231], v202 offset:39936
	global_load_lds_dwordx4 v[240:241], off
	v_lshl_add_u64 v[240:241], s[14:15], 0, v[172:173]
	s_mov_b32 m0, s19
	s_nop 0
	global_load_lds_dwordx4 v[240:241], off
	s_waitcnt vmcnt(8)
	s_waitcnt lgkmcnt(0)
	s_barrier
	s_setprio 1
	s_waitcnt lgkmcnt(0)
	v_mfma_f32_16x16x32_bf16 v[144:147], v[52:55], v[190:193], v[144:147]
	v_mfma_f32_16x16x32_bf16 v[140:143], v[68:71], v[190:193], v[140:143]
	v_mfma_f32_16x16x32_bf16 v[128:131], v[52:55], v[208:211], v[128:131]
	v_mfma_f32_16x16x32_bf16 v[124:127], v[68:71], v[208:211], v[124:127]
	v_mfma_f32_16x16x32_bf16 v[112:115], v[52:55], v[216:219], v[112:115]
	v_mfma_f32_16x16x32_bf16 v[108:111], v[68:71], v[216:219], v[108:111]
	v_mfma_f32_16x16x32_bf16 v[96:99], v[52:55], v[224:227], v[96:99]
	v_mfma_f32_16x16x32_bf16 v[92:95], v[68:71], v[224:227], v[92:95]
	v_mfma_f32_16x16x32_bf16 v[144:147], v[56:59], v[204:207], v[144:147]
	v_mfma_f32_16x16x32_bf16 v[140:143], v[72:75], v[204:207], v[140:143]
	v_mfma_f32_16x16x32_bf16 v[128:131], v[56:59], v[212:215], v[128:131]
	v_mfma_f32_16x16x32_bf16 v[124:127], v[72:75], v[212:215], v[124:127]
	v_mfma_f32_16x16x32_bf16 v[112:115], v[56:59], v[220:223], v[112:115]
	v_mfma_f32_16x16x32_bf16 v[108:111], v[72:75], v[220:223], v[108:111]
	v_mfma_f32_16x16x32_bf16 v[96:99], v[56:59], v[228:231], v[96:99]
	v_mfma_f32_16x16x32_bf16 v[92:95], v[72:75], v[228:231], v[92:95]
	s_setprio 0
	s_setprio 1
	v_mfma_f32_16x16x32_bf16 v[136:139], v[148:151], v[190:193], v[136:139]
	v_mfma_f32_16x16x32_bf16 v[132:135], v[182:185], v[190:193], v[132:135]
	v_mfma_f32_16x16x32_bf16 v[120:123], v[148:151], v[208:211], v[120:123]
	v_mfma_f32_16x16x32_bf16 v[116:119], v[182:185], v[208:211], v[116:119]
	v_mfma_f32_16x16x32_bf16 v[104:107], v[148:151], v[216:219], v[104:107]
	v_mfma_f32_16x16x32_bf16 v[100:103], v[182:185], v[216:219], v[100:103]
	v_mfma_f32_16x16x32_bf16 v[88:91], v[148:151], v[224:227], v[88:91]
	v_mfma_f32_16x16x32_bf16 v[84:87], v[182:185], v[224:227], v[84:87]
	v_mfma_f32_16x16x32_bf16 v[136:139], v[152:155], v[204:207], v[136:139]
	v_mfma_f32_16x16x32_bf16 v[132:135], v[186:189], v[204:207], v[132:135]
	v_mfma_f32_16x16x32_bf16 v[120:123], v[152:155], v[212:215], v[120:123]
	v_mfma_f32_16x16x32_bf16 v[116:119], v[186:189], v[212:215], v[116:119]
	v_mfma_f32_16x16x32_bf16 v[104:107], v[152:155], v[220:223], v[104:107]
	v_mfma_f32_16x16x32_bf16 v[100:103], v[186:189], v[220:223], v[100:103]
	v_mfma_f32_16x16x32_bf16 v[88:91], v[152:155], v[228:231], v[88:91]
	v_mfma_f32_16x16x32_bf16 v[84:87], v[186:189], v[228:231], v[84:87]
	s_setprio 0
	s_barrier
	s_add_i32 s14, s24, s89
	v_lshl_add_u64 v[232:233], v[232:233], 0, s[26:27]
	s_mov_b32 m0, s14
	ds_read_b128 v[190:193], v202 offset:49152
	ds_read_b128 v[204:207], v202 offset:50176
	ds_read_b128 v[208:211], v202 offset:51200
	ds_read_b128 v[212:215], v202 offset:52224
	ds_read_b128 v[216:219], v202 offset:53248
	ds_read_b128 v[220:223], v202 offset:54272
	ds_read_b128 v[224:227], v202 offset:55296
	ds_read_b128 v[228:231], v202 offset:56320
	global_load_lds_dwordx4 v[232:233], off
	s_add_i32 m0, s14, 0x2000
	s_add_u32 s12, s12, 0x40080
	v_lshl_add_u64 v[232:233], v[234:235], 0, s[26:27]
	s_addc_u32 s13, s13, 0
	s_add_i32 s14, s25, s89
	global_load_lds_dwordx4 v[232:233], off
	v_lshl_add_u64 v[232:233], s[12:13], 0, v[174:175]
	s_mov_b32 m0, s14
	s_nop 0
	global_load_lds_dwordx4 v[232:233], off
	v_lshl_add_u64 v[232:233], s[12:13], 0, v[0:1]
	s_add_i32 m0, s14, 0x2000
	s_nop 0
	global_load_lds_dwordx4 v[232:233], off
	v_lshl_add_u64 v[232:233], v[236:237], 0, s[26:27]
	s_mov_b32 m0, s20
	s_nop 0
	global_load_lds_dwordx4 v[232:233], off
	v_lshl_add_u64 v[232:233], v[238:239], 0, s[26:27]
	s_mov_b32 m0, s21
	s_nop 0
	global_load_lds_dwordx4 v[232:233], off
	s_waitcnt vmcnt(8)
	s_waitcnt lgkmcnt(0)
	s_barrier
	s_setprio 1
	s_waitcnt lgkmcnt(0)
	v_mfma_f32_16x16x32_bf16 v[80:83], v[52:55], v[190:193], v[80:83]
	v_mfma_f32_16x16x32_bf16 v[76:79], v[68:71], v[190:193], v[76:79]
	v_mfma_f32_16x16x32_bf16 v[64:67], v[52:55], v[208:211], v[64:67]
	v_mfma_f32_16x16x32_bf16 v[60:63], v[68:71], v[208:211], v[60:63]
	v_mfma_f32_16x16x32_bf16 v[48:51], v[52:55], v[216:219], v[48:51]
	v_mfma_f32_16x16x32_bf16 v[44:47], v[68:71], v[216:219], v[44:47]
	v_mfma_f32_16x16x32_bf16 v[16:19], v[52:55], v[224:227], v[16:19]
	v_mfma_f32_16x16x32_bf16 v[12:15], v[68:71], v[224:227], v[12:15]
	v_mfma_f32_16x16x32_bf16 v[80:83], v[56:59], v[204:207], v[80:83]
	v_mfma_f32_16x16x32_bf16 v[76:79], v[72:75], v[204:207], v[76:79]
	v_mfma_f32_16x16x32_bf16 v[64:67], v[56:59], v[212:215], v[64:67]
	v_mfma_f32_16x16x32_bf16 v[60:63], v[72:75], v[212:215], v[60:63]
	v_mfma_f32_16x16x32_bf16 v[48:51], v[56:59], v[220:223], v[48:51]
	v_mfma_f32_16x16x32_bf16 v[44:47], v[72:75], v[220:223], v[44:47]
	v_mfma_f32_16x16x32_bf16 v[16:19], v[56:59], v[228:231], v[16:19]
	v_mfma_f32_16x16x32_bf16 v[12:15], v[72:75], v[228:231], v[12:15]
	s_setprio 0
	s_setprio 1
	v_mfma_f32_16x16x32_bf16 v[20:23], v[148:151], v[190:193], v[20:23]
	v_mfma_f32_16x16x32_bf16 v[72:75], v[152:155], v[204:207], v[20:23]
	v_mfma_f32_16x16x32_bf16 v[20:23], v[182:185], v[190:193], v[24:27]
	v_mfma_f32_16x16x32_bf16 v[68:71], v[186:189], v[204:207], v[20:23]
	v_mfma_f32_16x16x32_bf16 v[20:23], v[148:151], v[208:211], v[36:39]
	v_mfma_f32_16x16x32_bf16 v[56:59], v[152:155], v[212:215], v[20:23]
	v_mfma_f32_16x16x32_bf16 v[20:23], v[182:185], v[208:211], v[40:43]
	v_mfma_f32_16x16x32_bf16 v[52:55], v[186:189], v[212:215], v[20:23]
	v_mfma_f32_16x16x32_bf16 v[20:23], v[148:151], v[216:219], v[32:35]
	v_mfma_f32_16x16x32_bf16 v[32:35], v[152:155], v[220:223], v[20:23]
	v_mfma_f32_16x16x32_bf16 v[20:23], v[182:185], v[216:219], v[28:31]
	v_mfma_f32_16x16x32_bf16 v[8:11], v[148:151], v[224:227], v[8:11]
	v_mfma_f32_16x16x32_bf16 v[4:7], v[182:185], v[224:227], v[4:7]
	v_mfma_f32_16x16x32_bf16 v[28:31], v[186:189], v[220:223], v[20:23]
	v_mfma_f32_16x16x32_bf16 v[8:11], v[152:155], v[228:231], v[8:11]
	v_mfma_f32_16x16x32_bf16 v[4:7], v[186:189], v[228:231], v[4:7]
	s_setprio 0
	s_barrier
	s_add_i32 s45, s45, 2
	s_add_u32 s43, s43, 0x100
	s_addc_u32 s44, s44, 0
	s_add_u32 s0, s0, 0x100
	s_addc_u32 s1, s1, 0
	s_cmp_gt_u32 s45, 13
	s_cbranch_scc0 .LBB0_198
	s_branch .Lpeel_exit_G1A

.Lpeel_exit_G1A:
	s_and_b64 vcc, exec, s[38:39]
	s_cbranch_vccz .LBB0_201
	s_barrier

.LBB0_492:
	s_ashr_i32 s29, s28, 31
	s_lshl_b64 s[38:39], s[28:29], 19
	s_add_u32 s38, s16, s38
	s_addc_u32 s39, s17, s39
	s_and_b64 s[40:41], s[0:1], exec
	s_cselect_b32 s29, s39, s15
	s_cselect_b32 s51, s38, s14
	s_ashr_i32 s13, s12, 31
	s_lshl_b64 s[40:41], s[12:13], 19
	s_add_u32 s40, s18, s40
	s_addc_u32 s41, s19, s41
	s_and_b64 s[46:47], s[0:1], exec
	s_cselect_b32 s13, s41, s45
	s_cselect_b32 s54, s40, s44
	s_add_u32 s55, s44, 0x100
	s_addc_u32 s60, s45, 0
	s_add_u32 s44, s14, 0x40080
	s_addc_u32 s45, s15, 0
	s_mov_b32 s61, -2
	s_add_u32 s14, s44, 0xfffc0080
	s_addc_u32 s15, s45, -1
	s_add_i32 s63, 0, 0x10000
	s_cmp_eq_u32 s61, 12
	s_cselect_b32 s47, s29, s15
	s_cselect_b32 s46, s51, s14
	s_cselect_b32 s15, s13, s60
	s_cselect_b32 s14, s54, s55
	s_add_i32 s76, 0, 0x14000
	v_add_u32_e32 v172, s63, v145
	v_add_u32_e32 v188, s76, v145
	ds_read_b128 v[140:143], v172
	ds_read_b128 v[148:151], v172 offset:1024
	ds_read_b128 v[152:155], v172 offset:2048
	ds_read_b128 v[172:175], v172 offset:3072
	ds_read_b128 v[176:179], v188
	ds_read_b128 v[180:183], v188 offset:1024
	ds_read_b128 v[184:187], v188 offset:2048
	ds_read_b128 v[188:191], v188 offset:3072
	v_lshl_add_u64 v[192:193], s[44:45], 0, v[138:139]
	s_add_i32 m0, s21, 0xc000
	ds_read_b128 v[200:203], v147
	ds_read_b128 v[204:207], v147 offset:1024
	ds_read_b128 v[208:211], v147 offset:2048
	ds_read_b128 v[212:215], v147 offset:3072
	ds_read_b128 v[216:219], v147 offset:4096
	ds_read_b128 v[220:223], v147 offset:5120
	ds_read_b128 v[224:227], v147 offset:6144
	ds_read_b128 v[228:231], v147 offset:7168
	global_load_lds_dwordx4 v[192:193], off
	v_lshl_add_u64 v[192:193], s[44:45], 0, v[136:137]
	s_add_i32 m0, s21, 0xe000
	s_nop 0
	global_load_lds_dwordx4 v[192:193], off
	s_waitcnt vmcnt(8)
	s_waitcnt lgkmcnt(0)
	s_barrier
	s_setprio 1
	s_waitcnt lgkmcnt(0)
	v_mfma_f32_16x16x32_bf16 v[128:131], v[140:143], v[200:203], 0
	v_mfma_f32_16x16x32_bf16 v[124:127], v[152:155], v[200:203], 0
	v_mfma_f32_16x16x32_bf16 v[112:115], v[140:143], v[208:211], 0
	v_mfma_f32_16x16x32_bf16 v[108:111], v[152:155], v[208:211], 0
	v_mfma_f32_16x16x32_bf16 v[96:99], v[140:143], v[216:219], 0
	v_mfma_f32_16x16x32_bf16 v[92:95], v[152:155], v[216:219], 0
	v_mfma_f32_16x16x32_bf16 v[80:83], v[140:143], v[224:227], 0
	v_mfma_f32_16x16x32_bf16 v[76:79], v[152:155], v[224:227], 0
	v_mfma_f32_16x16x32_bf16 v[128:131], v[148:151], v[204:207], v[128:131]
	v_mfma_f32_16x16x32_bf16 v[124:127], v[172:175], v[204:207], v[124:127]
	v_mfma_f32_16x16x32_bf16 v[112:115], v[148:151], v[212:215], v[112:115]
	v_mfma_f32_16x16x32_bf16 v[108:111], v[172:175], v[212:215], v[108:111]
	v_mfma_f32_16x16x32_bf16 v[96:99], v[148:151], v[220:223], v[96:99]
	v_mfma_f32_16x16x32_bf16 v[92:95], v[172:175], v[220:223], v[92:95]
	v_mfma_f32_16x16x32_bf16 v[80:83], v[148:151], v[228:231], v[80:83]
	v_mfma_f32_16x16x32_bf16 v[76:79], v[172:175], v[228:231], v[76:79]
	s_setprio 0
	s_setprio 1
	v_mfma_f32_16x16x32_bf16 v[120:123], v[176:179], v[200:203], 0
	v_mfma_f32_16x16x32_bf16 v[116:119], v[184:187], v[200:203], 0
	v_mfma_f32_16x16x32_bf16 v[104:107], v[176:179], v[208:211], 0
	v_mfma_f32_16x16x32_bf16 v[100:103], v[184:187], v[208:211], 0
	v_mfma_f32_16x16x32_bf16 v[88:91], v[176:179], v[216:219], 0
	v_mfma_f32_16x16x32_bf16 v[84:87], v[184:187], v[216:219], 0
	v_mfma_f32_16x16x32_bf16 v[72:75], v[176:179], v[224:227], 0
	v_mfma_f32_16x16x32_bf16 v[68:71], v[184:187], v[224:227], 0
	v_mfma_f32_16x16x32_bf16 v[120:123], v[180:183], v[204:207], v[120:123]
	v_mfma_f32_16x16x32_bf16 v[116:119], v[188:191], v[204:207], v[116:119]
	v_mfma_f32_16x16x32_bf16 v[104:107], v[180:183], v[212:215], v[104:107]
	v_mfma_f32_16x16x32_bf16 v[100:103], v[188:191], v[212:215], v[100:103]
	v_mfma_f32_16x16x32_bf16 v[88:91], v[180:183], v[220:223], v[88:91]
	v_mfma_f32_16x16x32_bf16 v[84:87], v[188:191], v[220:223], v[84:87]
	v_mfma_f32_16x16x32_bf16 v[72:75], v[180:183], v[228:231], v[72:75]
	v_mfma_f32_16x16x32_bf16 v[68:71], v[188:191], v[228:231], v[68:71]
	s_setprio 0
	s_barrier
	s_add_i32 s63, s63, s20
	v_lshl_add_u64 v[192:193], s[14:15], 0, v[2:3]
	s_mov_b32 m0, s63
	ds_read_b128 v[200:203], v147 offset:16384
	ds_read_b128 v[204:207], v147 offset:17408
	ds_read_b128 v[208:211], v147 offset:18432
	ds_read_b128 v[212:215], v147 offset:19456
	ds_read_b128 v[216:219], v147 offset:20480
	ds_read_b128 v[220:223], v147 offset:21504
	ds_read_b128 v[224:227], v147 offset:22528
	ds_read_b128 v[228:231], v147 offset:23552
	global_load_lds_dwordx4 v[192:193], off
	s_add_i32 m0, s63, 0x2000
	s_add_u32 s64, s14, 0x40000
	v_lshl_add_u64 v[232:233], s[14:15], 0, v[134:135]
	s_addc_u32 s65, s15, 0
	s_add_i32 s63, s76, s20
	global_load_lds_dwordx4 v[232:233], off
	v_lshl_add_u64 v[234:235], s[64:65], 0, v[2:3]
	s_mov_b32 m0, s63
	v_lshl_add_u64 v[236:237], s[46:47], 0, v[132:133]
	global_load_lds_dwordx4 v[234:235], off
	v_lshl_add_u64 v[234:235], s[64:65], 0, v[134:135]
	s_add_i32 m0, s63, 0x2000
	s_nop 0
	global_load_lds_dwordx4 v[234:235], off
	v_lshl_add_u64 v[234:235], s[46:47], 0, v[0:1]
	s_mov_b32 m0, s21
	s_nop 0
	global_load_lds_dwordx4 v[234:235], off
	s_mov_b32 m0, s22
	s_nop 0
	global_load_lds_dwordx4 v[236:237], off
	s_waitcnt vmcnt(8)
	s_waitcnt lgkmcnt(0)
	s_barrier
	s_setprio 1
	s_waitcnt lgkmcnt(0)
	v_mfma_f32_16x16x32_bf16 v[64:67], v[140:143], v[200:203], 0
	v_mfma_f32_16x16x32_bf16 v[60:63], v[152:155], v[200:203], 0
	v_mfma_f32_16x16x32_bf16 v[48:51], v[140:143], v[208:211], 0
	v_mfma_f32_16x16x32_bf16 v[44:47], v[152:155], v[208:211], 0
	v_mfma_f32_16x16x32_bf16 v[32:35], v[140:143], v[216:219], 0
	v_mfma_f32_16x16x32_bf16 v[28:31], v[152:155], v[216:219], 0
	v_mfma_f32_16x16x32_bf16 v[16:19], v[140:143], v[224:227], 0
	v_mfma_f32_16x16x32_bf16 v[12:15], v[152:155], v[224:227], 0
	v_mfma_f32_16x16x32_bf16 v[64:67], v[148:151], v[204:207], v[64:67]
	v_mfma_f32_16x16x32_bf16 v[60:63], v[172:175], v[204:207], v[60:63]
	v_mfma_f32_16x16x32_bf16 v[48:51], v[148:151], v[212:215], v[48:51]
	v_mfma_f32_16x16x32_bf16 v[44:47], v[172:175], v[212:215], v[44:47]
	v_mfma_f32_16x16x32_bf16 v[32:35], v[148:151], v[220:223], v[32:35]
	v_mfma_f32_16x16x32_bf16 v[28:31], v[172:175], v[220:223], v[28:31]
	v_mfma_f32_16x16x32_bf16 v[16:19], v[148:151], v[228:231], v[16:19]
	v_mfma_f32_16x16x32_bf16 v[12:15], v[172:175], v[228:231], v[12:15]
	s_setprio 0
	s_setprio 1
	v_mfma_f32_16x16x32_bf16 v[56:59], v[176:179], v[200:203], 0
	v_mfma_f32_16x16x32_bf16 v[52:55], v[184:187], v[200:203], 0
	v_mfma_f32_16x16x32_bf16 v[40:43], v[176:179], v[208:211], 0
	v_mfma_f32_16x16x32_bf16 v[36:39], v[184:187], v[208:211], 0
	v_mfma_f32_16x16x32_bf16 v[24:27], v[176:179], v[216:219], 0
	v_mfma_f32_16x16x32_bf16 v[20:23], v[184:187], v[216:219], 0
	v_mfma_f32_16x16x32_bf16 v[8:11], v[176:179], v[224:227], 0
	v_mfma_f32_16x16x32_bf16 v[4:7], v[184:187], v[224:227], 0
	v_mfma_f32_16x16x32_bf16 v[56:59], v[180:183], v[204:207], v[56:59]
	v_mfma_f32_16x16x32_bf16 v[52:55], v[188:191], v[204:207], v[52:55]
	v_mfma_f32_16x16x32_bf16 v[40:43], v[180:183], v[212:215], v[40:43]
	v_mfma_f32_16x16x32_bf16 v[36:39], v[188:191], v[212:215], v[36:39]
	v_mfma_f32_16x16x32_bf16 v[24:27], v[180:183], v[220:223], v[24:27]
	v_mfma_f32_16x16x32_bf16 v[20:23], v[188:191], v[220:223], v[20:23]
	v_mfma_f32_16x16x32_bf16 v[8:11], v[180:183], v[228:231], v[8:11]
	v_mfma_f32_16x16x32_bf16 v[4:7], v[188:191], v[228:231], v[4:7]
	s_setprio 0
	s_barrier
	s_add_i32 s63, 0, 0x18000
	s_add_i32 s64, 0, 0x1c000
	v_add_u32_e32 v172, s63, v145
	v_add_u32_e32 v188, s64, v145
	ds_read_b128 v[140:143], v172
	ds_read_b128 v[148:151], v172 offset:1024
	ds_read_b128 v[152:155], v172 offset:2048
	ds_read_b128 v[172:175], v172 offset:3072
	ds_read_b128 v[176:179], v188
	ds_read_b128 v[180:183], v188 offset:1024
	ds_read_b128 v[184:187], v188 offset:2048
	ds_read_b128 v[188:191], v188 offset:3072
	s_add_u32 s46, s46, 0x40000
	s_addc_u32 s47, s47, 0
	s_mov_b32 m0, s23
	v_lshl_add_u64 v[238:239], s[46:47], 0, v[0:1]
	ds_read_b128 v[200:203], v147 offset:32768
	ds_read_b128 v[204:207], v147 offset:33792
	ds_read_b128 v[208:211], v147 offset:34816
	ds_read_b128 v[212:215], v147 offset:35840
	ds_read_b128 v[216:219], v147 offset:36864
	ds_read_b128 v[220:223], v147 offset:37888
	ds_read_b128 v[224:227], v147 offset:38912
	ds_read_b128 v[228:231], v147 offset:39936
	global_load_lds_dwordx4 v[238:239], off
	v_lshl_add_u64 v[238:239], s[46:47], 0, v[132:133]
	s_mov_b32 m0, s36
	s_nop 0
	global_load_lds_dwordx4 v[238:239], off
	s_waitcnt vmcnt(8)
	s_waitcnt lgkmcnt(0)
	s_barrier
	s_setprio 1
	s_waitcnt lgkmcnt(0)
	v_mfma_f32_16x16x32_bf16 v[128:131], v[140:143], v[200:203], v[128:131]
	v_mfma_f32_16x16x32_bf16 v[124:127], v[152:155], v[200:203], v[124:127]
	v_mfma_f32_16x16x32_bf16 v[112:115], v[140:143], v[208:211], v[112:115]
	v_mfma_f32_16x16x32_bf16 v[108:111], v[152:155], v[208:211], v[108:111]
	v_mfma_f32_16x16x32_bf16 v[96:99], v[140:143], v[216:219], v[96:99]
	v_mfma_f32_16x16x32_bf16 v[92:95], v[152:155], v[216:219], v[92:95]
	v_mfma_f32_16x16x32_bf16 v[80:83], v[140:143], v[224:227], v[80:83]
	v_mfma_f32_16x16x32_bf16 v[76:79], v[152:155], v[224:227], v[76:79]
	v_mfma_f32_16x16x32_bf16 v[128:131], v[148:151], v[204:207], v[128:131]
	v_mfma_f32_16x16x32_bf16 v[124:127], v[172:175], v[204:207], v[124:127]
	v_mfma_f32_16x16x32_bf16 v[112:115], v[148:151], v[212:215], v[112:115]
	v_mfma_f32_16x16x32_bf16 v[108:111], v[172:175], v[212:215], v[108:111]
	v_mfma_f32_16x16x32_bf16 v[96:99], v[148:151], v[220:223], v[96:99]
	v_mfma_f32_16x16x32_bf16 v[92:95], v[172:175], v[220:223], v[92:95]
	v_mfma_f32_16x16x32_bf16 v[80:83], v[148:151], v[228:231], v[80:83]
	v_mfma_f32_16x16x32_bf16 v[76:79], v[172:175], v[228:231], v[76:79]
	s_setprio 0
	s_setprio 1
	v_mfma_f32_16x16x32_bf16 v[120:123], v[176:179], v[200:203], v[120:123]
	v_mfma_f32_16x16x32_bf16 v[116:119], v[184:187], v[200:203], v[116:119]
	v_mfma_f32_16x16x32_bf16 v[104:107], v[176:179], v[208:211], v[104:107]
	v_mfma_f32_16x16x32_bf16 v[100:103], v[184:187], v[208:211], v[100:103]
	v_mfma_f32_16x16x32_bf16 v[88:91], v[176:179], v[216:219], v[88:91]
	v_mfma_f32_16x16x32_bf16 v[84:87], v[184:187], v[216:219], v[84:87]
	v_mfma_f32_16x16x32_bf16 v[72:75], v[176:179], v[224:227], v[72:75]
	v_mfma_f32_16x16x32_bf16 v[68:71], v[184:187], v[224:227], v[68:71]
	v_mfma_f32_16x16x32_bf16 v[120:123], v[180:183], v[204:207], v[120:123]
	v_mfma_f32_16x16x32_bf16 v[116:119], v[188:191], v[204:207], v[116:119]
	v_mfma_f32_16x16x32_bf16 v[104:107], v[180:183], v[212:215], v[104:107]
	v_mfma_f32_16x16x32_bf16 v[100:103], v[188:191], v[212:215], v[100:103]
	v_mfma_f32_16x16x32_bf16 v[88:91], v[180:183], v[220:223], v[88:91]
	v_mfma_f32_16x16x32_bf16 v[84:87], v[188:191], v[220:223], v[84:87]
	v_mfma_f32_16x16x32_bf16 v[72:75], v[180:183], v[228:231], v[72:75]
	v_mfma_f32_16x16x32_bf16 v[68:71], v[188:191], v[228:231], v[68:71]
	s_setprio 0
	s_barrier
	s_add_i32 s46, s63, s20
	v_lshl_add_u64 v[192:193], v[192:193], 0, s[26:27]
	s_mov_b32 m0, s46
	ds_read_b128 v[200:203], v147 offset:49152
	ds_read_b128 v[204:207], v147 offset:50176
	ds_read_b128 v[208:211], v147 offset:51200
	ds_read_b128 v[212:215], v147 offset:52224
	ds_read_b128 v[216:219], v147 offset:53248
	ds_read_b128 v[220:223], v147 offset:54272
	ds_read_b128 v[224:227], v147 offset:55296
	ds_read_b128 v[228:231], v147 offset:56320
	global_load_lds_dwordx4 v[192:193], off
	s_add_i32 m0, s46, 0x2000
	s_add_u32 s14, s14, 0x40080
	v_lshl_add_u64 v[192:193], v[232:233], 0, s[26:27]
	s_addc_u32 s15, s15, 0
	s_add_i32 s46, s64, s20
	global_load_lds_dwordx4 v[192:193], off
	v_lshl_add_u64 v[192:193], s[14:15], 0, v[2:3]
	s_mov_b32 m0, s46
	s_nop 0
	global_load_lds_dwordx4 v[192:193], off
	v_lshl_add_u64 v[192:193], s[14:15], 0, v[134:135]
	s_add_i32 m0, s46, 0x2000
	s_nop 0
	global_load_lds_dwordx4 v[192:193], off
	v_lshl_add_u64 v[192:193], v[234:235], 0, s[26:27]
	s_mov_b32 m0, s43
	s_nop 0
	global_load_lds_dwordx4 v[192:193], off
	v_lshl_add_u64 v[192:193], v[236:237], 0, s[26:27]
	s_mov_b32 m0, s48
	s_nop 0
	global_load_lds_dwordx4 v[192:193], off
	s_waitcnt vmcnt(8)
	s_waitcnt lgkmcnt(0)
	s_barrier
	s_setprio 1
	s_waitcnt lgkmcnt(0)
	v_mfma_f32_16x16x32_bf16 v[64:67], v[140:143], v[200:203], v[64:67]
	v_mfma_f32_16x16x32_bf16 v[60:63], v[152:155], v[200:203], v[60:63]
	v_mfma_f32_16x16x32_bf16 v[48:51], v[140:143], v[208:211], v[48:51]
	v_mfma_f32_16x16x32_bf16 v[44:47], v[152:155], v[208:211], v[44:47]
	v_mfma_f32_16x16x32_bf16 v[32:35], v[140:143], v[216:219], v[32:35]
	v_mfma_f32_16x16x32_bf16 v[28:31], v[152:155], v[216:219], v[28:31]
	v_mfma_f32_16x16x32_bf16 v[16:19], v[140:143], v[224:227], v[16:19]
	v_mfma_f32_16x16x32_bf16 v[12:15], v[152:155], v[224:227], v[12:15]
	v_mfma_f32_16x16x32_bf16 v[64:67], v[148:151], v[204:207], v[64:67]
	v_mfma_f32_16x16x32_bf16 v[60:63], v[172:175], v[204:207], v[60:63]
	v_mfma_f32_16x16x32_bf16 v[48:51], v[148:151], v[212:215], v[48:51]
	v_mfma_f32_16x16x32_bf16 v[44:47], v[172:175], v[212:215], v[44:47]
	v_mfma_f32_16x16x32_bf16 v[32:35], v[148:151], v[220:223], v[32:35]
	v_mfma_f32_16x16x32_bf16 v[28:31], v[172:175], v[220:223], v[28:31]
	v_mfma_f32_16x16x32_bf16 v[16:19], v[148:151], v[228:231], v[16:19]
	v_mfma_f32_16x16x32_bf16 v[12:15], v[172:175], v[228:231], v[12:15]
	s_setprio 0
	s_setprio 1
	v_mfma_f32_16x16x32_bf16 v[56:59], v[176:179], v[200:203], v[56:59]
	v_mfma_f32_16x16x32_bf16 v[52:55], v[184:187], v[200:203], v[52:55]
	v_mfma_f32_16x16x32_bf16 v[40:43], v[176:179], v[208:211], v[40:43]
	v_mfma_f32_16x16x32_bf16 v[36:39], v[184:187], v[208:211], v[36:39]
	v_mfma_f32_16x16x32_bf16 v[24:27], v[176:179], v[216:219], v[24:27]
	v_mfma_f32_16x16x32_bf16 v[20:23], v[184:187], v[216:219], v[20:23]
	v_mfma_f32_16x16x32_bf16 v[8:11], v[176:179], v[224:227], v[8:11]
	v_mfma_f32_16x16x32_bf16 v[4:7], v[184:187], v[224:227], v[4:7]
	v_mfma_f32_16x16x32_bf16 v[56:59], v[180:183], v[204:207], v[56:59]
	v_mfma_f32_16x16x32_bf16 v[52:55], v[188:191], v[204:207], v[52:55]
	v_mfma_f32_16x16x32_bf16 v[40:43], v[180:183], v[212:215], v[40:43]
	v_mfma_f32_16x16x32_bf16 v[36:39], v[188:191], v[212:215], v[36:39]
	v_mfma_f32_16x16x32_bf16 v[24:27], v[180:183], v[220:223], v[24:27]
	v_mfma_f32_16x16x32_bf16 v[20:23], v[188:191], v[220:223], v[20:23]
	v_mfma_f32_16x16x32_bf16 v[8:11], v[180:183], v[228:231], v[8:11]
	v_mfma_f32_16x16x32_bf16 v[4:7], v[188:191], v[228:231], v[4:7]
	s_setprio 0
	s_barrier
	s_add_i32 s61, s61, 2
	s_add_u32 s55, s55, 0x100
	s_addc_u32 s60, s60, 0
	s_add_u32 s44, s44, 0x100
	s_addc_u32 s45, s45, 0
	s_cmp_gt_u32 s61, 13
	s_cbranch_scc0 .LBB0_493
	s_branch .Lpeel_exit_KV
.LBB0_493:
	s_add_u32 s14, s44, 0xfffc0080
	s_addc_u32 s15, s45, -1
	s_add_i32 s63, 0, 0x10000
	s_cmp_eq_u32 s61, 12
	s_cselect_b32 s47, s29, s15
	s_cselect_b32 s46, s51, s14
	s_cselect_b32 s15, s13, s60
	s_cselect_b32 s14, s54, s55
	s_add_i32 s76, 0, 0x14000
	v_add_u32_e32 v172, s63, v145
	v_add_u32_e32 v188, s76, v145
	ds_read_b128 v[140:143], v172
	ds_read_b128 v[148:151], v172 offset:1024
	ds_read_b128 v[152:155], v172 offset:2048
	ds_read_b128 v[172:175], v172 offset:3072
	ds_read_b128 v[176:179], v188
	ds_read_b128 v[180:183], v188 offset:1024
	ds_read_b128 v[184:187], v188 offset:2048
	ds_read_b128 v[188:191], v188 offset:3072
	v_lshl_add_u64 v[192:193], s[44:45], 0, v[138:139]
	s_add_i32 m0, s21, 0xc000
	ds_read_b128 v[200:203], v147
	ds_read_b128 v[204:207], v147 offset:1024
	ds_read_b128 v[208:211], v147 offset:2048
	ds_read_b128 v[212:215], v147 offset:3072
	ds_read_b128 v[216:219], v147 offset:4096
	ds_read_b128 v[220:223], v147 offset:5120
	ds_read_b128 v[224:227], v147 offset:6144
	ds_read_b128 v[228:231], v147 offset:7168
	global_load_lds_dwordx4 v[192:193], off
	v_lshl_add_u64 v[192:193], s[44:45], 0, v[136:137]
	s_add_i32 m0, s21, 0xe000
	s_nop 0
	global_load_lds_dwordx4 v[192:193], off
	s_waitcnt vmcnt(8)
	s_waitcnt lgkmcnt(0)
	s_barrier
	s_setprio 1
	s_waitcnt lgkmcnt(0)
	v_mfma_f32_16x16x32_bf16 v[128:131], v[140:143], v[200:203], v[128:131]
	v_mfma_f32_16x16x32_bf16 v[124:127], v[152:155], v[200:203], v[124:127]
	v_mfma_f32_16x16x32_bf16 v[112:115], v[140:143], v[208:211], v[112:115]
	v_mfma_f32_16x16x32_bf16 v[108:111], v[152:155], v[208:211], v[108:111]
	v_mfma_f32_16x16x32_bf16 v[96:99], v[140:143], v[216:219], v[96:99]
	v_mfma_f32_16x16x32_bf16 v[92:95], v[152:155], v[216:219], v[92:95]
	v_mfma_f32_16x16x32_bf16 v[80:83], v[140:143], v[224:227], v[80:83]
	v_mfma_f32_16x16x32_bf16 v[76:79], v[152:155], v[224:227], v[76:79]
	v_mfma_f32_16x16x32_bf16 v[128:131], v[148:151], v[204:207], v[128:131]
	v_mfma_f32_16x16x32_bf16 v[124:127], v[172:175], v[204:207], v[124:127]
	v_mfma_f32_16x16x32_bf16 v[112:115], v[148:151], v[212:215], v[112:115]
	v_mfma_f32_16x16x32_bf16 v[108:111], v[172:175], v[212:215], v[108:111]
	v_mfma_f32_16x16x32_bf16 v[96:99], v[148:151], v[220:223], v[96:99]
	v_mfma_f32_16x16x32_bf16 v[92:95], v[172:175], v[220:223], v[92:95]
	v_mfma_f32_16x16x32_bf16 v[80:83], v[148:151], v[228:231], v[80:83]
	v_mfma_f32_16x16x32_bf16 v[76:79], v[172:175], v[228:231], v[76:79]
	s_setprio 0
	s_setprio 1
	v_mfma_f32_16x16x32_bf16 v[120:123], v[176:179], v[200:203], v[120:123]
	v_mfma_f32_16x16x32_bf16 v[116:119], v[184:187], v[200:203], v[116:119]
	v_mfma_f32_16x16x32_bf16 v[104:107], v[176:179], v[208:211], v[104:107]
	v_mfma_f32_16x16x32_bf16 v[100:103], v[184:187], v[208:211], v[100:103]
	v_mfma_f32_16x16x32_bf16 v[88:91], v[176:179], v[216:219], v[88:91]
	v_mfma_f32_16x16x32_bf16 v[84:87], v[184:187], v[216:219], v[84:87]
	v_mfma_f32_16x16x32_bf16 v[72:75], v[176:179], v[224:227], v[72:75]
	v_mfma_f32_16x16x32_bf16 v[68:71], v[184:187], v[224:227], v[68:71]
	v_mfma_f32_16x16x32_bf16 v[120:123], v[180:183], v[204:207], v[120:123]
	v_mfma_f32_16x16x32_bf16 v[116:119], v[188:191], v[204:207], v[116:119]
	v_mfma_f32_16x16x32_bf16 v[104:107], v[180:183], v[212:215], v[104:107]
	v_mfma_f32_16x16x32_bf16 v[100:103], v[188:191], v[212:215], v[100:103]
	v_mfma_f32_16x16x32_bf16 v[88:91], v[180:183], v[220:223], v[88:91]
	v_mfma_f32_16x16x32_bf16 v[84:87], v[188:191], v[220:223], v[84:87]
	v_mfma_f32_16x16x32_bf16 v[72:75], v[180:183], v[228:231], v[72:75]
	v_mfma_f32_16x16x32_bf16 v[68:71], v[188:191], v[228:231], v[68:71]
	s_setprio 0
	s_barrier
	s_add_i32 s63, s63, s20
	v_lshl_add_u64 v[192:193], s[14:15], 0, v[2:3]
	s_mov_b32 m0, s63
	ds_read_b128 v[200:203], v147 offset:16384
	ds_read_b128 v[204:207], v147 offset:17408
	ds_read_b128 v[208:211], v147 offset:18432
	ds_read_b128 v[212:215], v147 offset:19456
	ds_read_b128 v[216:219], v147 offset:20480
	ds_read_b128 v[220:223], v147 offset:21504
	ds_read_b128 v[224:227], v147 offset:22528
	ds_read_b128 v[228:231], v147 offset:23552
	global_load_lds_dwordx4 v[192:193], off
	s_add_i32 m0, s63, 0x2000
	s_add_u32 s64, s14, 0x40000
	v_lshl_add_u64 v[232:233], s[14:15], 0, v[134:135]
	s_addc_u32 s65, s15, 0
	s_add_i32 s63, s76, s20
	global_load_lds_dwordx4 v[232:233], off
	v_lshl_add_u64 v[234:235], s[64:65], 0, v[2:3]
	s_mov_b32 m0, s63
	v_lshl_add_u64 v[236:237], s[46:47], 0, v[132:133]
	global_load_lds_dwordx4 v[234:235], off
	v_lshl_add_u64 v[234:235], s[64:65], 0, v[134:135]
	s_add_i32 m0, s63, 0x2000
	s_nop 0
	global_load_lds_dwordx4 v[234:235], off
	v_lshl_add_u64 v[234:235], s[46:47], 0, v[0:1]
	s_mov_b32 m0, s21
	s_nop 0
	global_load_lds_dwordx4 v[234:235], off
	s_mov_b32 m0, s22
	s_nop 0
	global_load_lds_dwordx4 v[236:237], off
	s_waitcnt vmcnt(8)
	s_waitcnt lgkmcnt(0)
	s_barrier
	s_setprio 1
	s_waitcnt lgkmcnt(0)
	v_mfma_f32_16x16x32_bf16 v[64:67], v[140:143], v[200:203], v[64:67]
	v_mfma_f32_16x16x32_bf16 v[60:63], v[152:155], v[200:203], v[60:63]
	v_mfma_f32_16x16x32_bf16 v[48:51], v[140:143], v[208:211], v[48:51]
	v_mfma_f32_16x16x32_bf16 v[44:47], v[152:155], v[208:211], v[44:47]
	v_mfma_f32_16x16x32_bf16 v[32:35], v[140:143], v[216:219], v[32:35]
	v_mfma_f32_16x16x32_bf16 v[28:31], v[152:155], v[216:219], v[28:31]
	v_mfma_f32_16x16x32_bf16 v[16:19], v[140:143], v[224:227], v[16:19]
	v_mfma_f32_16x16x32_bf16 v[12:15], v[152:155], v[224:227], v[12:15]
	v_mfma_f32_16x16x32_bf16 v[64:67], v[148:151], v[204:207], v[64:67]
	v_mfma_f32_16x16x32_bf16 v[60:63], v[172:175], v[204:207], v[60:63]
	v_mfma_f32_16x16x32_bf16 v[48:51], v[148:151], v[212:215], v[48:51]
	v_mfma_f32_16x16x32_bf16 v[44:47], v[172:175], v[212:215], v[44:47]
	v_mfma_f32_16x16x32_bf16 v[32:35], v[148:151], v[220:223], v[32:35]
	v_mfma_f32_16x16x32_bf16 v[28:31], v[172:175], v[220:223], v[28:31]
	v_mfma_f32_16x16x32_bf16 v[16:19], v[148:151], v[228:231], v[16:19]
	v_mfma_f32_16x16x32_bf16 v[12:15], v[172:175], v[228:231], v[12:15]
	s_setprio 0
	s_setprio 1
	v_mfma_f32_16x16x32_bf16 v[56:59], v[176:179], v[200:203], v[56:59]
	v_mfma_f32_16x16x32_bf16 v[52:55], v[184:187], v[200:203], v[52:55]
	v_mfma_f32_16x16x32_bf16 v[40:43], v[176:179], v[208:211], v[40:43]
	v_mfma_f32_16x16x32_bf16 v[36:39], v[184:187], v[208:211], v[36:39]
	v_mfma_f32_16x16x32_bf16 v[24:27], v[176:179], v[216:219], v[24:27]
	v_mfma_f32_16x16x32_bf16 v[20:23], v[184:187], v[216:219], v[20:23]
	v_mfma_f32_16x16x32_bf16 v[8:11], v[176:179], v[224:227], v[8:11]
	v_mfma_f32_16x16x32_bf16 v[4:7], v[184:187], v[224:227], v[4:7]
	v_mfma_f32_16x16x32_bf16 v[56:59], v[180:183], v[204:207], v[56:59]
	v_mfma_f32_16x16x32_bf16 v[52:55], v[188:191], v[204:207], v[52:55]
	v_mfma_f32_16x16x32_bf16 v[40:43], v[180:183], v[212:215], v[40:43]
	v_mfma_f32_16x16x32_bf16 v[36:39], v[188:191], v[212:215], v[36:39]
	v_mfma_f32_16x16x32_bf16 v[24:27], v[180:183], v[220:223], v[24:27]
	v_mfma_f32_16x16x32_bf16 v[20:23], v[188:191], v[220:223], v[20:23]
	v_mfma_f32_16x16x32_bf16 v[8:11], v[180:183], v[228:231], v[8:11]
	v_mfma_f32_16x16x32_bf16 v[4:7], v[188:191], v[228:231], v[4:7]
	s_setprio 0
	s_barrier
	s_add_i32 s63, 0, 0x18000
	s_add_i32 s64, 0, 0x1c000
	v_add_u32_e32 v172, s63, v145
	v_add_u32_e32 v188, s64, v145
	ds_read_b128 v[140:143], v172
	ds_read_b128 v[148:151], v172 offset:1024
	ds_read_b128 v[152:155], v172 offset:2048
	ds_read_b128 v[172:175], v172 offset:3072
	ds_read_b128 v[176:179], v188
	ds_read_b128 v[180:183], v188 offset:1024
	ds_read_b128 v[184:187], v188 offset:2048
	ds_read_b128 v[188:191], v188 offset:3072
	s_add_u32 s46, s46, 0x40000
	s_addc_u32 s47, s47, 0
	s_mov_b32 m0, s23
	v_lshl_add_u64 v[238:239], s[46:47], 0, v[0:1]
	ds_read_b128 v[200:203], v147 offset:32768
	ds_read_b128 v[204:207], v147 offset:33792
	ds_read_b128 v[208:211], v147 offset:34816
	ds_read_b128 v[212:215], v147 offset:35840
	ds_read_b128 v[216:219], v147 offset:36864
	ds_read_b128 v[220:223], v147 offset:37888
	ds_read_b128 v[224:227], v147 offset:38912
	ds_read_b128 v[228:231], v147 offset:39936
	global_load_lds_dwordx4 v[238:239], off
	v_lshl_add_u64 v[238:239], s[46:47], 0, v[132:133]
	s_mov_b32 m0, s36
	s_nop 0
	global_load_lds_dwordx4 v[238:239], off
	s_waitcnt vmcnt(8)
	s_waitcnt lgkmcnt(0)
	s_barrier
	s_setprio 1
	s_waitcnt lgkmcnt(0)
	v_mfma_f32_16x16x32_bf16 v[128:131], v[140:143], v[200:203], v[128:131]
	v_mfma_f32_16x16x32_bf16 v[124:127], v[152:155], v[200:203], v[124:127]
	v_mfma_f32_16x16x32_bf16 v[112:115], v[140:143], v[208:211], v[112:115]
	v_mfma_f32_16x16x32_bf16 v[108:111], v[152:155], v[208:211], v[108:111]
	v_mfma_f32_16x16x32_bf16 v[96:99], v[140:143], v[216:219], v[96:99]
	v_mfma_f32_16x16x32_bf16 v[92:95], v[152:155], v[216:219], v[92:95]
	v_mfma_f32_16x16x32_bf16 v[80:83], v[140:143], v[224:227], v[80:83]
	v_mfma_f32_16x16x32_bf16 v[76:79], v[152:155], v[224:227], v[76:79]
	v_mfma_f32_16x16x32_bf16 v[128:131], v[148:151], v[204:207], v[128:131]
	v_mfma_f32_16x16x32_bf16 v[124:127], v[172:175], v[204:207], v[124:127]
	v_mfma_f32_16x16x32_bf16 v[112:115], v[148:151], v[212:215], v[112:115]
	v_mfma_f32_16x16x32_bf16 v[108:111], v[172:175], v[212:215], v[108:111]
	v_mfma_f32_16x16x32_bf16 v[96:99], v[148:151], v[220:223], v[96:99]
	v_mfma_f32_16x16x32_bf16 v[92:95], v[172:175], v[220:223], v[92:95]
	v_mfma_f32_16x16x32_bf16 v[80:83], v[148:151], v[228:231], v[80:83]
	v_mfma_f32_16x16x32_bf16 v[76:79], v[172:175], v[228:231], v[76:79]
	s_setprio 0
	s_setprio 1
	v_mfma_f32_16x16x32_bf16 v[120:123], v[176:179], v[200:203], v[120:123]
	v_mfma_f32_16x16x32_bf16 v[116:119], v[184:187], v[200:203], v[116:119]
	v_mfma_f32_16x16x32_bf16 v[104:107], v[176:179], v[208:211], v[104:107]
	v_mfma_f32_16x16x32_bf16 v[100:103], v[184:187], v[208:211], v[100:103]
	v_mfma_f32_16x16x32_bf16 v[88:91], v[176:179], v[216:219], v[88:91]
	v_mfma_f32_16x16x32_bf16 v[84:87], v[184:187], v[216:219], v[84:87]
	v_mfma_f32_16x16x32_bf16 v[72:75], v[176:179], v[224:227], v[72:75]
	v_mfma_f32_16x16x32_bf16 v[68:71], v[184:187], v[224:227], v[68:71]
	v_mfma_f32_16x16x32_bf16 v[120:123], v[180:183], v[204:207], v[120:123]
	v_mfma_f32_16x16x32_bf16 v[116:119], v[188:191], v[204:207], v[116:119]
	v_mfma_f32_16x16x32_bf16 v[104:107], v[180:183], v[212:215], v[104:107]
	v_mfma_f32_16x16x32_bf16 v[100:103], v[188:191], v[212:215], v[100:103]
	v_mfma_f32_16x16x32_bf16 v[88:91], v[180:183], v[220:223], v[88:91]
	v_mfma_f32_16x16x32_bf16 v[84:87], v[188:191], v[220:223], v[84:87]
	v_mfma_f32_16x16x32_bf16 v[72:75], v[180:183], v[228:231], v[72:75]
	v_mfma_f32_16x16x32_bf16 v[68:71], v[188:191], v[228:231], v[68:71]
	s_setprio 0
	s_barrier
	s_add_i32 s46, s63, s20
	v_lshl_add_u64 v[192:193], v[192:193], 0, s[26:27]
	s_mov_b32 m0, s46
	ds_read_b128 v[200:203], v147 offset:49152
	ds_read_b128 v[204:207], v147 offset:50176
	ds_read_b128 v[208:211], v147 offset:51200
	ds_read_b128 v[212:215], v147 offset:52224
	ds_read_b128 v[216:219], v147 offset:53248
	ds_read_b128 v[220:223], v147 offset:54272
	ds_read_b128 v[224:227], v147 offset:55296
	ds_read_b128 v[228:231], v147 offset:56320
	global_load_lds_dwordx4 v[192:193], off
	s_add_i32 m0, s46, 0x2000
	s_add_u32 s14, s14, 0x40080
	v_lshl_add_u64 v[192:193], v[232:233], 0, s[26:27]
	s_addc_u32 s15, s15, 0
	s_add_i32 s46, s64, s20
	global_load_lds_dwordx4 v[192:193], off
	v_lshl_add_u64 v[192:193], s[14:15], 0, v[2:3]
	s_mov_b32 m0, s46
	s_nop 0
	global_load_lds_dwordx4 v[192:193], off
	v_lshl_add_u64 v[192:193], s[14:15], 0, v[134:135]
	s_add_i32 m0, s46, 0x2000
	s_nop 0
	global_load_lds_dwordx4 v[192:193], off
	v_lshl_add_u64 v[192:193], v[234:235], 0, s[26:27]
	s_mov_b32 m0, s43
	s_nop 0
	global_load_lds_dwordx4 v[192:193], off
	v_lshl_add_u64 v[192:193], v[236:237], 0, s[26:27]
	s_mov_b32 m0, s48
	s_nop 0
	global_load_lds_dwordx4 v[192:193], off
	s_waitcnt vmcnt(8)
	s_waitcnt lgkmcnt(0)
	s_barrier
	s_setprio 1
	s_waitcnt lgkmcnt(0)
	v_mfma_f32_16x16x32_bf16 v[64:67], v[140:143], v[200:203], v[64:67]
	v_mfma_f32_16x16x32_bf16 v[60:63], v[152:155], v[200:203], v[60:63]
	v_mfma_f32_16x16x32_bf16 v[48:51], v[140:143], v[208:211], v[48:51]
	v_mfma_f32_16x16x32_bf16 v[44:47], v[152:155], v[208:211], v[44:47]
	v_mfma_f32_16x16x32_bf16 v[32:35], v[140:143], v[216:219], v[32:35]
	v_mfma_f32_16x16x32_bf16 v[28:31], v[152:155], v[216:219], v[28:31]
	v_mfma_f32_16x16x32_bf16 v[16:19], v[140:143], v[224:227], v[16:19]
	v_mfma_f32_16x16x32_bf16 v[12:15], v[152:155], v[224:227], v[12:15]
	v_mfma_f32_16x16x32_bf16 v[64:67], v[148:151], v[204:207], v[64:67]
	v_mfma_f32_16x16x32_bf16 v[60:63], v[172:175], v[204:207], v[60:63]
	v_mfma_f32_16x16x32_bf16 v[48:51], v[148:151], v[212:215], v[48:51]
	v_mfma_f32_16x16x32_bf16 v[44:47], v[172:175], v[212:215], v[44:47]
	v_mfma_f32_16x16x32_bf16 v[32:35], v[148:151], v[220:223], v[32:35]
	v_mfma_f32_16x16x32_bf16 v[28:31], v[172:175], v[220:223], v[28:31]
	v_mfma_f32_16x16x32_bf16 v[16:19], v[148:151], v[228:231], v[16:19]
	v_mfma_f32_16x16x32_bf16 v[12:15], v[172:175], v[228:231], v[12:15]
	s_setprio 0
	s_setprio 1
	v_mfma_f32_16x16x32_bf16 v[56:59], v[176:179], v[200:203], v[56:59]
	v_mfma_f32_16x16x32_bf16 v[52:55], v[184:187], v[200:203], v[52:55]
	v_mfma_f32_16x16x32_bf16 v[40:43], v[176:179], v[208:211], v[40:43]
	v_mfma_f32_16x16x32_bf16 v[36:39], v[184:187], v[208:211], v[36:39]
	v_mfma_f32_16x16x32_bf16 v[24:27], v[176:179], v[216:219], v[24:27]
	v_mfma_f32_16x16x32_bf16 v[20:23], v[184:187], v[216:219], v[20:23]
	v_mfma_f32_16x16x32_bf16 v[8:11], v[176:179], v[224:227], v[8:11]
	v_mfma_f32_16x16x32_bf16 v[4:7], v[184:187], v[224:227], v[4:7]
	v_mfma_f32_16x16x32_bf16 v[56:59], v[180:183], v[204:207], v[56:59]
	v_mfma_f32_16x16x32_bf16 v[52:55], v[188:191], v[204:207], v[52:55]
	v_mfma_f32_16x16x32_bf16 v[40:43], v[180:183], v[212:215], v[40:43]
	v_mfma_f32_16x16x32_bf16 v[36:39], v[188:191], v[212:215], v[36:39]
	v_mfma_f32_16x16x32_bf16 v[24:27], v[180:183], v[220:223], v[24:27]
	v_mfma_f32_16x16x32_bf16 v[20:23], v[188:191], v[220:223], v[20:23]
	v_mfma_f32_16x16x32_bf16 v[8:11], v[180:183], v[228:231], v[8:11]
	v_mfma_f32_16x16x32_bf16 v[4:7], v[188:191], v[228:231], v[4:7]
	s_setprio 0
	s_barrier
	s_add_i32 s61, s61, 2
	s_add_u32 s55, s55, 0x100
	s_addc_u32 s60, s60, 0
	s_add_u32 s44, s44, 0x100
	s_addc_u32 s45, s45, 0
	s_cmp_gt_u32 s61, 13
	s_cbranch_scc0 .LBB0_493
.Lpeel_exit_KV:
	s_and_b64 vcc, exec, s[10:11]
	s_cbranch_vccz .LBB0_496
	s_barrier
.LBB0_496:
	v_lshl_add_u32 v148, s42, 8, v144
	v_ashrrev_i32_e32 v149, 31, v148
	v_lshl_add_u64 v[142:143], v[148:149], 2, s[6:7]
	global_load_dword v152, v[142:143], off
	v_lshlrev_b64 v[150:151], 11, v[148:149]
	v_lshl_or_b32 v140, s50, 8, v146
	v_ashrrev_i32_e32 v141, 31, v140
	v_lshlrev_b64 v[154:155], 1, v[140:141]
	v_lshl_add_u64 v[140:141], s[8:9], 0, v[150:151]
	v_lshl_add_u64 v[140:141], v[140:141], 0, v[154:155]
	s_mov_b32 s13, 0x40000
	s_mov_b64 s[14:15], 0x40000
	s_waitcnt vmcnt(0)
	v_fmamk_f32 v149, v152, 0x3a800000, v195
	v_rsq_f32_e32 v152, v149
	s_nop 0
	v_pk_mul_f32 v[130:131], v[130:131], v[152:153] op_sel_hi:[1,0]
	v_pk_mul_f32 v[128:129], v[128:129], v[152:153] op_sel_hi:[1,0]
	v_pk_mul_f32 v[126:127], v[126:127], v[152:153] op_sel_hi:[1,0]
	v_pk_mul_f32 v[124:125], v[124:125], v[152:153] op_sel_hi:[1,0]
	v_pk_mul_f32 v[122:123], v[122:123], v[152:153] op_sel_hi:[1,0]
	v_pk_mul_f32 v[120:121], v[120:121], v[152:153] op_sel_hi:[1,0]
	v_pk_mul_f32 v[150:151], v[118:119], v[152:153] op_sel_hi:[1,0]
	v_pk_mul_f32 v[152:153], v[116:117], v[152:153] op_sel_hi:[1,0]
	v_cvt_pk_bf16_f32 v116, v128, v129
	v_cvt_pk_bf16_f32 v117, v130, v131
	v_cvt_pk_bf16_f32 v118, v124, v125
	v_cvt_pk_bf16_f32 v119, v126, v127
	global_store_dwordx4 v[140:141], v[116:119], off
	s_nop 1
	v_cvt_pk_bf16_f32 v116, v120, v121
	v_cvt_pk_bf16_f32 v117, v122, v123
	v_cvt_pk_bf16_f32 v118, v152, v153
	v_cvt_pk_bf16_f32 v119, v150, v151
	global_store_dwordx4 v[140:141], v[116:119], off offset:256
	global_load_dword v118, v[142:143], off offset:64
	s_nop 0
	v_or_b32_e32 v116, 16, v148
	v_ashrrev_i32_e32 v117, 31, v116
	v_lshlrev_b64 v[116:117], 11, v[116:117]
	v_lshl_add_u64 v[116:117], s[8:9], 0, v[116:117]
	v_lshl_add_u64 v[116:117], v[116:117], 0, v[154:155]
	s_waitcnt vmcnt(0)
	v_fmamk_f32 v118, v118, 0x3a800000, v195
	v_rsq_f32_e32 v118, v118
	s_nop 0
	v_pk_mul_f32 v[114:115], v[114:115], v[118:119] op_sel_hi:[1,0]
	v_pk_mul_f32 v[112:113], v[112:113], v[118:119] op_sel_hi:[1,0]
	v_pk_mul_f32 v[110:111], v[110:111], v[118:119] op_sel_hi:[1,0]
	v_pk_mul_f32 v[108:109], v[108:109], v[118:119] op_sel_hi:[1,0]
	v_pk_mul_f32 v[106:107], v[106:107], v[118:119] op_sel_hi:[1,0]
	v_pk_mul_f32 v[104:105], v[104:105], v[118:119] op_sel_hi:[1,0]
	v_pk_mul_f32 v[120:121], v[102:103], v[118:119] op_sel_hi:[1,0]
	v_pk_mul_f32 v[118:119], v[100:101], v[118:119] op_sel_hi:[1,0]
	v_cvt_pk_bf16_f32 v100, v112, v113
	v_cvt_pk_bf16_f32 v101, v114, v115
	v_cvt_pk_bf16_f32 v102, v108, v109
	v_cvt_pk_bf16_f32 v103, v110, v111
	global_store_dwordx4 v[116:117], v[100:103], off
	s_nop 1
	v_cvt_pk_bf16_f32 v100, v104, v105
	v_cvt_pk_bf16_f32 v101, v106, v107
	v_cvt_pk_bf16_f32 v102, v118, v119
	v_cvt_pk_bf16_f32 v103, v120, v121
	global_store_dwordx4 v[116:117], v[100:103], off offset:256
	global_load_dword v102, v[142:143], off offset:128
	s_nop 0
	v_or_b32_e32 v100, 32, v148
	v_ashrrev_i32_e32 v101, 31, v100
	v_lshlrev_b64 v[100:101], 11, v[100:101]
	v_lshl_add_u64 v[100:101], s[8:9], 0, v[100:101]
	v_lshl_add_u64 v[100:101], v[100:101], 0, v[154:155]
	s_waitcnt vmcnt(0)
	v_fmamk_f32 v102, v102, 0x3a800000, v195
	v_rsq_f32_e32 v102, v102
	s_nop 0
	v_pk_mul_f32 v[98:99], v[98:99], v[102:103] op_sel_hi:[1,0]
	v_pk_mul_f32 v[96:97], v[96:97], v[102:103] op_sel_hi:[1,0]
	v_pk_mul_f32 v[94:95], v[94:95], v[102:103] op_sel_hi:[1,0]
	v_pk_mul_f32 v[92:93], v[92:93], v[102:103] op_sel_hi:[1,0]
	v_pk_mul_f32 v[90:91], v[90:91], v[102:103] op_sel_hi:[1,0]
	v_pk_mul_f32 v[88:89], v[88:89], v[102:103] op_sel_hi:[1,0]
	v_pk_mul_f32 v[104:105], v[86:87], v[102:103] op_sel_hi:[1,0]
	v_pk_mul_f32 v[102:103], v[84:85], v[102:103] op_sel_hi:[1,0]
	v_cvt_pk_bf16_f32 v84, v96, v97
	v_cvt_pk_bf16_f32 v85, v98, v99
	v_cvt_pk_bf16_f32 v86, v92, v93
	v_cvt_pk_bf16_f32 v87, v94, v95
	global_store_dwordx4 v[100:101], v[84:87], off
	s_nop 1
	v_cvt_pk_bf16_f32 v84, v88, v89
	v_cvt_pk_bf16_f32 v85, v90, v91
	v_cvt_pk_bf16_f32 v86, v102, v103
	v_cvt_pk_bf16_f32 v87, v104, v105
	global_store_dwordx4 v[100:101], v[84:87], off offset:256
	global_load_dword v86, v[142:143], off offset:192
	s_nop 0
	v_or_b32_e32 v84, 48, v148
	v_ashrrev_i32_e32 v85, 31, v84
	v_lshlrev_b64 v[84:85], 11, v[84:85]
	v_lshl_add_u64 v[84:85], s[8:9], 0, v[84:85]
	v_lshl_add_u64 v[84:85], v[84:85], 0, v[154:155]
	s_waitcnt vmcnt(0)
	v_fmamk_f32 v86, v86, 0x3a800000, v195
	v_rsq_f32_e32 v86, v86
	s_nop 0
	v_pk_mul_f32 v[82:83], v[82:83], v[86:87] op_sel_hi:[1,0]
	v_pk_mul_f32 v[80:81], v[80:81], v[86:87] op_sel_hi:[1,0]
	v_pk_mul_f32 v[78:79], v[78:79], v[86:87] op_sel_hi:[1,0]
	v_pk_mul_f32 v[76:77], v[76:77], v[86:87] op_sel_hi:[1,0]
	v_pk_mul_f32 v[74:75], v[74:75], v[86:87] op_sel_hi:[1,0]
	v_pk_mul_f32 v[72:73], v[72:73], v[86:87] op_sel_hi:[1,0]
	v_pk_mul_f32 v[88:89], v[70:71], v[86:87] op_sel_hi:[1,0]
	v_pk_mul_f32 v[86:87], v[68:69], v[86:87] op_sel_hi:[1,0]
	v_cvt_pk_bf16_f32 v68, v80, v81
	v_cvt_pk_bf16_f32 v69, v82, v83
	v_cvt_pk_bf16_f32 v70, v76, v77
	v_cvt_pk_bf16_f32 v71, v78, v79
	global_store_dwordx4 v[84:85], v[68:71], off
	s_nop 1
	v_cvt_pk_bf16_f32 v68, v72, v73
	v_cvt_pk_bf16_f32 v69, v74, v75
	v_cvt_pk_bf16_f32 v70, v86, v87
	v_cvt_pk_bf16_f32 v71, v88, v89
	global_store_dwordx4 v[84:85], v[68:71], off offset:256
	global_load_dword v70, v[142:143], off offset:512
	v_add_co_u32_e32 v72, vcc, s13, v140
	v_lshl_add_u64 v[68:69], v[140:141], 0, s[14:15]
	s_nop 0
	v_addc_co_u32_e32 v73, vcc, 0, v141, vcc
	s_mov_b32 s13, 0x48000
	s_mov_b64 s[14:15], 0x48000
	s_waitcnt vmcnt(0)
	v_fmamk_f32 v70, v70, 0x3a800000, v195
	v_rsq_f32_e32 v70, v70
	s_nop 0
	v_pk_mul_f32 v[66:67], v[66:67], v[70:71] op_sel_hi:[1,0]
	v_pk_mul_f32 v[64:65], v[64:65], v[70:71] op_sel_hi:[1,0]
	v_pk_mul_f32 v[62:63], v[62:63], v[70:71] op_sel_hi:[1,0]
	v_pk_mul_f32 v[60:61], v[60:61], v[70:71] op_sel_hi:[1,0]
	v_pk_mul_f32 v[58:59], v[58:59], v[70:71] op_sel_hi:[1,0]
	v_pk_mul_f32 v[56:57], v[56:57], v[70:71] op_sel_hi:[1,0]
	v_pk_mul_f32 v[74:75], v[54:55], v[70:71] op_sel_hi:[1,0]
	v_pk_mul_f32 v[70:71], v[52:53], v[70:71] op_sel_hi:[1,0]
	v_cvt_pk_bf16_f32 v52, v64, v65
	v_cvt_pk_bf16_f32 v53, v66, v67
	v_cvt_pk_bf16_f32 v54, v60, v61
	v_cvt_pk_bf16_f32 v55, v62, v63
	global_store_dwordx4 v[72:73], v[52:55], off
	s_nop 1
	v_cvt_pk_bf16_f32 v52, v56, v57
	v_cvt_pk_bf16_f32 v53, v58, v59
	v_cvt_pk_bf16_f32 v54, v70, v71
	v_cvt_pk_bf16_f32 v55, v74, v75
	global_store_dwordx4 v[68:69], v[52:55], off offset:256
	global_load_dword v54, v[142:143], off offset:576
	v_add_co_u32_e32 v56, vcc, s13, v140
	v_lshl_add_u64 v[52:53], v[140:141], 0, s[14:15]
	s_nop 0
	v_addc_co_u32_e32 v57, vcc, 0, v141, vcc
	s_mov_b32 s13, 0x50000
	s_mov_b64 s[14:15], 0x50000
	s_waitcnt vmcnt(0)
	v_fmamk_f32 v54, v54, 0x3a800000, v195
	v_rsq_f32_e32 v54, v54
	s_nop 0
	v_pk_mul_f32 v[50:51], v[50:51], v[54:55] op_sel_hi:[1,0]
	v_pk_mul_f32 v[48:49], v[48:49], v[54:55] op_sel_hi:[1,0]
	v_pk_mul_f32 v[46:47], v[46:47], v[54:55] op_sel_hi:[1,0]
	v_pk_mul_f32 v[44:45], v[44:45], v[54:55] op_sel_hi:[1,0]
	v_pk_mul_f32 v[42:43], v[42:43], v[54:55] op_sel_hi:[1,0]
	v_pk_mul_f32 v[40:41], v[40:41], v[54:55] op_sel_hi:[1,0]
	v_pk_mul_f32 v[58:59], v[38:39], v[54:55] op_sel_hi:[1,0]
	v_pk_mul_f32 v[54:55], v[36:37], v[54:55] op_sel_hi:[1,0]
	v_cvt_pk_bf16_f32 v36, v48, v49
	v_cvt_pk_bf16_f32 v37, v50, v51
	v_cvt_pk_bf16_f32 v38, v44, v45
	v_cvt_pk_bf16_f32 v39, v46, v47
	global_store_dwordx4 v[56:57], v[36:39], off
	s_nop 1
	v_cvt_pk_bf16_f32 v36, v40, v41
	v_cvt_pk_bf16_f32 v37, v42, v43
	v_cvt_pk_bf16_f32 v38, v54, v55
	v_cvt_pk_bf16_f32 v39, v58, v59
	global_store_dwordx4 v[52:53], v[36:39], off offset:256
	global_load_dword v38, v[142:143], off offset:640
	v_add_co_u32_e32 v40, vcc, s13, v140
	v_lshl_add_u64 v[36:37], v[140:141], 0, s[14:15]
	s_nop 0
	v_addc_co_u32_e32 v41, vcc, 0, v141, vcc
	s_andn2_b64 vcc, exec, s[0:1]
	s_mov_b64 s[0:1], 0x58000
	s_waitcnt vmcnt(0)
	v_fmamk_f32 v38, v38, 0x3a800000, v195
	v_rsq_f32_e32 v38, v38
	s_nop 0
	v_pk_mul_f32 v[34:35], v[34:35], v[38:39] op_sel_hi:[1,0]
	v_pk_mul_f32 v[32:33], v[32:33], v[38:39] op_sel_hi:[1,0]
	v_pk_mul_f32 v[30:31], v[30:31], v[38:39] op_sel_hi:[1,0]
	v_pk_mul_f32 v[28:29], v[28:29], v[38:39] op_sel_hi:[1,0]
	v_pk_mul_f32 v[26:27], v[26:27], v[38:39] op_sel_hi:[1,0]
	v_pk_mul_f32 v[24:25], v[24:25], v[38:39] op_sel_hi:[1,0]
	v_pk_mul_f32 v[42:43], v[22:23], v[38:39] op_sel_hi:[1,0]
	v_pk_mul_f32 v[38:39], v[20:21], v[38:39] op_sel_hi:[1,0]
	v_cvt_pk_bf16_f32 v20, v32, v33
	v_cvt_pk_bf16_f32 v21, v34, v35
	v_cvt_pk_bf16_f32 v22, v28, v29
	v_cvt_pk_bf16_f32 v23, v30, v31
	global_store_dwordx4 v[40:41], v[20:23], off
	s_nop 1
	v_cvt_pk_bf16_f32 v20, v24, v25
	v_cvt_pk_bf16_f32 v21, v26, v27
	v_cvt_pk_bf16_f32 v22, v38, v39
	v_cvt_pk_bf16_f32 v23, v42, v43
	global_store_dwordx4 v[36:37], v[20:23], off offset:256
	global_load_dword v22, v[142:143], off offset:704
	s_nop 0
	v_lshl_add_u64 v[20:21], v[140:141], 0, s[0:1]
	s_mov_b32 s0, 0x58000
	v_add_co_u32_e64 v24, s[0:1], s0, v140
	s_waitcnt vmcnt(0)
	v_fmamk_f32 v22, v22, 0x3a800000, v195
	v_rsq_f32_e32 v22, v22
	v_addc_co_u32_e64 v25, s[0:1], 0, v141, s[0:1]
	s_mov_b64 s[0:1], -1
	v_pk_mul_f32 v[18:19], v[18:19], v[22:23] op_sel_hi:[1,0]
	v_pk_mul_f32 v[16:17], v[16:17], v[22:23] op_sel_hi:[1,0]
	v_pk_mul_f32 v[14:15], v[14:15], v[22:23] op_sel_hi:[1,0]
	v_pk_mul_f32 v[12:13], v[12:13], v[22:23] op_sel_hi:[1,0]
	v_pk_mul_f32 v[10:11], v[10:11], v[22:23] op_sel_hi:[1,0]
	v_pk_mul_f32 v[8:9], v[8:9], v[22:23] op_sel_hi:[1,0]
	v_pk_mul_f32 v[26:27], v[6:7], v[22:23] op_sel_hi:[1,0]
	v_pk_mul_f32 v[22:23], v[4:5], v[22:23] op_sel_hi:[1,0]
	v_cvt_pk_bf16_f32 v4, v16, v17
	v_cvt_pk_bf16_f32 v5, v18, v19
	v_cvt_pk_bf16_f32 v6, v12, v13
	v_cvt_pk_bf16_f32 v7, v14, v15
	global_store_dwordx4 v[24:25], v[4:7], off
	s_nop 1
	v_cvt_pk_bf16_f32 v4, v8, v9
	v_cvt_pk_bf16_f32 v5, v10, v11
	v_cvt_pk_bf16_f32 v6, v22, v23
	v_cvt_pk_bf16_f32 v7, v26, v27
	global_store_dwordx4 v[20:21], v[4:7], off offset:256
	s_cbranch_vccnz .LBB0_485
	s_andn2_b64 vcc, exec, s[4:5]
	s_cbranch_vccnz .LBB0_484
	s_barrier
	s_branch .LBB0_484

.LBB0_811:
	s_ashr_i32 s47, s46, 31
	s_lshl_b64 s[16:17], s[46:47], 19
	s_add_u32 s48, s18, s16
	s_addc_u32 s49, s19, s17
	s_and_b64 s[16:17], s[40:41], exec
	s_cselect_b32 s16, s49, s43
	s_cselect_b32 s17, s48, s42
	s_ashr_i32 s39, s38, 31
	s_lshl_b64 s[50:51], s[38:39], 19
	s_add_u32 s50, s20, s50
	s_addc_u32 s51, s21, s51
	s_and_b64 s[54:55], s[40:41], exec
	s_cselect_b32 s39, s51, s15
	s_cselect_b32 s47, s50, s14
	s_add_u32 s87, s14, 0x100
	s_addc_u32 s89, s15, 0
	s_add_u32 s42, s42, 0x40080
	s_addc_u32 s43, s43, 0
	s_mov_b32 s91, -2
	s_waitcnt lgkmcnt(0)
	s_add_u32 s14, s42, 0xfffc0080
	s_addc_u32 s15, s43, -1
	s_add_i32 s24, 0, 0x10000
	s_cmp_eq_u32 s91, 12
	s_cselect_b32 s55, s16, s15
	s_cselect_b32 s54, s17, s14
	s_cselect_b32 s15, s39, s89
	s_cselect_b32 s14, s47, s87
	s_add_i32 s25, 0, 0x14000
	v_add_u32_e32 v152, s24, v175
	v_add_u32_e32 v172, s25, v175
	ds_read_b128 v[132:135], v152
	ds_read_b128 v[136:139], v152 offset:1024
	ds_read_b128 v[148:151], v152 offset:2048
	ds_read_b128 v[152:155], v152 offset:3072
	ds_read_b128 v[178:181], v172
	ds_read_b128 v[182:185], v172 offset:1024
	ds_read_b128 v[186:189], v172 offset:2048
	ds_read_b128 v[190:193], v172 offset:3072
	v_lshl_add_u64 v[172:173], s[42:43], 0, v[146:147]
	s_add_i32 m0, s23, 0xc000
	ds_read_b128 v[200:203], v177
	ds_read_b128 v[204:207], v177 offset:1024
	ds_read_b128 v[208:211], v177 offset:2048
	ds_read_b128 v[212:215], v177 offset:3072
	ds_read_b128 v[216:219], v177 offset:4096
	ds_read_b128 v[220:223], v177 offset:5120
	ds_read_b128 v[224:227], v177 offset:6144
	ds_read_b128 v[228:231], v177 offset:7168
	global_load_lds_dwordx4 v[172:173], off
	v_lshl_add_u64 v[172:173], s[42:43], 0, v[144:145]
	s_add_i32 m0, s23, 0xe000
	s_nop 0
	global_load_lds_dwordx4 v[172:173], off
	s_waitcnt vmcnt(8)
	s_waitcnt lgkmcnt(0)
	s_barrier
	s_setprio 1
	s_waitcnt lgkmcnt(0)
	v_mfma_f32_16x16x32_bf16 v[128:131], v[132:135], v[200:203], 0
	v_mfma_f32_16x16x32_bf16 v[124:127], v[148:151], v[200:203], 0
	v_mfma_f32_16x16x32_bf16 v[112:115], v[132:135], v[208:211], 0
	v_mfma_f32_16x16x32_bf16 v[108:111], v[148:151], v[208:211], 0
	v_mfma_f32_16x16x32_bf16 v[96:99], v[132:135], v[216:219], 0
	v_mfma_f32_16x16x32_bf16 v[92:95], v[148:151], v[216:219], 0
	v_mfma_f32_16x16x32_bf16 v[80:83], v[132:135], v[224:227], 0
	v_mfma_f32_16x16x32_bf16 v[76:79], v[148:151], v[224:227], 0
	v_mfma_f32_16x16x32_bf16 v[128:131], v[136:139], v[204:207], v[128:131]
	v_mfma_f32_16x16x32_bf16 v[124:127], v[152:155], v[204:207], v[124:127]
	v_mfma_f32_16x16x32_bf16 v[112:115], v[136:139], v[212:215], v[112:115]
	v_mfma_f32_16x16x32_bf16 v[108:111], v[152:155], v[212:215], v[108:111]
	v_mfma_f32_16x16x32_bf16 v[96:99], v[136:139], v[220:223], v[96:99]
	v_mfma_f32_16x16x32_bf16 v[92:95], v[152:155], v[220:223], v[92:95]
	v_mfma_f32_16x16x32_bf16 v[80:83], v[136:139], v[228:231], v[80:83]
	v_mfma_f32_16x16x32_bf16 v[76:79], v[152:155], v[228:231], v[76:79]
	s_setprio 0
	s_setprio 1
	v_mfma_f32_16x16x32_bf16 v[120:123], v[178:181], v[200:203], 0
	v_mfma_f32_16x16x32_bf16 v[116:119], v[186:189], v[200:203], 0
	v_mfma_f32_16x16x32_bf16 v[104:107], v[178:181], v[208:211], 0
	v_mfma_f32_16x16x32_bf16 v[100:103], v[186:189], v[208:211], 0
	v_mfma_f32_16x16x32_bf16 v[88:91], v[178:181], v[216:219], 0
	v_mfma_f32_16x16x32_bf16 v[84:87], v[186:189], v[216:219], 0
	v_mfma_f32_16x16x32_bf16 v[72:75], v[178:181], v[224:227], 0
	v_mfma_f32_16x16x32_bf16 v[68:71], v[186:189], v[224:227], 0
	v_mfma_f32_16x16x32_bf16 v[120:123], v[182:185], v[204:207], v[120:123]
	v_mfma_f32_16x16x32_bf16 v[116:119], v[190:193], v[204:207], v[116:119]
	v_mfma_f32_16x16x32_bf16 v[104:107], v[182:185], v[212:215], v[104:107]
	v_mfma_f32_16x16x32_bf16 v[100:103], v[190:193], v[212:215], v[100:103]
	v_mfma_f32_16x16x32_bf16 v[88:91], v[182:185], v[220:223], v[88:91]
	v_mfma_f32_16x16x32_bf16 v[84:87], v[190:193], v[220:223], v[84:87]
	v_mfma_f32_16x16x32_bf16 v[72:75], v[182:185], v[228:231], v[72:75]
	v_mfma_f32_16x16x32_bf16 v[68:71], v[190:193], v[228:231], v[68:71]
	s_setprio 0
	s_barrier
	s_add_i32 s24, s24, s22
	v_lshl_add_u64 v[172:173], s[14:15], 0, v[2:3]
	s_mov_b32 m0, s24
	ds_read_b128 v[200:203], v177 offset:16384
	ds_read_b128 v[204:207], v177 offset:17408
	ds_read_b128 v[208:211], v177 offset:18432
	ds_read_b128 v[212:215], v177 offset:19456
	ds_read_b128 v[216:219], v177 offset:20480
	ds_read_b128 v[220:223], v177 offset:21504
	ds_read_b128 v[224:227], v177 offset:22528
	ds_read_b128 v[228:231], v177 offset:23552
	global_load_lds_dwordx4 v[172:173], off
	s_add_i32 m0, s24, 0x2000
	s_add_u32 s96, s14, 0x40000
	v_lshl_add_u64 v[232:233], s[14:15], 0, v[0:1]
	s_addc_u32 s97, s15, 0
	s_add_i32 s24, s25, s22
	global_load_lds_dwordx4 v[232:233], off
	v_lshl_add_u64 v[234:235], s[96:97], 0, v[2:3]
	s_mov_b32 m0, s24
	v_lshl_add_u64 v[236:237], s[54:55], 0, v[140:141]
	global_load_lds_dwordx4 v[234:235], off
	v_lshl_add_u64 v[234:235], s[96:97], 0, v[0:1]
	s_add_i32 m0, s24, 0x2000
	s_nop 0
	global_load_lds_dwordx4 v[234:235], off
	v_lshl_add_u64 v[234:235], s[54:55], 0, v[142:143]
	s_mov_b32 m0, s23
	s_nop 0
	global_load_lds_dwordx4 v[234:235], off
	s_mov_b32 m0, s45
	s_nop 0
	global_load_lds_dwordx4 v[236:237], off
	s_waitcnt vmcnt(8)
	s_waitcnt lgkmcnt(0)
	s_barrier
	s_setprio 1
	s_waitcnt lgkmcnt(0)
	v_mfma_f32_16x16x32_bf16 v[64:67], v[132:135], v[200:203], 0
	v_mfma_f32_16x16x32_bf16 v[60:63], v[148:151], v[200:203], 0
	v_mfma_f32_16x16x32_bf16 v[48:51], v[132:135], v[208:211], 0
	v_mfma_f32_16x16x32_bf16 v[44:47], v[148:151], v[208:211], 0
	v_mfma_f32_16x16x32_bf16 v[32:35], v[132:135], v[216:219], 0
	v_mfma_f32_16x16x32_bf16 v[28:31], v[148:151], v[216:219], 0
	v_mfma_f32_16x16x32_bf16 v[16:19], v[132:135], v[224:227], 0
	v_mfma_f32_16x16x32_bf16 v[12:15], v[148:151], v[224:227], 0
	v_mfma_f32_16x16x32_bf16 v[64:67], v[136:139], v[204:207], v[64:67]
	v_mfma_f32_16x16x32_bf16 v[60:63], v[152:155], v[204:207], v[60:63]
	v_mfma_f32_16x16x32_bf16 v[48:51], v[136:139], v[212:215], v[48:51]
	v_mfma_f32_16x16x32_bf16 v[44:47], v[152:155], v[212:215], v[44:47]
	v_mfma_f32_16x16x32_bf16 v[32:35], v[136:139], v[220:223], v[32:35]
	v_mfma_f32_16x16x32_bf16 v[28:31], v[152:155], v[220:223], v[28:31]
	v_mfma_f32_16x16x32_bf16 v[16:19], v[136:139], v[228:231], v[16:19]
	v_mfma_f32_16x16x32_bf16 v[12:15], v[152:155], v[228:231], v[12:15]
	s_setprio 0
	s_setprio 1
	v_mfma_f32_16x16x32_bf16 v[56:59], v[178:181], v[200:203], 0
	v_mfma_f32_16x16x32_bf16 v[52:55], v[186:189], v[200:203], 0
	v_mfma_f32_16x16x32_bf16 v[40:43], v[178:181], v[208:211], 0
	v_mfma_f32_16x16x32_bf16 v[36:39], v[186:189], v[208:211], 0
	v_mfma_f32_16x16x32_bf16 v[24:27], v[178:181], v[216:219], 0
	v_mfma_f32_16x16x32_bf16 v[20:23], v[186:189], v[216:219], 0
	v_mfma_f32_16x16x32_bf16 v[8:11], v[178:181], v[224:227], 0
	v_mfma_f32_16x16x32_bf16 v[4:7], v[186:189], v[224:227], 0
	v_mfma_f32_16x16x32_bf16 v[56:59], v[182:185], v[204:207], v[56:59]
	v_mfma_f32_16x16x32_bf16 v[52:55], v[190:193], v[204:207], v[52:55]
	v_mfma_f32_16x16x32_bf16 v[40:43], v[182:185], v[212:215], v[40:43]
	v_mfma_f32_16x16x32_bf16 v[36:39], v[190:193], v[212:215], v[36:39]
	v_mfma_f32_16x16x32_bf16 v[24:27], v[182:185], v[220:223], v[24:27]
	v_mfma_f32_16x16x32_bf16 v[20:23], v[190:193], v[220:223], v[20:23]
	v_mfma_f32_16x16x32_bf16 v[8:11], v[182:185], v[228:231], v[8:11]
	v_mfma_f32_16x16x32_bf16 v[4:7], v[190:193], v[228:231], v[4:7]
	s_setprio 0
	s_barrier
	s_add_i32 s24, 0, 0x18000
	s_add_i32 s25, 0, 0x1c000
	v_add_u32_e32 v152, s24, v175
	v_add_u32_e32 v190, s25, v175
	ds_read_b128 v[132:135], v152
	ds_read_b128 v[136:139], v152 offset:1024
	ds_read_b128 v[148:151], v152 offset:2048
	ds_read_b128 v[152:155], v152 offset:3072
	ds_read_b128 v[178:181], v190
	ds_read_b128 v[182:185], v190 offset:1024
	ds_read_b128 v[186:189], v190 offset:2048
	ds_read_b128 v[190:193], v190 offset:3072
	s_add_u32 s54, s54, 0x40000
	s_addc_u32 s55, s55, 0
	s_mov_b32 m0, s60
	v_lshl_add_u64 v[238:239], s[54:55], 0, v[142:143]
	ds_read_b128 v[200:203], v177 offset:32768
	ds_read_b128 v[204:207], v177 offset:33792
	ds_read_b128 v[208:211], v177 offset:34816
	ds_read_b128 v[212:215], v177 offset:35840
	ds_read_b128 v[216:219], v177 offset:36864
	ds_read_b128 v[220:223], v177 offset:37888
	ds_read_b128 v[224:227], v177 offset:38912
	ds_read_b128 v[228:231], v177 offset:39936
	global_load_lds_dwordx4 v[238:239], off
	v_lshl_add_u64 v[238:239], s[54:55], 0, v[140:141]
	s_mov_b32 m0, s61
	s_nop 0
	global_load_lds_dwordx4 v[238:239], off
	s_waitcnt vmcnt(8)
	s_waitcnt lgkmcnt(0)
	s_barrier
	s_setprio 1
	s_waitcnt lgkmcnt(0)
	v_mfma_f32_16x16x32_bf16 v[128:131], v[132:135], v[200:203], v[128:131]
	v_mfma_f32_16x16x32_bf16 v[124:127], v[148:151], v[200:203], v[124:127]
	v_mfma_f32_16x16x32_bf16 v[112:115], v[132:135], v[208:211], v[112:115]
	v_mfma_f32_16x16x32_bf16 v[108:111], v[148:151], v[208:211], v[108:111]
	v_mfma_f32_16x16x32_bf16 v[96:99], v[132:135], v[216:219], v[96:99]
	v_mfma_f32_16x16x32_bf16 v[92:95], v[148:151], v[216:219], v[92:95]
	v_mfma_f32_16x16x32_bf16 v[80:83], v[132:135], v[224:227], v[80:83]
	v_mfma_f32_16x16x32_bf16 v[76:79], v[148:151], v[224:227], v[76:79]
	v_mfma_f32_16x16x32_bf16 v[128:131], v[136:139], v[204:207], v[128:131]
	v_mfma_f32_16x16x32_bf16 v[124:127], v[152:155], v[204:207], v[124:127]
	v_mfma_f32_16x16x32_bf16 v[112:115], v[136:139], v[212:215], v[112:115]
	v_mfma_f32_16x16x32_bf16 v[108:111], v[152:155], v[212:215], v[108:111]
	v_mfma_f32_16x16x32_bf16 v[96:99], v[136:139], v[220:223], v[96:99]
	v_mfma_f32_16x16x32_bf16 v[92:95], v[152:155], v[220:223], v[92:95]
	v_mfma_f32_16x16x32_bf16 v[80:83], v[136:139], v[228:231], v[80:83]
	v_mfma_f32_16x16x32_bf16 v[76:79], v[152:155], v[228:231], v[76:79]
	s_setprio 0
	s_setprio 1
	v_mfma_f32_16x16x32_bf16 v[120:123], v[178:181], v[200:203], v[120:123]
	v_mfma_f32_16x16x32_bf16 v[116:119], v[186:189], v[200:203], v[116:119]
	v_mfma_f32_16x16x32_bf16 v[104:107], v[178:181], v[208:211], v[104:107]
	v_mfma_f32_16x16x32_bf16 v[100:103], v[186:189], v[208:211], v[100:103]
	v_mfma_f32_16x16x32_bf16 v[88:91], v[178:181], v[216:219], v[88:91]
	v_mfma_f32_16x16x32_bf16 v[84:87], v[186:189], v[216:219], v[84:87]
	v_mfma_f32_16x16x32_bf16 v[72:75], v[178:181], v[224:227], v[72:75]
	v_mfma_f32_16x16x32_bf16 v[68:71], v[186:189], v[224:227], v[68:71]
	v_mfma_f32_16x16x32_bf16 v[120:123], v[182:185], v[204:207], v[120:123]
	v_mfma_f32_16x16x32_bf16 v[116:119], v[190:193], v[204:207], v[116:119]
	v_mfma_f32_16x16x32_bf16 v[104:107], v[182:185], v[212:215], v[104:107]
	v_mfma_f32_16x16x32_bf16 v[100:103], v[190:193], v[212:215], v[100:103]
	v_mfma_f32_16x16x32_bf16 v[88:91], v[182:185], v[220:223], v[88:91]
	v_mfma_f32_16x16x32_bf16 v[84:87], v[190:193], v[220:223], v[84:87]
	v_mfma_f32_16x16x32_bf16 v[72:75], v[182:185], v[228:231], v[72:75]
	v_mfma_f32_16x16x32_bf16 v[68:71], v[190:193], v[228:231], v[68:71]
	s_setprio 0
	s_barrier
	s_add_i32 s24, s24, s22
	v_lshl_add_u64 v[172:173], v[172:173], 0, s[26:27]
	s_mov_b32 m0, s24
	ds_read_b128 v[200:203], v177 offset:49152
	ds_read_b128 v[204:207], v177 offset:50176
	ds_read_b128 v[208:211], v177 offset:51200
	ds_read_b128 v[212:215], v177 offset:52224
	ds_read_b128 v[216:219], v177 offset:53248
	ds_read_b128 v[220:223], v177 offset:54272
	ds_read_b128 v[224:227], v177 offset:55296
	ds_read_b128 v[228:231], v177 offset:56320
	global_load_lds_dwordx4 v[172:173], off
	s_add_i32 m0, s24, 0x2000
	s_add_u32 s14, s14, 0x40080
	v_lshl_add_u64 v[172:173], v[232:233], 0, s[26:27]
	s_addc_u32 s15, s15, 0
	s_add_i32 s24, s25, s22
	global_load_lds_dwordx4 v[172:173], off
	v_lshl_add_u64 v[172:173], s[14:15], 0, v[2:3]
	s_mov_b32 m0, s24
	s_nop 0
	global_load_lds_dwordx4 v[172:173], off
	v_lshl_add_u64 v[172:173], s[14:15], 0, v[0:1]
	s_add_i32 m0, s24, 0x2000
	s_nop 0
	global_load_lds_dwordx4 v[172:173], off
	v_lshl_add_u64 v[172:173], v[234:235], 0, s[26:27]
	s_mov_b32 m0, s64
	s_nop 0
	global_load_lds_dwordx4 v[172:173], off
	v_lshl_add_u64 v[172:173], v[236:237], 0, s[26:27]
	s_mov_b32 m0, s65
	s_nop 0
	global_load_lds_dwordx4 v[172:173], off
	s_waitcnt vmcnt(8)
	s_waitcnt lgkmcnt(0)
	s_barrier
	s_setprio 1
	s_waitcnt lgkmcnt(0)
	v_mfma_f32_16x16x32_bf16 v[64:67], v[132:135], v[200:203], v[64:67]
	v_mfma_f32_16x16x32_bf16 v[60:63], v[148:151], v[200:203], v[60:63]
	v_mfma_f32_16x16x32_bf16 v[48:51], v[132:135], v[208:211], v[48:51]
	v_mfma_f32_16x16x32_bf16 v[44:47], v[148:151], v[208:211], v[44:47]
	v_mfma_f32_16x16x32_bf16 v[32:35], v[132:135], v[216:219], v[32:35]
	v_mfma_f32_16x16x32_bf16 v[28:31], v[148:151], v[216:219], v[28:31]
	v_mfma_f32_16x16x32_bf16 v[16:19], v[132:135], v[224:227], v[16:19]
	v_mfma_f32_16x16x32_bf16 v[12:15], v[148:151], v[224:227], v[12:15]
	v_mfma_f32_16x16x32_bf16 v[64:67], v[136:139], v[204:207], v[64:67]
	v_mfma_f32_16x16x32_bf16 v[60:63], v[152:155], v[204:207], v[60:63]
	v_mfma_f32_16x16x32_bf16 v[48:51], v[136:139], v[212:215], v[48:51]
	v_mfma_f32_16x16x32_bf16 v[44:47], v[152:155], v[212:215], v[44:47]
	v_mfma_f32_16x16x32_bf16 v[32:35], v[136:139], v[220:223], v[32:35]
	v_mfma_f32_16x16x32_bf16 v[28:31], v[152:155], v[220:223], v[28:31]
	v_mfma_f32_16x16x32_bf16 v[16:19], v[136:139], v[228:231], v[16:19]
	v_mfma_f32_16x16x32_bf16 v[12:15], v[152:155], v[228:231], v[12:15]
	s_setprio 0
	s_setprio 1
	v_mfma_f32_16x16x32_bf16 v[56:59], v[178:181], v[200:203], v[56:59]
	v_mfma_f32_16x16x32_bf16 v[52:55], v[186:189], v[200:203], v[52:55]
	v_mfma_f32_16x16x32_bf16 v[40:43], v[178:181], v[208:211], v[40:43]
	v_mfma_f32_16x16x32_bf16 v[36:39], v[186:189], v[208:211], v[36:39]
	v_mfma_f32_16x16x32_bf16 v[24:27], v[178:181], v[216:219], v[24:27]
	v_mfma_f32_16x16x32_bf16 v[20:23], v[186:189], v[216:219], v[20:23]
	v_mfma_f32_16x16x32_bf16 v[8:11], v[178:181], v[224:227], v[8:11]
	v_mfma_f32_16x16x32_bf16 v[4:7], v[186:189], v[224:227], v[4:7]
	v_mfma_f32_16x16x32_bf16 v[56:59], v[182:185], v[204:207], v[56:59]
	v_mfma_f32_16x16x32_bf16 v[52:55], v[190:193], v[204:207], v[52:55]
	v_mfma_f32_16x16x32_bf16 v[40:43], v[182:185], v[212:215], v[40:43]
	v_mfma_f32_16x16x32_bf16 v[36:39], v[190:193], v[212:215], v[36:39]
	v_mfma_f32_16x16x32_bf16 v[24:27], v[182:185], v[220:223], v[24:27]
	v_mfma_f32_16x16x32_bf16 v[20:23], v[190:193], v[220:223], v[20:23]
	v_mfma_f32_16x16x32_bf16 v[8:11], v[182:185], v[228:231], v[8:11]
	v_mfma_f32_16x16x32_bf16 v[4:7], v[190:193], v[228:231], v[4:7]
	s_setprio 0
	s_barrier
	s_add_i32 s91, s91, 2
	s_add_u32 s87, s87, 0x100
	s_addc_u32 s89, s89, 0
	s_add_u32 s42, s42, 0x100
	s_addc_u32 s43, s43, 0
	s_cmp_gt_u32 s91, 13
	s_cbranch_scc0 .LBB0_812
	s_branch .Lpeel_exit_G2

.Lpeel_exit_G2:
	s_and_b64 vcc, exec, s[12:13]
	s_cbranch_vccz .LBB0_815
	s_barrier

.LBB0_1043:
	s_add_u32 s55, s14, 0x100
	s_addc_u32 s60, s15, 0
	s_mov_b32 s61, -2
	s_waitcnt lgkmcnt(0)
	s_add_u32 s14, s38, 0x100
	s_addc_u32 s15, s39, 0
	s_add_i32 s24, 0, 0x10000
	s_cmp_eq_u32 s61, 40
	s_cselect_b32 s45, s13, s15
	s_cselect_b32 s44, s12, s14
	v_add_u32_e32 v144, s24, v147
	s_cselect_b32 s43, s29, s60
	s_cselect_b32 s42, s28, s55
	s_add_i32 s25, 0, 0x14000
	ds_read_b128 v[140:143], v144
	ds_read_b128 v[150:153], v144 offset:1024
	ds_read_b128 v[172:175], v144 offset:2048
	ds_read_b128 v[176:179], v144 offset:3072
	v_add_u32_e32 v144, s25, v147
	ds_read_b128 v[180:183], v144
	ds_read_b128 v[184:187], v144 offset:1024
	ds_read_b128 v[188:191], v144 offset:2048
	ds_read_b128 v[200:203], v144 offset:3072
	v_lshl_add_u64 v[144:145], s[38:39], 0, v[138:139]
	s_add_i32 m0, s21, 0xc000
	ds_read_b128 v[204:207], v149
	ds_read_b128 v[208:211], v149 offset:1024
	ds_read_b128 v[212:215], v149 offset:2048
	ds_read_b128 v[216:219], v149 offset:3072
	ds_read_b128 v[220:223], v149 offset:4096
	ds_read_b128 v[224:227], v149 offset:5120
	ds_read_b128 v[228:231], v149 offset:6144
	ds_read_b128 v[232:235], v149 offset:7168
	global_load_lds_dwordx4 v[144:145], off
	v_lshl_add_u64 v[144:145], s[38:39], 0, v[136:137]
	s_add_i32 m0, s21, 0xe000
	s_nop 0
	global_load_lds_dwordx4 v[144:145], off
	s_waitcnt vmcnt(8)
	s_waitcnt lgkmcnt(0)
	s_barrier
	s_setprio 1
	s_waitcnt lgkmcnt(0)
	v_mfma_f32_16x16x32_bf16 v[128:131], v[140:143], v[204:207], 0
	v_mfma_f32_16x16x32_bf16 v[124:127], v[172:175], v[204:207], 0
	v_mfma_f32_16x16x32_bf16 v[112:115], v[140:143], v[212:215], 0
	v_mfma_f32_16x16x32_bf16 v[108:111], v[172:175], v[212:215], 0
	v_mfma_f32_16x16x32_bf16 v[96:99], v[140:143], v[220:223], 0
	v_mfma_f32_16x16x32_bf16 v[92:95], v[172:175], v[220:223], 0
	v_mfma_f32_16x16x32_bf16 v[80:83], v[140:143], v[228:231], 0
	v_mfma_f32_16x16x32_bf16 v[76:79], v[172:175], v[228:231], 0
	v_mfma_f32_16x16x32_bf16 v[128:131], v[150:153], v[208:211], v[128:131]
	v_mfma_f32_16x16x32_bf16 v[124:127], v[176:179], v[208:211], v[124:127]
	v_mfma_f32_16x16x32_bf16 v[112:115], v[150:153], v[216:219], v[112:115]
	v_mfma_f32_16x16x32_bf16 v[108:111], v[176:179], v[216:219], v[108:111]
	v_mfma_f32_16x16x32_bf16 v[96:99], v[150:153], v[224:227], v[96:99]
	v_mfma_f32_16x16x32_bf16 v[92:95], v[176:179], v[224:227], v[92:95]
	v_mfma_f32_16x16x32_bf16 v[80:83], v[150:153], v[232:235], v[80:83]
	v_mfma_f32_16x16x32_bf16 v[76:79], v[176:179], v[232:235], v[76:79]
	s_setprio 0
	s_setprio 1
	v_mfma_f32_16x16x32_bf16 v[120:123], v[180:183], v[204:207], 0
	v_mfma_f32_16x16x32_bf16 v[116:119], v[188:191], v[204:207], 0
	v_mfma_f32_16x16x32_bf16 v[104:107], v[180:183], v[212:215], 0
	v_mfma_f32_16x16x32_bf16 v[100:103], v[188:191], v[212:215], 0
	v_mfma_f32_16x16x32_bf16 v[88:91], v[180:183], v[220:223], 0
	v_mfma_f32_16x16x32_bf16 v[84:87], v[188:191], v[220:223], 0
	v_mfma_f32_16x16x32_bf16 v[72:75], v[180:183], v[228:231], 0
	v_mfma_f32_16x16x32_bf16 v[68:71], v[188:191], v[228:231], 0
	v_mfma_f32_16x16x32_bf16 v[120:123], v[184:187], v[208:211], v[120:123]
	v_mfma_f32_16x16x32_bf16 v[116:119], v[200:203], v[208:211], v[116:119]
	v_mfma_f32_16x16x32_bf16 v[104:107], v[184:187], v[216:219], v[104:107]
	v_mfma_f32_16x16x32_bf16 v[100:103], v[200:203], v[216:219], v[100:103]
	v_mfma_f32_16x16x32_bf16 v[88:91], v[184:187], v[224:227], v[88:91]
	v_mfma_f32_16x16x32_bf16 v[84:87], v[200:203], v[224:227], v[84:87]
	v_mfma_f32_16x16x32_bf16 v[72:75], v[184:187], v[232:235], v[72:75]
	v_mfma_f32_16x16x32_bf16 v[68:71], v[200:203], v[232:235], v[68:71]
	s_setprio 0
	s_barrier
	s_add_i32 s24, s24, s20
	v_lshl_add_u64 v[144:145], s[42:43], 0, v[2:3]
	s_mov_b32 m0, s24
	ds_read_b128 v[204:207], v149 offset:16384
	ds_read_b128 v[208:211], v149 offset:17408
	ds_read_b128 v[212:215], v149 offset:18432
	ds_read_b128 v[216:219], v149 offset:19456
	ds_read_b128 v[220:223], v149 offset:20480
	ds_read_b128 v[224:227], v149 offset:21504
	ds_read_b128 v[228:231], v149 offset:22528
	ds_read_b128 v[232:235], v149 offset:23552
	global_load_lds_dwordx4 v[144:145], off
	s_add_i32 m0, s24, 0x2000
	s_add_u32 s38, s42, 0xb0000
	v_lshl_add_u64 v[154:155], s[42:43], 0, v[134:135]
	s_addc_u32 s39, s43, 0
	s_add_i32 s24, s25, s20
	global_load_lds_dwordx4 v[154:155], off
	v_lshl_add_u64 v[192:193], s[38:39], 0, v[2:3]
	s_mov_b32 m0, s24
	v_lshl_add_u64 v[236:237], s[44:45], 0, v[132:133]
	global_load_lds_dwordx4 v[192:193], off
	v_lshl_add_u64 v[192:193], s[38:39], 0, v[134:135]
	s_add_i32 m0, s24, 0x2000
	s_nop 0
	global_load_lds_dwordx4 v[192:193], off
	v_lshl_add_u64 v[192:193], s[44:45], 0, v[0:1]
	s_mov_b32 m0, s21
	s_nop 0
	global_load_lds_dwordx4 v[192:193], off
	s_mov_b32 m0, s22
	s_nop 0
	global_load_lds_dwordx4 v[236:237], off
	s_waitcnt vmcnt(8)
	s_waitcnt lgkmcnt(0)
	s_barrier
	s_setprio 1
	s_waitcnt lgkmcnt(0)
	v_mfma_f32_16x16x32_bf16 v[64:67], v[140:143], v[204:207], 0
	v_mfma_f32_16x16x32_bf16 v[60:63], v[172:175], v[204:207], 0
	v_mfma_f32_16x16x32_bf16 v[48:51], v[140:143], v[212:215], 0
	v_mfma_f32_16x16x32_bf16 v[44:47], v[172:175], v[212:215], 0
	v_mfma_f32_16x16x32_bf16 v[32:35], v[140:143], v[220:223], 0
	v_mfma_f32_16x16x32_bf16 v[28:31], v[172:175], v[220:223], 0
	v_mfma_f32_16x16x32_bf16 v[16:19], v[140:143], v[228:231], 0
	v_mfma_f32_16x16x32_bf16 v[12:15], v[172:175], v[228:231], 0
	v_mfma_f32_16x16x32_bf16 v[64:67], v[150:153], v[208:211], v[64:67]
	v_mfma_f32_16x16x32_bf16 v[60:63], v[176:179], v[208:211], v[60:63]
	v_mfma_f32_16x16x32_bf16 v[48:51], v[150:153], v[216:219], v[48:51]
	v_mfma_f32_16x16x32_bf16 v[44:47], v[176:179], v[216:219], v[44:47]
	v_mfma_f32_16x16x32_bf16 v[32:35], v[150:153], v[224:227], v[32:35]
	v_mfma_f32_16x16x32_bf16 v[28:31], v[176:179], v[224:227], v[28:31]
	v_mfma_f32_16x16x32_bf16 v[16:19], v[150:153], v[232:235], v[16:19]
	v_mfma_f32_16x16x32_bf16 v[12:15], v[176:179], v[232:235], v[12:15]
	s_setprio 0
	s_setprio 1
	v_mfma_f32_16x16x32_bf16 v[56:59], v[180:183], v[204:207], 0
	v_mfma_f32_16x16x32_bf16 v[52:55], v[188:191], v[204:207], 0
	v_mfma_f32_16x16x32_bf16 v[40:43], v[180:183], v[212:215], 0
	v_mfma_f32_16x16x32_bf16 v[36:39], v[188:191], v[212:215], 0
	v_mfma_f32_16x16x32_bf16 v[24:27], v[180:183], v[220:223], 0
	v_mfma_f32_16x16x32_bf16 v[20:23], v[188:191], v[220:223], 0
	v_mfma_f32_16x16x32_bf16 v[8:11], v[180:183], v[228:231], 0
	v_mfma_f32_16x16x32_bf16 v[4:7], v[188:191], v[228:231], 0
	v_mfma_f32_16x16x32_bf16 v[56:59], v[184:187], v[208:211], v[56:59]
	v_mfma_f32_16x16x32_bf16 v[52:55], v[200:203], v[208:211], v[52:55]
	v_mfma_f32_16x16x32_bf16 v[40:43], v[184:187], v[216:219], v[40:43]
	v_mfma_f32_16x16x32_bf16 v[36:39], v[200:203], v[216:219], v[36:39]
	v_mfma_f32_16x16x32_bf16 v[24:27], v[184:187], v[224:227], v[24:27]
	v_mfma_f32_16x16x32_bf16 v[20:23], v[200:203], v[224:227], v[20:23]
	v_mfma_f32_16x16x32_bf16 v[8:11], v[184:187], v[232:235], v[8:11]
	v_mfma_f32_16x16x32_bf16 v[4:7], v[200:203], v[232:235], v[4:7]
	s_setprio 0
	s_barrier
	s_add_i32 s24, 0, 0x18000
	s_add_i32 s25, 0, 0x1c000
	v_add_u32_e32 v176, s24, v147
	v_add_u32_e32 v199, s25, v147
	ds_read_b128 v[140:143], v176
	ds_read_b128 v[150:153], v176 offset:1024
	ds_read_b128 v[172:175], v176 offset:2048
	ds_read_b128 v[176:179], v176 offset:3072
	ds_read_b128 v[180:183], v199
	ds_read_b128 v[184:187], v199 offset:1024
	ds_read_b128 v[188:191], v199 offset:2048
	ds_read_b128 v[200:203], v199 offset:3072
	s_add_u32 s38, s44, 0xb0000
	s_addc_u32 s39, s45, 0
	s_mov_b32 m0, s23
	v_lshl_add_u64 v[238:239], s[38:39], 0, v[0:1]
	ds_read_b128 v[204:207], v149 offset:32768
	ds_read_b128 v[208:211], v149 offset:33792
	ds_read_b128 v[212:215], v149 offset:34816
	ds_read_b128 v[216:219], v149 offset:35840
	ds_read_b128 v[220:223], v149 offset:36864
	ds_read_b128 v[224:227], v149 offset:37888
	ds_read_b128 v[228:231], v149 offset:38912
	ds_read_b128 v[232:235], v149 offset:39936
	global_load_lds_dwordx4 v[238:239], off
	v_lshl_add_u64 v[238:239], s[38:39], 0, v[132:133]
	s_mov_b32 m0, s36
	s_nop 0
	global_load_lds_dwordx4 v[238:239], off
	s_waitcnt vmcnt(8)
	s_waitcnt lgkmcnt(0)
	s_barrier
	s_setprio 1
	s_waitcnt lgkmcnt(0)
	v_mfma_f32_16x16x32_bf16 v[128:131], v[140:143], v[204:207], v[128:131]
	v_mfma_f32_16x16x32_bf16 v[124:127], v[172:175], v[204:207], v[124:127]
	v_mfma_f32_16x16x32_bf16 v[112:115], v[140:143], v[212:215], v[112:115]
	v_mfma_f32_16x16x32_bf16 v[108:111], v[172:175], v[212:215], v[108:111]
	v_mfma_f32_16x16x32_bf16 v[96:99], v[140:143], v[220:223], v[96:99]
	v_mfma_f32_16x16x32_bf16 v[92:95], v[172:175], v[220:223], v[92:95]
	v_mfma_f32_16x16x32_bf16 v[80:83], v[140:143], v[228:231], v[80:83]
	v_mfma_f32_16x16x32_bf16 v[76:79], v[172:175], v[228:231], v[76:79]
	v_mfma_f32_16x16x32_bf16 v[128:131], v[150:153], v[208:211], v[128:131]
	v_mfma_f32_16x16x32_bf16 v[124:127], v[176:179], v[208:211], v[124:127]
	v_mfma_f32_16x16x32_bf16 v[112:115], v[150:153], v[216:219], v[112:115]
	v_mfma_f32_16x16x32_bf16 v[108:111], v[176:179], v[216:219], v[108:111]
	v_mfma_f32_16x16x32_bf16 v[96:99], v[150:153], v[224:227], v[96:99]
	v_mfma_f32_16x16x32_bf16 v[92:95], v[176:179], v[224:227], v[92:95]
	v_mfma_f32_16x16x32_bf16 v[80:83], v[150:153], v[232:235], v[80:83]
	v_mfma_f32_16x16x32_bf16 v[76:79], v[176:179], v[232:235], v[76:79]
	s_setprio 0
	s_setprio 1
	v_mfma_f32_16x16x32_bf16 v[120:123], v[180:183], v[204:207], v[120:123]
	v_mfma_f32_16x16x32_bf16 v[116:119], v[188:191], v[204:207], v[116:119]
	v_mfma_f32_16x16x32_bf16 v[104:107], v[180:183], v[212:215], v[104:107]
	v_mfma_f32_16x16x32_bf16 v[100:103], v[188:191], v[212:215], v[100:103]
	v_mfma_f32_16x16x32_bf16 v[88:91], v[180:183], v[220:223], v[88:91]
	v_mfma_f32_16x16x32_bf16 v[84:87], v[188:191], v[220:223], v[84:87]
	v_mfma_f32_16x16x32_bf16 v[72:75], v[180:183], v[228:231], v[72:75]
	v_mfma_f32_16x16x32_bf16 v[68:71], v[188:191], v[228:231], v[68:71]
	v_mfma_f32_16x16x32_bf16 v[120:123], v[184:187], v[208:211], v[120:123]
	v_mfma_f32_16x16x32_bf16 v[116:119], v[200:203], v[208:211], v[116:119]
	v_mfma_f32_16x16x32_bf16 v[104:107], v[184:187], v[216:219], v[104:107]
	v_mfma_f32_16x16x32_bf16 v[100:103], v[200:203], v[216:219], v[100:103]
	v_mfma_f32_16x16x32_bf16 v[88:91], v[184:187], v[224:227], v[88:91]
	v_mfma_f32_16x16x32_bf16 v[84:87], v[200:203], v[224:227], v[84:87]
	v_mfma_f32_16x16x32_bf16 v[72:75], v[184:187], v[232:235], v[72:75]
	v_mfma_f32_16x16x32_bf16 v[68:71], v[200:203], v[232:235], v[68:71]
	s_setprio 0
	s_barrier
	s_add_i32 s24, s24, s20
	v_lshl_add_u64 v[144:145], v[144:145], 0, s[26:27]
	s_mov_b32 m0, s24
	ds_read_b128 v[204:207], v149 offset:49152
	ds_read_b128 v[208:211], v149 offset:50176
	ds_read_b128 v[212:215], v149 offset:51200
	ds_read_b128 v[216:219], v149 offset:52224
	ds_read_b128 v[220:223], v149 offset:53248
	ds_read_b128 v[224:227], v149 offset:54272
	ds_read_b128 v[228:231], v149 offset:55296
	ds_read_b128 v[232:235], v149 offset:56320
	global_load_lds_dwordx4 v[144:145], off
	s_add_i32 m0, s24, 0x2000
	s_add_u32 s38, s42, 0xb0080
	v_lshl_add_u64 v[144:145], v[154:155], 0, s[26:27]
	s_addc_u32 s39, s43, 0
	s_add_i32 s24, s25, s20
	global_load_lds_dwordx4 v[144:145], off
	v_lshl_add_u64 v[144:145], s[38:39], 0, v[2:3]
	s_mov_b32 m0, s24
	s_nop 0
	global_load_lds_dwordx4 v[144:145], off
	v_lshl_add_u64 v[144:145], s[38:39], 0, v[134:135]
	s_add_i32 m0, s24, 0x2000
	s_nop 0
	global_load_lds_dwordx4 v[144:145], off
	v_lshl_add_u64 v[144:145], v[192:193], 0, s[26:27]
	s_mov_b32 m0, s46
	s_nop 0
	global_load_lds_dwordx4 v[144:145], off
	v_lshl_add_u64 v[144:145], v[236:237], 0, s[26:27]
	s_mov_b32 m0, s47
	s_nop 0
	global_load_lds_dwordx4 v[144:145], off
	s_waitcnt vmcnt(8)
	s_waitcnt lgkmcnt(0)
	s_barrier
	s_setprio 1
	s_waitcnt lgkmcnt(0)
	v_mfma_f32_16x16x32_bf16 v[64:67], v[140:143], v[204:207], v[64:67]
	v_mfma_f32_16x16x32_bf16 v[60:63], v[172:175], v[204:207], v[60:63]
	v_mfma_f32_16x16x32_bf16 v[48:51], v[140:143], v[212:215], v[48:51]
	v_mfma_f32_16x16x32_bf16 v[44:47], v[172:175], v[212:215], v[44:47]
	v_mfma_f32_16x16x32_bf16 v[32:35], v[140:143], v[220:223], v[32:35]
	v_mfma_f32_16x16x32_bf16 v[28:31], v[172:175], v[220:223], v[28:31]
	v_mfma_f32_16x16x32_bf16 v[16:19], v[140:143], v[228:231], v[16:19]
	v_mfma_f32_16x16x32_bf16 v[12:15], v[172:175], v[228:231], v[12:15]
	v_mfma_f32_16x16x32_bf16 v[64:67], v[150:153], v[208:211], v[64:67]
	v_mfma_f32_16x16x32_bf16 v[60:63], v[176:179], v[208:211], v[60:63]
	v_mfma_f32_16x16x32_bf16 v[48:51], v[150:153], v[216:219], v[48:51]
	v_mfma_f32_16x16x32_bf16 v[44:47], v[176:179], v[216:219], v[44:47]
	v_mfma_f32_16x16x32_bf16 v[32:35], v[150:153], v[224:227], v[32:35]
	v_mfma_f32_16x16x32_bf16 v[28:31], v[176:179], v[224:227], v[28:31]
	v_mfma_f32_16x16x32_bf16 v[16:19], v[150:153], v[232:235], v[16:19]
	v_mfma_f32_16x16x32_bf16 v[12:15], v[176:179], v[232:235], v[12:15]
	s_setprio 0
	s_setprio 1
	v_mfma_f32_16x16x32_bf16 v[56:59], v[180:183], v[204:207], v[56:59]
	v_mfma_f32_16x16x32_bf16 v[52:55], v[188:191], v[204:207], v[52:55]
	v_mfma_f32_16x16x32_bf16 v[40:43], v[180:183], v[212:215], v[40:43]
	v_mfma_f32_16x16x32_bf16 v[36:39], v[188:191], v[212:215], v[36:39]
	v_mfma_f32_16x16x32_bf16 v[24:27], v[180:183], v[220:223], v[24:27]
	v_mfma_f32_16x16x32_bf16 v[20:23], v[188:191], v[220:223], v[20:23]
	v_mfma_f32_16x16x32_bf16 v[8:11], v[180:183], v[228:231], v[8:11]
	v_mfma_f32_16x16x32_bf16 v[4:7], v[188:191], v[228:231], v[4:7]
	v_mfma_f32_16x16x32_bf16 v[56:59], v[184:187], v[208:211], v[56:59]
	v_mfma_f32_16x16x32_bf16 v[52:55], v[200:203], v[208:211], v[52:55]
	v_mfma_f32_16x16x32_bf16 v[40:43], v[184:187], v[216:219], v[40:43]
	v_mfma_f32_16x16x32_bf16 v[36:39], v[200:203], v[216:219], v[36:39]
	v_mfma_f32_16x16x32_bf16 v[24:27], v[184:187], v[224:227], v[24:27]
	v_mfma_f32_16x16x32_bf16 v[20:23], v[200:203], v[224:227], v[20:23]
	v_mfma_f32_16x16x32_bf16 v[8:11], v[184:187], v[232:235], v[8:11]
	v_mfma_f32_16x16x32_bf16 v[4:7], v[200:203], v[232:235], v[4:7]
	s_setprio 0
	s_barrier
	s_add_i32 s61, s61, 2
	s_add_u32 s55, s55, 0x100
	s_addc_u32 s60, s60, 0
	s_cmp_gt_u32 s61, 41
	s_mov_b64 s[38:39], s[14:15]
	s_cbranch_scc0 .LBB0_1044
	s_branch .Lpeel_exit_G4
.LBB0_1044:
	s_add_u32 s14, s38, 0x100
	s_addc_u32 s15, s39, 0
	s_add_i32 s24, 0, 0x10000
	s_cmp_eq_u32 s61, 40
	s_cselect_b32 s45, s13, s15
	s_cselect_b32 s44, s12, s14
	v_add_u32_e32 v144, s24, v147
	s_cselect_b32 s43, s29, s60
	s_cselect_b32 s42, s28, s55
	s_add_i32 s25, 0, 0x14000
	ds_read_b128 v[140:143], v144
	ds_read_b128 v[150:153], v144 offset:1024
	ds_read_b128 v[172:175], v144 offset:2048
	ds_read_b128 v[176:179], v144 offset:3072
	v_add_u32_e32 v144, s25, v147
	ds_read_b128 v[180:183], v144
	ds_read_b128 v[184:187], v144 offset:1024
	ds_read_b128 v[188:191], v144 offset:2048
	ds_read_b128 v[200:203], v144 offset:3072
	v_lshl_add_u64 v[144:145], s[38:39], 0, v[138:139]
	s_add_i32 m0, s21, 0xc000
	ds_read_b128 v[204:207], v149
	ds_read_b128 v[208:211], v149 offset:1024
	ds_read_b128 v[212:215], v149 offset:2048
	ds_read_b128 v[216:219], v149 offset:3072
	ds_read_b128 v[220:223], v149 offset:4096
	ds_read_b128 v[224:227], v149 offset:5120
	ds_read_b128 v[228:231], v149 offset:6144
	ds_read_b128 v[232:235], v149 offset:7168
	global_load_lds_dwordx4 v[144:145], off
	v_lshl_add_u64 v[144:145], s[38:39], 0, v[136:137]
	s_add_i32 m0, s21, 0xe000
	s_nop 0
	global_load_lds_dwordx4 v[144:145], off
	s_waitcnt vmcnt(8)
	s_waitcnt lgkmcnt(0)
	s_barrier
	s_setprio 1
	s_waitcnt lgkmcnt(0)
	v_mfma_f32_16x16x32_bf16 v[128:131], v[140:143], v[204:207], v[128:131]
	v_mfma_f32_16x16x32_bf16 v[124:127], v[172:175], v[204:207], v[124:127]
	v_mfma_f32_16x16x32_bf16 v[112:115], v[140:143], v[212:215], v[112:115]
	v_mfma_f32_16x16x32_bf16 v[108:111], v[172:175], v[212:215], v[108:111]
	v_mfma_f32_16x16x32_bf16 v[96:99], v[140:143], v[220:223], v[96:99]
	v_mfma_f32_16x16x32_bf16 v[92:95], v[172:175], v[220:223], v[92:95]
	v_mfma_f32_16x16x32_bf16 v[80:83], v[140:143], v[228:231], v[80:83]
	v_mfma_f32_16x16x32_bf16 v[76:79], v[172:175], v[228:231], v[76:79]
	v_mfma_f32_16x16x32_bf16 v[128:131], v[150:153], v[208:211], v[128:131]
	v_mfma_f32_16x16x32_bf16 v[124:127], v[176:179], v[208:211], v[124:127]
	v_mfma_f32_16x16x32_bf16 v[112:115], v[150:153], v[216:219], v[112:115]
	v_mfma_f32_16x16x32_bf16 v[108:111], v[176:179], v[216:219], v[108:111]
	v_mfma_f32_16x16x32_bf16 v[96:99], v[150:153], v[224:227], v[96:99]
	v_mfma_f32_16x16x32_bf16 v[92:95], v[176:179], v[224:227], v[92:95]
	v_mfma_f32_16x16x32_bf16 v[80:83], v[150:153], v[232:235], v[80:83]
	v_mfma_f32_16x16x32_bf16 v[76:79], v[176:179], v[232:235], v[76:79]
	s_setprio 0
	s_setprio 1
	v_mfma_f32_16x16x32_bf16 v[120:123], v[180:183], v[204:207], v[120:123]
	v_mfma_f32_16x16x32_bf16 v[116:119], v[188:191], v[204:207], v[116:119]
	v_mfma_f32_16x16x32_bf16 v[104:107], v[180:183], v[212:215], v[104:107]
	v_mfma_f32_16x16x32_bf16 v[100:103], v[188:191], v[212:215], v[100:103]
	v_mfma_f32_16x16x32_bf16 v[88:91], v[180:183], v[220:223], v[88:91]
	v_mfma_f32_16x16x32_bf16 v[84:87], v[188:191], v[220:223], v[84:87]
	v_mfma_f32_16x16x32_bf16 v[72:75], v[180:183], v[228:231], v[72:75]
	v_mfma_f32_16x16x32_bf16 v[68:71], v[188:191], v[228:231], v[68:71]
	v_mfma_f32_16x16x32_bf16 v[120:123], v[184:187], v[208:211], v[120:123]
	v_mfma_f32_16x16x32_bf16 v[116:119], v[200:203], v[208:211], v[116:119]
	v_mfma_f32_16x16x32_bf16 v[104:107], v[184:187], v[216:219], v[104:107]
	v_mfma_f32_16x16x32_bf16 v[100:103], v[200:203], v[216:219], v[100:103]
	v_mfma_f32_16x16x32_bf16 v[88:91], v[184:187], v[224:227], v[88:91]
	v_mfma_f32_16x16x32_bf16 v[84:87], v[200:203], v[224:227], v[84:87]
	v_mfma_f32_16x16x32_bf16 v[72:75], v[184:187], v[232:235], v[72:75]
	v_mfma_f32_16x16x32_bf16 v[68:71], v[200:203], v[232:235], v[68:71]
	s_setprio 0
	s_barrier
	s_add_i32 s24, s24, s20
	v_lshl_add_u64 v[144:145], s[42:43], 0, v[2:3]
	s_mov_b32 m0, s24
	ds_read_b128 v[204:207], v149 offset:16384
	ds_read_b128 v[208:211], v149 offset:17408
	ds_read_b128 v[212:215], v149 offset:18432
	ds_read_b128 v[216:219], v149 offset:19456
	ds_read_b128 v[220:223], v149 offset:20480
	ds_read_b128 v[224:227], v149 offset:21504
	ds_read_b128 v[228:231], v149 offset:22528
	ds_read_b128 v[232:235], v149 offset:23552
	global_load_lds_dwordx4 v[144:145], off
	s_add_i32 m0, s24, 0x2000
	s_add_u32 s38, s42, 0xb0000
	v_lshl_add_u64 v[154:155], s[42:43], 0, v[134:135]
	s_addc_u32 s39, s43, 0
	s_add_i32 s24, s25, s20
	global_load_lds_dwordx4 v[154:155], off
	v_lshl_add_u64 v[192:193], s[38:39], 0, v[2:3]
	s_mov_b32 m0, s24
	v_lshl_add_u64 v[236:237], s[44:45], 0, v[132:133]
	global_load_lds_dwordx4 v[192:193], off
	v_lshl_add_u64 v[192:193], s[38:39], 0, v[134:135]
	s_add_i32 m0, s24, 0x2000
	s_nop 0
	global_load_lds_dwordx4 v[192:193], off
	v_lshl_add_u64 v[192:193], s[44:45], 0, v[0:1]
	s_mov_b32 m0, s21
	s_nop 0
	global_load_lds_dwordx4 v[192:193], off
	s_mov_b32 m0, s22
	s_nop 0
	global_load_lds_dwordx4 v[236:237], off
	s_waitcnt vmcnt(8)
	s_waitcnt lgkmcnt(0)
	s_barrier
	s_setprio 1
	s_waitcnt lgkmcnt(0)
	v_mfma_f32_16x16x32_bf16 v[64:67], v[140:143], v[204:207], v[64:67]
	v_mfma_f32_16x16x32_bf16 v[60:63], v[172:175], v[204:207], v[60:63]
	v_mfma_f32_16x16x32_bf16 v[48:51], v[140:143], v[212:215], v[48:51]
	v_mfma_f32_16x16x32_bf16 v[44:47], v[172:175], v[212:215], v[44:47]
	v_mfma_f32_16x16x32_bf16 v[32:35], v[140:143], v[220:223], v[32:35]
	v_mfma_f32_16x16x32_bf16 v[28:31], v[172:175], v[220:223], v[28:31]
	v_mfma_f32_16x16x32_bf16 v[16:19], v[140:143], v[228:231], v[16:19]
	v_mfma_f32_16x16x32_bf16 v[12:15], v[172:175], v[228:231], v[12:15]
	v_mfma_f32_16x16x32_bf16 v[64:67], v[150:153], v[208:211], v[64:67]
	v_mfma_f32_16x16x32_bf16 v[60:63], v[176:179], v[208:211], v[60:63]
	v_mfma_f32_16x16x32_bf16 v[48:51], v[150:153], v[216:219], v[48:51]
	v_mfma_f32_16x16x32_bf16 v[44:47], v[176:179], v[216:219], v[44:47]
	v_mfma_f32_16x16x32_bf16 v[32:35], v[150:153], v[224:227], v[32:35]
	v_mfma_f32_16x16x32_bf16 v[28:31], v[176:179], v[224:227], v[28:31]
	v_mfma_f32_16x16x32_bf16 v[16:19], v[150:153], v[232:235], v[16:19]
	v_mfma_f32_16x16x32_bf16 v[12:15], v[176:179], v[232:235], v[12:15]
	s_setprio 0
	s_setprio 1
	v_mfma_f32_16x16x32_bf16 v[56:59], v[180:183], v[204:207], v[56:59]
	v_mfma_f32_16x16x32_bf16 v[52:55], v[188:191], v[204:207], v[52:55]
	v_mfma_f32_16x16x32_bf16 v[40:43], v[180:183], v[212:215], v[40:43]
	v_mfma_f32_16x16x32_bf16 v[36:39], v[188:191], v[212:215], v[36:39]
	v_mfma_f32_16x16x32_bf16 v[24:27], v[180:183], v[220:223], v[24:27]
	v_mfma_f32_16x16x32_bf16 v[20:23], v[188:191], v[220:223], v[20:23]
	v_mfma_f32_16x16x32_bf16 v[8:11], v[180:183], v[228:231], v[8:11]
	v_mfma_f32_16x16x32_bf16 v[4:7], v[188:191], v[228:231], v[4:7]
	v_mfma_f32_16x16x32_bf16 v[56:59], v[184:187], v[208:211], v[56:59]
	v_mfma_f32_16x16x32_bf16 v[52:55], v[200:203], v[208:211], v[52:55]
	v_mfma_f32_16x16x32_bf16 v[40:43], v[184:187], v[216:219], v[40:43]
	v_mfma_f32_16x16x32_bf16 v[36:39], v[200:203], v[216:219], v[36:39]
	v_mfma_f32_16x16x32_bf16 v[24:27], v[184:187], v[224:227], v[24:27]
	v_mfma_f32_16x16x32_bf16 v[20:23], v[200:203], v[224:227], v[20:23]
	v_mfma_f32_16x16x32_bf16 v[8:11], v[184:187], v[232:235], v[8:11]
	v_mfma_f32_16x16x32_bf16 v[4:7], v[200:203], v[232:235], v[4:7]
	s_setprio 0
	s_barrier
	s_add_i32 s24, 0, 0x18000
	s_add_i32 s25, 0, 0x1c000
	v_add_u32_e32 v176, s24, v147
	v_add_u32_e32 v199, s25, v147
	ds_read_b128 v[140:143], v176
	ds_read_b128 v[150:153], v176 offset:1024
	ds_read_b128 v[172:175], v176 offset:2048
	ds_read_b128 v[176:179], v176 offset:3072
	ds_read_b128 v[180:183], v199
	ds_read_b128 v[184:187], v199 offset:1024
	ds_read_b128 v[188:191], v199 offset:2048
	ds_read_b128 v[200:203], v199 offset:3072
	s_add_u32 s38, s44, 0xb0000
	s_addc_u32 s39, s45, 0
	s_mov_b32 m0, s23
	v_lshl_add_u64 v[238:239], s[38:39], 0, v[0:1]
	ds_read_b128 v[204:207], v149 offset:32768
	ds_read_b128 v[208:211], v149 offset:33792
	ds_read_b128 v[212:215], v149 offset:34816
	ds_read_b128 v[216:219], v149 offset:35840
	ds_read_b128 v[220:223], v149 offset:36864
	ds_read_b128 v[224:227], v149 offset:37888
	ds_read_b128 v[228:231], v149 offset:38912
	ds_read_b128 v[232:235], v149 offset:39936
	global_load_lds_dwordx4 v[238:239], off
	v_lshl_add_u64 v[238:239], s[38:39], 0, v[132:133]
	s_mov_b32 m0, s36
	s_nop 0
	global_load_lds_dwordx4 v[238:239], off
	s_waitcnt vmcnt(8)
	s_waitcnt lgkmcnt(0)
	s_barrier
	s_setprio 1
	s_waitcnt lgkmcnt(0)
	v_mfma_f32_16x16x32_bf16 v[128:131], v[140:143], v[204:207], v[128:131]
	v_mfma_f32_16x16x32_bf16 v[124:127], v[172:175], v[204:207], v[124:127]
	v_mfma_f32_16x16x32_bf16 v[112:115], v[140:143], v[212:215], v[112:115]
	v_mfma_f32_16x16x32_bf16 v[108:111], v[172:175], v[212:215], v[108:111]
	v_mfma_f32_16x16x32_bf16 v[96:99], v[140:143], v[220:223], v[96:99]
	v_mfma_f32_16x16x32_bf16 v[92:95], v[172:175], v[220:223], v[92:95]
	v_mfma_f32_16x16x32_bf16 v[80:83], v[140:143], v[228:231], v[80:83]
	v_mfma_f32_16x16x32_bf16 v[76:79], v[172:175], v[228:231], v[76:79]
	v_mfma_f32_16x16x32_bf16 v[128:131], v[150:153], v[208:211], v[128:131]
	v_mfma_f32_16x16x32_bf16 v[124:127], v[176:179], v[208:211], v[124:127]
	v_mfma_f32_16x16x32_bf16 v[112:115], v[150:153], v[216:219], v[112:115]
	v_mfma_f32_16x16x32_bf16 v[108:111], v[176:179], v[216:219], v[108:111]
	v_mfma_f32_16x16x32_bf16 v[96:99], v[150:153], v[224:227], v[96:99]
	v_mfma_f32_16x16x32_bf16 v[92:95], v[176:179], v[224:227], v[92:95]
	v_mfma_f32_16x16x32_bf16 v[80:83], v[150:153], v[232:235], v[80:83]
	v_mfma_f32_16x16x32_bf16 v[76:79], v[176:179], v[232:235], v[76:79]
	s_setprio 0
	s_setprio 1
	v_mfma_f32_16x16x32_bf16 v[120:123], v[180:183], v[204:207], v[120:123]
	v_mfma_f32_16x16x32_bf16 v[116:119], v[188:191], v[204:207], v[116:119]
	v_mfma_f32_16x16x32_bf16 v[104:107], v[180:183], v[212:215], v[104:107]
	v_mfma_f32_16x16x32_bf16 v[100:103], v[188:191], v[212:215], v[100:103]
	v_mfma_f32_16x16x32_bf16 v[88:91], v[180:183], v[220:223], v[88:91]
	v_mfma_f32_16x16x32_bf16 v[84:87], v[188:191], v[220:223], v[84:87]
	v_mfma_f32_16x16x32_bf16 v[72:75], v[180:183], v[228:231], v[72:75]
	v_mfma_f32_16x16x32_bf16 v[68:71], v[188:191], v[228:231], v[68:71]
	v_mfma_f32_16x16x32_bf16 v[120:123], v[184:187], v[208:211], v[120:123]
	v_mfma_f32_16x16x32_bf16 v[116:119], v[200:203], v[208:211], v[116:119]
	v_mfma_f32_16x16x32_bf16 v[104:107], v[184:187], v[216:219], v[104:107]
	v_mfma_f32_16x16x32_bf16 v[100:103], v[200:203], v[216:219], v[100:103]
	v_mfma_f32_16x16x32_bf16 v[88:91], v[184:187], v[224:227], v[88:91]
	v_mfma_f32_16x16x32_bf16 v[84:87], v[200:203], v[224:227], v[84:87]
	v_mfma_f32_16x16x32_bf16 v[72:75], v[184:187], v[232:235], v[72:75]
	v_mfma_f32_16x16x32_bf16 v[68:71], v[200:203], v[232:235], v[68:71]
	s_setprio 0
	s_barrier
	s_add_i32 s24, s24, s20
	v_lshl_add_u64 v[144:145], v[144:145], 0, s[26:27]
	s_mov_b32 m0, s24
	ds_read_b128 v[204:207], v149 offset:49152
	ds_read_b128 v[208:211], v149 offset:50176
	ds_read_b128 v[212:215], v149 offset:51200
	ds_read_b128 v[216:219], v149 offset:52224
	ds_read_b128 v[220:223], v149 offset:53248
	ds_read_b128 v[224:227], v149 offset:54272
	ds_read_b128 v[228:231], v149 offset:55296
	ds_read_b128 v[232:235], v149 offset:56320
	global_load_lds_dwordx4 v[144:145], off
	s_add_i32 m0, s24, 0x2000
	s_add_u32 s38, s42, 0xb0080
	v_lshl_add_u64 v[144:145], v[154:155], 0, s[26:27]
	s_addc_u32 s39, s43, 0
	s_add_i32 s24, s25, s20
	global_load_lds_dwordx4 v[144:145], off
	v_lshl_add_u64 v[144:145], s[38:39], 0, v[2:3]
	s_mov_b32 m0, s24
	s_nop 0
	global_load_lds_dwordx4 v[144:145], off
	v_lshl_add_u64 v[144:145], s[38:39], 0, v[134:135]
	s_add_i32 m0, s24, 0x2000
	s_nop 0
	global_load_lds_dwordx4 v[144:145], off
	v_lshl_add_u64 v[144:145], v[192:193], 0, s[26:27]
	s_mov_b32 m0, s46
	s_nop 0
	global_load_lds_dwordx4 v[144:145], off
	v_lshl_add_u64 v[144:145], v[236:237], 0, s[26:27]
	s_mov_b32 m0, s47
	s_nop 0
	global_load_lds_dwordx4 v[144:145], off
	s_waitcnt vmcnt(8)
	s_waitcnt lgkmcnt(0)
	s_barrier
	s_setprio 1
	s_waitcnt lgkmcnt(0)
	v_mfma_f32_16x16x32_bf16 v[64:67], v[140:143], v[204:207], v[64:67]
	v_mfma_f32_16x16x32_bf16 v[60:63], v[172:175], v[204:207], v[60:63]
	v_mfma_f32_16x16x32_bf16 v[48:51], v[140:143], v[212:215], v[48:51]
	v_mfma_f32_16x16x32_bf16 v[44:47], v[172:175], v[212:215], v[44:47]
	v_mfma_f32_16x16x32_bf16 v[32:35], v[140:143], v[220:223], v[32:35]
	v_mfma_f32_16x16x32_bf16 v[28:31], v[172:175], v[220:223], v[28:31]
	v_mfma_f32_16x16x32_bf16 v[16:19], v[140:143], v[228:231], v[16:19]
	v_mfma_f32_16x16x32_bf16 v[12:15], v[172:175], v[228:231], v[12:15]
	v_mfma_f32_16x16x32_bf16 v[64:67], v[150:153], v[208:211], v[64:67]
	v_mfma_f32_16x16x32_bf16 v[60:63], v[176:179], v[208:211], v[60:63]
	v_mfma_f32_16x16x32_bf16 v[48:51], v[150:153], v[216:219], v[48:51]
	v_mfma_f32_16x16x32_bf16 v[44:47], v[176:179], v[216:219], v[44:47]
	v_mfma_f32_16x16x32_bf16 v[32:35], v[150:153], v[224:227], v[32:35]
	v_mfma_f32_16x16x32_bf16 v[28:31], v[176:179], v[224:227], v[28:31]
	v_mfma_f32_16x16x32_bf16 v[16:19], v[150:153], v[232:235], v[16:19]
	v_mfma_f32_16x16x32_bf16 v[12:15], v[176:179], v[232:235], v[12:15]
	s_setprio 0
	s_setprio 1
	v_mfma_f32_16x16x32_bf16 v[56:59], v[180:183], v[204:207], v[56:59]
	v_mfma_f32_16x16x32_bf16 v[52:55], v[188:191], v[204:207], v[52:55]
	v_mfma_f32_16x16x32_bf16 v[40:43], v[180:183], v[212:215], v[40:43]
	v_mfma_f32_16x16x32_bf16 v[36:39], v[188:191], v[212:215], v[36:39]
	v_mfma_f32_16x16x32_bf16 v[24:27], v[180:183], v[220:223], v[24:27]
	v_mfma_f32_16x16x32_bf16 v[20:23], v[188:191], v[220:223], v[20:23]
	v_mfma_f32_16x16x32_bf16 v[8:11], v[180:183], v[228:231], v[8:11]
	v_mfma_f32_16x16x32_bf16 v[4:7], v[188:191], v[228:231], v[4:7]
	v_mfma_f32_16x16x32_bf16 v[56:59], v[184:187], v[208:211], v[56:59]
	v_mfma_f32_16x16x32_bf16 v[52:55], v[200:203], v[208:211], v[52:55]
	v_mfma_f32_16x16x32_bf16 v[40:43], v[184:187], v[216:219], v[40:43]
	v_mfma_f32_16x16x32_bf16 v[36:39], v[200:203], v[216:219], v[36:39]
	v_mfma_f32_16x16x32_bf16 v[24:27], v[184:187], v[224:227], v[24:27]
	v_mfma_f32_16x16x32_bf16 v[20:23], v[200:203], v[224:227], v[20:23]
	v_mfma_f32_16x16x32_bf16 v[8:11], v[184:187], v[232:235], v[8:11]
	v_mfma_f32_16x16x32_bf16 v[4:7], v[200:203], v[232:235], v[4:7]
	s_setprio 0
	s_barrier
	s_add_i32 s61, s61, 2
	s_add_u32 s55, s55, 0x100
	s_addc_u32 s60, s60, 0
	s_cmp_gt_u32 s61, 41
	s_mov_b64 s[38:39], s[14:15]
	s_cbranch_scc0 .LBB0_1044
.Lpeel_exit_G4:
	s_and_b64 vcc, exec, s[10:11]
	s_cbranch_vccz .LBB0_1047
	s_barrier
.LBB0_1047:
	v_lshl_add_u32 v154, s54, 8, v146
	v_lshl_or_b32 v145, s51, 8, v148
	v_lshl_add_u32 v144, v154, 10, v145
	v_lshlrev_b32_e32 v144, 1, v144
	v_mov_b32_e32 v145, v144
	v_lshlrev_b32_e32 v154, 2, v154
	global_load_dwordx4 v[140:143], v144, s[6:7]
	global_load_dwordx4 v[150:153], v144, s[6:7] offset:256
	v_add_u32_e32 v144, 0x8000, v144
	global_load_dwordx4 v[172:175], v144, s[6:7]
	global_load_dwordx4 v[176:179], v144, s[6:7] offset:256
	v_add_u32_e32 v144, 0x8000, v144
	global_load_dwordx4 v[180:183], v144, s[6:7]
	global_load_dwordx4 v[184:187], v144, s[6:7] offset:256
	v_add_u32_e32 v144, 0x8000, v144
	global_load_dwordx4 v[188:191], v144, s[6:7]
	global_load_dwordx4 v[200:203], v144, s[6:7] offset:256
	v_add_u32_e32 v144, 0x28000, v144
	global_load_dwordx4 v[204:207], v144, s[6:7]
	global_load_dwordx4 v[208:211], v144, s[6:7] offset:256
	v_add_u32_e32 v144, 0x8000, v144
	global_load_dwordx4 v[212:215], v144, s[6:7]
	global_load_dwordx4 v[216:219], v144, s[6:7] offset:256
	v_add_u32_e32 v144, 0x8000, v144
	global_load_dwordx4 v[220:223], v144, s[6:7]
	global_load_dwordx4 v[224:227], v144, s[6:7] offset:256
	v_add_u32_e32 v144, 0x8000, v144
	global_load_dwordx4 v[228:231], v144, s[6:7]
	global_load_dwordx4 v[232:235], v144, s[6:7] offset:256
	v_xor_b32_e32 v155, 16, v197
	v_xor_b32_e32 v192, 32, v197
	v_lshlrev_b32_e32 v155, 2, v155
	v_lshlrev_b32_e32 v192, 2, v192
	s_waitcnt vmcnt(14)
	v_lshlrev_b32_e32 v236, 16, v140
	v_and_b32_e32 v237, 0xffff0000, v140
	v_lshlrev_b32_e32 v238, 16, v141
	v_and_b32_e32 v239, 0xffff0000, v141
	v_lshlrev_b32_e32 v140, 16, v142
	v_and_b32_e32 v141, 0xffff0000, v142
	v_lshlrev_b32_e32 v142, 16, v143
	v_and_b32_e32 v143, 0xffff0000, v143
	v_pk_add_f32 v[128:129], v[128:129], v[236:237]
	v_pk_add_f32 v[130:131], v[130:131], v[238:239]
	v_pk_add_f32 v[124:125], v[124:125], v[140:141]
	v_pk_add_f32 v[126:127], v[126:127], v[142:143]
	v_cvt_pk_bf16_f32 v140, v128, v129
	v_cvt_pk_bf16_f32 v141, v130, v131
	v_cvt_pk_bf16_f32 v142, v124, v125
	v_cvt_pk_bf16_f32 v143, v126, v127
	global_store_dwordx4 v145, v[140:143], s[6:7]
	v_pk_mul_f32 v[128:129], v[128:129], v[128:129]
	v_pk_mul_f32 v[130:131], v[130:131], v[130:131]
	v_pk_fma_f32 v[128:129], v[124:125], v[124:125], v[128:129]
	v_pk_fma_f32 v[130:131], v[126:127], v[126:127], v[130:131]
	v_lshlrev_b32_e32 v236, 16, v150
	v_and_b32_e32 v237, 0xffff0000, v150
	v_lshlrev_b32_e32 v238, 16, v151
	v_and_b32_e32 v239, 0xffff0000, v151
	v_lshlrev_b32_e32 v150, 16, v152
	v_and_b32_e32 v151, 0xffff0000, v152
	v_lshlrev_b32_e32 v152, 16, v153
	v_and_b32_e32 v153, 0xffff0000, v153
	v_pk_add_f32 v[120:121], v[120:121], v[236:237]
	v_pk_add_f32 v[122:123], v[122:123], v[238:239]
	v_pk_add_f32 v[116:117], v[116:117], v[150:151]
	v_pk_add_f32 v[118:119], v[118:119], v[152:153]
	v_cvt_pk_bf16_f32 v150, v120, v121
	v_cvt_pk_bf16_f32 v151, v122, v123
	v_cvt_pk_bf16_f32 v152, v116, v117
	v_cvt_pk_bf16_f32 v153, v118, v119
	global_store_dwordx4 v145, v[150:153], s[6:7] offset:256
	v_pk_fma_f32 v[128:129], v[120:121], v[120:121], v[128:129]
	v_pk_fma_f32 v[130:131], v[122:123], v[122:123], v[130:131]
	v_pk_fma_f32 v[128:129], v[116:117], v[116:117], v[128:129]
	v_pk_fma_f32 v[130:131], v[118:119], v[118:119], v[130:131]
	v_add_u32_e32 v145, 0x8000, v145
	v_add_f32_e32 v128, v128, v129
	v_add_f32_e32 v130, v130, v131
	v_add_f32_e32 v128, v128, v130
	s_waitcnt vmcnt(14)
	v_lshlrev_b32_e32 v236, 16, v172
	v_and_b32_e32 v237, 0xffff0000, v172
	v_lshlrev_b32_e32 v238, 16, v173
	v_and_b32_e32 v239, 0xffff0000, v173
	v_lshlrev_b32_e32 v172, 16, v174
	v_and_b32_e32 v173, 0xffff0000, v174
	v_lshlrev_b32_e32 v174, 16, v175
	v_and_b32_e32 v175, 0xffff0000, v175
	v_pk_add_f32 v[112:113], v[112:113], v[236:237]
	v_pk_add_f32 v[114:115], v[114:115], v[238:239]
	v_pk_add_f32 v[108:109], v[108:109], v[172:173]
	v_pk_add_f32 v[110:111], v[110:111], v[174:175]
	v_cvt_pk_bf16_f32 v172, v112, v113
	v_cvt_pk_bf16_f32 v173, v114, v115
	v_cvt_pk_bf16_f32 v174, v108, v109
	v_cvt_pk_bf16_f32 v175, v110, v111
	global_store_dwordx4 v145, v[172:175], s[6:7]
	v_pk_mul_f32 v[112:113], v[112:113], v[112:113]
	v_pk_mul_f32 v[114:115], v[114:115], v[114:115]
	v_pk_fma_f32 v[112:113], v[108:109], v[108:109], v[112:113]
	v_pk_fma_f32 v[114:115], v[110:111], v[110:111], v[114:115]
	v_lshlrev_b32_e32 v236, 16, v176
	v_and_b32_e32 v237, 0xffff0000, v176
	v_lshlrev_b32_e32 v238, 16, v177
	v_and_b32_e32 v239, 0xffff0000, v177
	v_lshlrev_b32_e32 v176, 16, v178
	v_and_b32_e32 v177, 0xffff0000, v178
	v_lshlrev_b32_e32 v178, 16, v179
	v_and_b32_e32 v179, 0xffff0000, v179
	v_pk_add_f32 v[104:105], v[104:105], v[236:237]
	v_pk_add_f32 v[106:107], v[106:107], v[238:239]
	v_pk_add_f32 v[100:101], v[100:101], v[176:177]
	v_pk_add_f32 v[102:103], v[102:103], v[178:179]
	v_cvt_pk_bf16_f32 v176, v104, v105
	v_cvt_pk_bf16_f32 v177, v106, v107
	v_cvt_pk_bf16_f32 v178, v100, v101
	v_cvt_pk_bf16_f32 v179, v102, v103
	global_store_dwordx4 v145, v[176:179], s[6:7] offset:256
	v_pk_fma_f32 v[112:113], v[104:105], v[104:105], v[112:113]
	v_pk_fma_f32 v[114:115], v[106:107], v[106:107], v[114:115]
	v_pk_fma_f32 v[112:113], v[100:101], v[100:101], v[112:113]
	v_pk_fma_f32 v[114:115], v[102:103], v[102:103], v[114:115]
	v_add_u32_e32 v145, 0x8000, v145
	v_add_f32_e32 v112, v112, v113
	v_add_f32_e32 v114, v114, v115
	v_add_f32_e32 v112, v112, v114
	s_waitcnt vmcnt(14)
	v_lshlrev_b32_e32 v236, 16, v180
	v_and_b32_e32 v237, 0xffff0000, v180
	v_lshlrev_b32_e32 v238, 16, v181
	v_and_b32_e32 v239, 0xffff0000, v181
	v_lshlrev_b32_e32 v180, 16, v182
	v_and_b32_e32 v181, 0xffff0000, v182
	v_lshlrev_b32_e32 v182, 16, v183
	v_and_b32_e32 v183, 0xffff0000, v183
	v_pk_add_f32 v[96:97], v[96:97], v[236:237]
	v_pk_add_f32 v[98:99], v[98:99], v[238:239]
	v_pk_add_f32 v[92:93], v[92:93], v[180:181]
	v_pk_add_f32 v[94:95], v[94:95], v[182:183]
	v_cvt_pk_bf16_f32 v180, v96, v97
	v_cvt_pk_bf16_f32 v181, v98, v99
	v_cvt_pk_bf16_f32 v182, v92, v93
	v_cvt_pk_bf16_f32 v183, v94, v95
	global_store_dwordx4 v145, v[180:183], s[6:7]
	v_pk_mul_f32 v[96:97], v[96:97], v[96:97]
	v_pk_mul_f32 v[98:99], v[98:99], v[98:99]
	v_pk_fma_f32 v[96:97], v[92:93], v[92:93], v[96:97]
	v_pk_fma_f32 v[98:99], v[94:95], v[94:95], v[98:99]
	v_lshlrev_b32_e32 v236, 16, v184
	v_and_b32_e32 v237, 0xffff0000, v184
	v_lshlrev_b32_e32 v238, 16, v185
	v_and_b32_e32 v239, 0xffff0000, v185
	v_lshlrev_b32_e32 v184, 16, v186
	v_and_b32_e32 v185, 0xffff0000, v186
	v_lshlrev_b32_e32 v186, 16, v187
	v_and_b32_e32 v187, 0xffff0000, v187
	v_pk_add_f32 v[88:89], v[88:89], v[236:237]
	v_pk_add_f32 v[90:91], v[90:91], v[238:239]
	v_pk_add_f32 v[84:85], v[84:85], v[184:185]
	v_pk_add_f32 v[86:87], v[86:87], v[186:187]
	v_cvt_pk_bf16_f32 v184, v88, v89
	v_cvt_pk_bf16_f32 v185, v90, v91
	v_cvt_pk_bf16_f32 v186, v84, v85
	v_cvt_pk_bf16_f32 v187, v86, v87
	global_store_dwordx4 v145, v[184:187], s[6:7] offset:256
	v_pk_fma_f32 v[96:97], v[88:89], v[88:89], v[96:97]
	v_pk_fma_f32 v[98:99], v[90:91], v[90:91], v[98:99]
	v_pk_fma_f32 v[96:97], v[84:85], v[84:85], v[96:97]
	v_pk_fma_f32 v[98:99], v[86:87], v[86:87], v[98:99]
	v_add_u32_e32 v145, 0x8000, v145
	v_add_f32_e32 v96, v96, v97
	v_add_f32_e32 v98, v98, v99
	v_add_f32_e32 v96, v96, v98
	s_waitcnt vmcnt(14)
	v_lshlrev_b32_e32 v236, 16, v188
	v_and_b32_e32 v237, 0xffff0000, v188
	v_lshlrev_b32_e32 v238, 16, v189
	v_and_b32_e32 v239, 0xffff0000, v189
	v_lshlrev_b32_e32 v188, 16, v190
	v_and_b32_e32 v189, 0xffff0000, v190
	v_lshlrev_b32_e32 v190, 16, v191
	v_and_b32_e32 v191, 0xffff0000, v191
	v_pk_add_f32 v[80:81], v[80:81], v[236:237]
	v_pk_add_f32 v[82:83], v[82:83], v[238:239]
	v_pk_add_f32 v[76:77], v[76:77], v[188:189]
	v_pk_add_f32 v[78:79], v[78:79], v[190:191]
	v_cvt_pk_bf16_f32 v188, v80, v81
	v_cvt_pk_bf16_f32 v189, v82, v83
	v_cvt_pk_bf16_f32 v190, v76, v77
	v_cvt_pk_bf16_f32 v191, v78, v79
	global_store_dwordx4 v145, v[188:191], s[6:7]
	v_pk_mul_f32 v[80:81], v[80:81], v[80:81]
	v_pk_mul_f32 v[82:83], v[82:83], v[82:83]
	v_pk_fma_f32 v[80:81], v[76:77], v[76:77], v[80:81]
	v_pk_fma_f32 v[82:83], v[78:79], v[78:79], v[82:83]
	v_lshlrev_b32_e32 v236, 16, v200
	v_and_b32_e32 v237, 0xffff0000, v200
	v_lshlrev_b32_e32 v238, 16, v201
	v_and_b32_e32 v239, 0xffff0000, v201
	v_lshlrev_b32_e32 v200, 16, v202
	v_and_b32_e32 v201, 0xffff0000, v202
	v_lshlrev_b32_e32 v202, 16, v203
	v_and_b32_e32 v203, 0xffff0000, v203
	v_pk_add_f32 v[72:73], v[72:73], v[236:237]
	v_pk_add_f32 v[74:75], v[74:75], v[238:239]
	v_pk_add_f32 v[68:69], v[68:69], v[200:201]
	v_pk_add_f32 v[70:71], v[70:71], v[202:203]
	v_cvt_pk_bf16_f32 v200, v72, v73
	v_cvt_pk_bf16_f32 v201, v74, v75
	v_cvt_pk_bf16_f32 v202, v68, v69
	v_cvt_pk_bf16_f32 v203, v70, v71
	global_store_dwordx4 v145, v[200:203], s[6:7] offset:256
	v_pk_fma_f32 v[80:81], v[72:73], v[72:73], v[80:81]
	v_pk_fma_f32 v[82:83], v[74:75], v[74:75], v[82:83]
	v_pk_fma_f32 v[80:81], v[68:69], v[68:69], v[80:81]
	v_pk_fma_f32 v[82:83], v[70:71], v[70:71], v[82:83]
	v_add_u32_e32 v145, 0x28000, v145
	v_add_f32_e32 v80, v80, v81
	v_add_f32_e32 v82, v82, v83
	v_add_f32_e32 v80, v80, v82
	s_waitcnt vmcnt(14)
	v_lshlrev_b32_e32 v236, 16, v204
	v_and_b32_e32 v237, 0xffff0000, v204
	v_lshlrev_b32_e32 v238, 16, v205
	v_and_b32_e32 v239, 0xffff0000, v205
	v_lshlrev_b32_e32 v204, 16, v206
	v_and_b32_e32 v205, 0xffff0000, v206
	v_lshlrev_b32_e32 v206, 16, v207
	v_and_b32_e32 v207, 0xffff0000, v207
	v_pk_add_f32 v[64:65], v[64:65], v[236:237]
	v_pk_add_f32 v[66:67], v[66:67], v[238:239]
	v_pk_add_f32 v[60:61], v[60:61], v[204:205]
	v_pk_add_f32 v[62:63], v[62:63], v[206:207]
	v_cvt_pk_bf16_f32 v204, v64, v65
	v_cvt_pk_bf16_f32 v205, v66, v67
	v_cvt_pk_bf16_f32 v206, v60, v61
	v_cvt_pk_bf16_f32 v207, v62, v63
	global_store_dwordx4 v145, v[204:207], s[6:7]
	v_pk_mul_f32 v[64:65], v[64:65], v[64:65]
	v_pk_mul_f32 v[66:67], v[66:67], v[66:67]
	v_pk_fma_f32 v[64:65], v[60:61], v[60:61], v[64:65]
	v_pk_fma_f32 v[66:67], v[62:63], v[62:63], v[66:67]
	v_lshlrev_b32_e32 v236, 16, v208
	v_and_b32_e32 v237, 0xffff0000, v208
	v_lshlrev_b32_e32 v238, 16, v209
	v_and_b32_e32 v239, 0xffff0000, v209
	v_lshlrev_b32_e32 v208, 16, v210
	v_and_b32_e32 v209, 0xffff0000, v210
	v_lshlrev_b32_e32 v210, 16, v211
	v_and_b32_e32 v211, 0xffff0000, v211
	v_pk_add_f32 v[56:57], v[56:57], v[236:237]
	v_pk_add_f32 v[58:59], v[58:59], v[238:239]
	v_pk_add_f32 v[52:53], v[52:53], v[208:209]
	v_pk_add_f32 v[54:55], v[54:55], v[210:211]
	v_cvt_pk_bf16_f32 v208, v56, v57
	v_cvt_pk_bf16_f32 v209, v58, v59
	v_cvt_pk_bf16_f32 v210, v52, v53
	v_cvt_pk_bf16_f32 v211, v54, v55
	global_store_dwordx4 v145, v[208:211], s[6:7] offset:256
	v_pk_fma_f32 v[64:65], v[56:57], v[56:57], v[64:65]
	v_pk_fma_f32 v[66:67], v[58:59], v[58:59], v[66:67]
	v_pk_fma_f32 v[64:65], v[52:53], v[52:53], v[64:65]
	v_pk_fma_f32 v[66:67], v[54:55], v[54:55], v[66:67]
	v_add_u32_e32 v145, 0x8000, v145
	v_add_f32_e32 v64, v64, v65
	v_add_f32_e32 v66, v66, v67
	v_add_f32_e32 v64, v64, v66
	s_waitcnt vmcnt(14)
	v_lshlrev_b32_e32 v236, 16, v212
	v_and_b32_e32 v237, 0xffff0000, v212
	v_lshlrev_b32_e32 v238, 16, v213
	v_and_b32_e32 v239, 0xffff0000, v213
	v_lshlrev_b32_e32 v212, 16, v214
	v_and_b32_e32 v213, 0xffff0000, v214
	v_lshlrev_b32_e32 v214, 16, v215
	v_and_b32_e32 v215, 0xffff0000, v215
	v_pk_add_f32 v[48:49], v[48:49], v[236:237]
	v_pk_add_f32 v[50:51], v[50:51], v[238:239]
	v_pk_add_f32 v[44:45], v[44:45], v[212:213]
	v_pk_add_f32 v[46:47], v[46:47], v[214:215]
	v_cvt_pk_bf16_f32 v212, v48, v49
	v_cvt_pk_bf16_f32 v213, v50, v51
	v_cvt_pk_bf16_f32 v214, v44, v45
	v_cvt_pk_bf16_f32 v215, v46, v47
	global_store_dwordx4 v145, v[212:215], s[6:7]
	v_pk_mul_f32 v[48:49], v[48:49], v[48:49]
	v_pk_mul_f32 v[50:51], v[50:51], v[50:51]
	v_pk_fma_f32 v[48:49], v[44:45], v[44:45], v[48:49]
	v_pk_fma_f32 v[50:51], v[46:47], v[46:47], v[50:51]
	v_lshlrev_b32_e32 v236, 16, v216
	v_and_b32_e32 v237, 0xffff0000, v216
	v_lshlrev_b32_e32 v238, 16, v217
	v_and_b32_e32 v239, 0xffff0000, v217
	v_lshlrev_b32_e32 v216, 16, v218
	v_and_b32_e32 v217, 0xffff0000, v218
	v_lshlrev_b32_e32 v218, 16, v219
	v_and_b32_e32 v219, 0xffff0000, v219
	v_pk_add_f32 v[40:41], v[40:41], v[236:237]
	v_pk_add_f32 v[42:43], v[42:43], v[238:239]
	v_pk_add_f32 v[36:37], v[36:37], v[216:217]
	v_pk_add_f32 v[38:39], v[38:39], v[218:219]
	v_cvt_pk_bf16_f32 v216, v40, v41
	v_cvt_pk_bf16_f32 v217, v42, v43
	v_cvt_pk_bf16_f32 v218, v36, v37
	v_cvt_pk_bf16_f32 v219, v38, v39
	global_store_dwordx4 v145, v[216:219], s[6:7] offset:256
	v_pk_fma_f32 v[48:49], v[40:41], v[40:41], v[48:49]
	v_pk_fma_f32 v[50:51], v[42:43], v[42:43], v[50:51]
	v_pk_fma_f32 v[48:49], v[36:37], v[36:37], v[48:49]
	v_pk_fma_f32 v[50:51], v[38:39], v[38:39], v[50:51]
	v_add_u32_e32 v145, 0x8000, v145
	v_add_f32_e32 v48, v48, v49
	v_add_f32_e32 v50, v50, v51
	v_add_f32_e32 v48, v48, v50
	s_waitcnt vmcnt(14)
	v_lshlrev_b32_e32 v236, 16, v220
	v_and_b32_e32 v237, 0xffff0000, v220
	v_lshlrev_b32_e32 v238, 16, v221
	v_and_b32_e32 v239, 0xffff0000, v221
	v_lshlrev_b32_e32 v220, 16, v222
	v_and_b32_e32 v221, 0xffff0000, v222
	v_lshlrev_b32_e32 v222, 16, v223
	v_and_b32_e32 v223, 0xffff0000, v223
	v_pk_add_f32 v[32:33], v[32:33], v[236:237]
	v_pk_add_f32 v[34:35], v[34:35], v[238:239]
	v_pk_add_f32 v[28:29], v[28:29], v[220:221]
	v_pk_add_f32 v[30:31], v[30:31], v[222:223]
	v_cvt_pk_bf16_f32 v220, v32, v33
	v_cvt_pk_bf16_f32 v221, v34, v35
	v_cvt_pk_bf16_f32 v222, v28, v29
	v_cvt_pk_bf16_f32 v223, v30, v31
	global_store_dwordx4 v145, v[220:223], s[6:7]
	v_pk_mul_f32 v[32:33], v[32:33], v[32:33]
	v_pk_mul_f32 v[34:35], v[34:35], v[34:35]
	v_pk_fma_f32 v[32:33], v[28:29], v[28:29], v[32:33]
	v_pk_fma_f32 v[34:35], v[30:31], v[30:31], v[34:35]
	v_lshlrev_b32_e32 v236, 16, v224
	v_and_b32_e32 v237, 0xffff0000, v224
	v_lshlrev_b32_e32 v238, 16, v225
	v_and_b32_e32 v239, 0xffff0000, v225
	v_lshlrev_b32_e32 v224, 16, v226
	v_and_b32_e32 v225, 0xffff0000, v226
	v_lshlrev_b32_e32 v226, 16, v227
	v_and_b32_e32 v227, 0xffff0000, v227
	v_pk_add_f32 v[24:25], v[24:25], v[236:237]
	v_pk_add_f32 v[26:27], v[26:27], v[238:239]
	v_pk_add_f32 v[20:21], v[20:21], v[224:225]
	v_pk_add_f32 v[22:23], v[22:23], v[226:227]
	v_cvt_pk_bf16_f32 v224, v24, v25
	v_cvt_pk_bf16_f32 v225, v26, v27
	v_cvt_pk_bf16_f32 v226, v20, v21
	v_cvt_pk_bf16_f32 v227, v22, v23
	global_store_dwordx4 v145, v[224:227], s[6:7] offset:256
	v_pk_fma_f32 v[32:33], v[24:25], v[24:25], v[32:33]
	v_pk_fma_f32 v[34:35], v[26:27], v[26:27], v[34:35]
	v_pk_fma_f32 v[32:33], v[20:21], v[20:21], v[32:33]
	v_pk_fma_f32 v[34:35], v[22:23], v[22:23], v[34:35]
	v_add_u32_e32 v145, 0x8000, v145
	v_add_f32_e32 v32, v32, v33
	v_add_f32_e32 v34, v34, v35
	v_add_f32_e32 v32, v32, v34
	s_waitcnt vmcnt(14)
	v_lshlrev_b32_e32 v236, 16, v228
	v_and_b32_e32 v237, 0xffff0000, v228
	v_lshlrev_b32_e32 v238, 16, v229
	v_and_b32_e32 v239, 0xffff0000, v229
	v_lshlrev_b32_e32 v228, 16, v230
	v_and_b32_e32 v229, 0xffff0000, v230
	v_lshlrev_b32_e32 v230, 16, v231
	v_and_b32_e32 v231, 0xffff0000, v231
	v_pk_add_f32 v[16:17], v[16:17], v[236:237]
	v_pk_add_f32 v[18:19], v[18:19], v[238:239]
	v_pk_add_f32 v[12:13], v[12:13], v[228:229]
	v_pk_add_f32 v[14:15], v[14:15], v[230:231]
	v_cvt_pk_bf16_f32 v228, v16, v17
	v_cvt_pk_bf16_f32 v229, v18, v19
	v_cvt_pk_bf16_f32 v230, v12, v13
	v_cvt_pk_bf16_f32 v231, v14, v15
	global_store_dwordx4 v145, v[228:231], s[6:7]
	v_pk_mul_f32 v[16:17], v[16:17], v[16:17]
	v_pk_mul_f32 v[18:19], v[18:19], v[18:19]
	v_pk_fma_f32 v[16:17], v[12:13], v[12:13], v[16:17]
	v_pk_fma_f32 v[18:19], v[14:15], v[14:15], v[18:19]
	v_lshlrev_b32_e32 v236, 16, v232
	v_and_b32_e32 v237, 0xffff0000, v232
	v_lshlrev_b32_e32 v238, 16, v233
	v_and_b32_e32 v239, 0xffff0000, v233
	v_lshlrev_b32_e32 v232, 16, v234
	v_and_b32_e32 v233, 0xffff0000, v234
	v_lshlrev_b32_e32 v234, 16, v235
	v_and_b32_e32 v235, 0xffff0000, v235
	v_pk_add_f32 v[8:9], v[8:9], v[236:237]
	v_pk_add_f32 v[10:11], v[10:11], v[238:239]
	v_pk_add_f32 v[4:5], v[4:5], v[232:233]
	v_pk_add_f32 v[6:7], v[6:7], v[234:235]
	v_cvt_pk_bf16_f32 v232, v8, v9
	v_cvt_pk_bf16_f32 v233, v10, v11
	v_cvt_pk_bf16_f32 v234, v4, v5
	v_cvt_pk_bf16_f32 v235, v6, v7
	global_store_dwordx4 v145, v[232:235], s[6:7] offset:256
	v_pk_fma_f32 v[16:17], v[8:9], v[8:9], v[16:17]
	v_pk_fma_f32 v[18:19], v[10:11], v[10:11], v[18:19]
	v_pk_fma_f32 v[16:17], v[4:5], v[4:5], v[16:17]
	v_pk_fma_f32 v[18:19], v[6:7], v[6:7], v[18:19]
	v_add_f32_e32 v16, v16, v17
	v_add_f32_e32 v18, v18, v19
	v_add_f32_e32 v16, v16, v18
	ds_bpermute_b32 v129, v155, v128
	ds_bpermute_b32 v113, v155, v112
	ds_bpermute_b32 v97, v155, v96
	ds_bpermute_b32 v81, v155, v80
	ds_bpermute_b32 v65, v155, v64
	ds_bpermute_b32 v49, v155, v48
	ds_bpermute_b32 v33, v155, v32
	ds_bpermute_b32 v17, v155, v16
	s_waitcnt lgkmcnt(0)
	v_add_f32_e32 v128, v128, v129
	v_add_f32_e32 v112, v112, v113
	v_add_f32_e32 v96, v96, v97
	v_add_f32_e32 v80, v80, v81
	v_add_f32_e32 v64, v64, v65
	v_add_f32_e32 v48, v48, v49
	v_add_f32_e32 v32, v32, v33
	v_add_f32_e32 v16, v16, v17
	ds_bpermute_b32 v129, v192, v128
	ds_bpermute_b32 v113, v192, v112
	ds_bpermute_b32 v97, v192, v96
	ds_bpermute_b32 v81, v192, v80
	ds_bpermute_b32 v65, v192, v64
	ds_bpermute_b32 v49, v192, v48
	ds_bpermute_b32 v33, v192, v32
	ds_bpermute_b32 v17, v192, v16
	s_waitcnt lgkmcnt(0)
	s_and_saveexec_b64 s[14:15], s[0:1]
	v_add_f32_e32 v128, v128, v129
	v_add_f32_e32 v112, v112, v113
	v_add_f32_e32 v96, v96, v97
	v_add_f32_e32 v80, v80, v81
	v_add_f32_e32 v64, v64, v65
	v_add_f32_e32 v48, v48, v49
	v_add_f32_e32 v32, v32, v33
	v_add_f32_e32 v16, v16, v17
	global_atomic_add_f32 v154, v128, s[8:9]
	global_atomic_add_f32 v154, v112, s[8:9] offset:64
	global_atomic_add_f32 v154, v96, s[8:9] offset:128
	global_atomic_add_f32 v154, v80, s[8:9] offset:192
	global_atomic_add_f32 v154, v64, s[8:9] offset:512
	global_atomic_add_f32 v154, v48, s[8:9] offset:576
	global_atomic_add_f32 v154, v32, s[8:9] offset:640
	global_atomic_add_f32 v154, v16, s[8:9] offset:704
